# GEMM K loops: blanket s_waitcnt lgkmcnt(0) at compute-segment heads replaced by a counted ladder (each MFMA waits only for the fragment reads of its own operands), 60 sites; on v092
# baseline (speedup 1.0000x reference)
.LBB0_177:
	s_ashr_i32 s45, s44, 31
	v_cmp_lt_i64_e32 vcc, s[46:47], v[144:145]
	s_lshl_b64 s[46:47], s[44:45], 19
	s_add_u32 s46, s68, s46
	s_addc_u32 s47, s69, s47
	s_and_b64 s[48:49], vcc, exec
	s_cselect_b32 s11, s47, s51
	s_cselect_b32 s13, s46, s50
	s_ashr_i32 s43, s42, 31
	s_lshl_b64 s[48:49], s[42:43], 19
	s_add_u32 s48, s26, s48
	s_addc_u32 s49, s27, s49
	s_and_b64 s[54:55], vcc, exec
	s_cselect_b32 s17, s49, s53
	s_cselect_b32 s43, s48, s52
	s_add_u32 s50, s50, 0x40080
	s_addc_u32 s51, s51, 0
	s_add_u32 s45, s52, 0x100
	s_addc_u32 s91, s53, 0
	s_mov_b32 s92, -2
	s_waitcnt lgkmcnt(0)
	ds_read_b128 v[148:151], v159
	ds_read_b128 v[152:155], v159 offset:1024
	ds_read_b128 v[164:167], v159 offset:2048
	ds_read_b128 v[168:171], v159 offset:3072
	s_add_u32 s52, s50, 0xfffc0080
	s_addc_u32 s53, s51, -1
	s_cmp_eq_u32 s92, 12
	s_cselect_b32 s55, s11, s53
	s_cselect_b32 s54, s13, s52
	s_cselect_b32 s53, s17, s91
	s_cselect_b32 s52, s43, s45
	v_lshl_add_u64 v[156:157], s[50:51], 0, v[140:141]
	s_add_i32 m0, s58, 0xc000
	ds_read_b128 v[172:175], v160
	ds_read_b128 v[176:179], v160 offset:1024
	ds_read_b128 v[180:183], v160 offset:2048
	ds_read_b128 v[184:187], v160 offset:3072
	ds_read_b128 v[188:191], v160 offset:4096
	ds_read_b128 v[196:199], v160 offset:5120
	ds_read_b128 v[200:203], v160 offset:6144
	ds_read_b128 v[204:207], v160 offset:7168
	global_load_lds_dwordx4 v[156:157], off
	v_lshl_add_u64 v[156:157], s[50:51], 0, v[142:143]
	s_add_i32 m0, s58, 0xe000
	s_nop 0
	global_load_lds_dwordx4 v[156:157], off
	s_waitcnt lgkmcnt(8)
	s_barrier
	s_waitcnt lgkmcnt(7)
	v_mfma_f32_16x16x32_bf16 v[124:127], v[148:151], v[172:175], 0
	v_mfma_f32_16x16x32_bf16 v[120:123], v[164:167], v[172:175], 0
	s_waitcnt lgkmcnt(5)
	v_mfma_f32_16x16x32_bf16 v[108:111], v[148:151], v[180:183], 0
	v_mfma_f32_16x16x32_bf16 v[104:107], v[164:167], v[180:183], 0
	s_waitcnt lgkmcnt(3)
	v_mfma_f32_16x16x32_bf16 v[92:95], v[148:151], v[188:191], 0
	v_mfma_f32_16x16x32_bf16 v[88:91], v[164:167], v[188:191], 0
	s_waitcnt lgkmcnt(1)
	v_mfma_f32_16x16x32_bf16 v[76:79], v[148:151], v[200:203], 0
	v_mfma_f32_16x16x32_bf16 v[72:75], v[164:167], v[200:203], 0
	v_mfma_f32_16x16x32_bf16 v[124:127], v[152:155], v[176:179], v[124:127]
	v_mfma_f32_16x16x32_bf16 v[120:123], v[168:171], v[176:179], v[120:123]
	v_mfma_f32_16x16x32_bf16 v[108:111], v[152:155], v[184:187], v[108:111]
	v_mfma_f32_16x16x32_bf16 v[104:107], v[168:171], v[184:187], v[104:107]
	v_mfma_f32_16x16x32_bf16 v[92:95], v[152:155], v[196:199], v[92:95]
	v_mfma_f32_16x16x32_bf16 v[88:91], v[168:171], v[196:199], v[88:91]
	s_waitcnt lgkmcnt(0)
	v_mfma_f32_16x16x32_bf16 v[76:79], v[152:155], v[204:207], v[76:79]
	v_mfma_f32_16x16x32_bf16 v[72:75], v[168:171], v[204:207], v[72:75]
	s_barrier
	s_add_i32 s93, s89, s57
	v_lshl_add_u64 v[156:157], s[52:53], 0, v[130:131]
	s_mov_b32 m0, s93
	ds_read_b128 v[208:211], v161
	ds_read_b128 v[212:215], v161 offset:1024
	ds_read_b128 v[216:219], v161 offset:2048
	ds_read_b128 v[220:223], v161 offset:3072
	global_load_lds_dwordx4 v[156:157], off
	v_lshl_add_u64 v[224:225], s[52:53], 0, v[134:135]
	s_add_i32 m0, s93, 0x2000
	s_nop 0
	global_load_lds_dwordx4 v[224:225], off
	s_barrier
	s_waitcnt lgkmcnt(3)
	v_mfma_f32_16x16x32_bf16 v[116:119], v[208:211], v[172:175], 0
	s_waitcnt lgkmcnt(1)
	v_mfma_f32_16x16x32_bf16 v[112:115], v[216:219], v[172:175], 0
	v_mfma_f32_16x16x32_bf16 v[100:103], v[208:211], v[180:183], 0
	v_mfma_f32_16x16x32_bf16 v[96:99], v[216:219], v[180:183], 0
	v_mfma_f32_16x16x32_bf16 v[84:87], v[208:211], v[188:191], 0
	v_mfma_f32_16x16x32_bf16 v[80:83], v[216:219], v[188:191], 0
	v_mfma_f32_16x16x32_bf16 v[68:71], v[208:211], v[200:203], 0
	v_mfma_f32_16x16x32_bf16 v[64:67], v[216:219], v[200:203], 0
	v_mfma_f32_16x16x32_bf16 v[116:119], v[212:215], v[176:179], v[116:119]
	s_waitcnt lgkmcnt(0)
	v_mfma_f32_16x16x32_bf16 v[112:115], v[220:223], v[176:179], v[112:115]
	v_mfma_f32_16x16x32_bf16 v[100:103], v[212:215], v[184:187], v[100:103]
	v_mfma_f32_16x16x32_bf16 v[96:99], v[220:223], v[184:187], v[96:99]
	v_mfma_f32_16x16x32_bf16 v[84:87], v[212:215], v[196:199], v[84:87]
	v_mfma_f32_16x16x32_bf16 v[80:83], v[220:223], v[196:199], v[80:83]
	v_mfma_f32_16x16x32_bf16 v[68:71], v[212:215], v[204:207], v[68:71]
	v_mfma_f32_16x16x32_bf16 v[64:67], v[220:223], v[204:207], v[64:67]
	s_mov_b32 m0, s58
	v_lshl_add_u64 v[226:227], s[54:55], 0, v[128:129]
	s_barrier
	ds_read_b128 v[172:175], v160 offset:16384
	ds_read_b128 v[176:179], v160 offset:17408
	ds_read_b128 v[180:183], v160 offset:18432
	ds_read_b128 v[184:187], v160 offset:19456
	ds_read_b128 v[188:191], v160 offset:20480
	ds_read_b128 v[196:199], v160 offset:21504
	ds_read_b128 v[200:203], v160 offset:22528
	ds_read_b128 v[204:207], v160 offset:23552
	global_load_lds_dwordx4 v[226:227], off
	v_lshl_add_u64 v[228:229], s[54:55], 0, v[132:133]
	s_mov_b32 m0, s59
	s_nop 0
	global_load_lds_dwordx4 v[228:229], off
	s_barrier
	s_waitcnt lgkmcnt(7)
	v_mfma_f32_16x16x32_bf16 v[60:63], v[148:151], v[172:175], 0
	v_mfma_f32_16x16x32_bf16 v[56:59], v[164:167], v[172:175], 0
	s_waitcnt lgkmcnt(5)
	v_mfma_f32_16x16x32_bf16 v[44:47], v[148:151], v[180:183], 0
	v_mfma_f32_16x16x32_bf16 v[40:43], v[164:167], v[180:183], 0
	s_waitcnt lgkmcnt(3)
	v_mfma_f32_16x16x32_bf16 v[28:31], v[148:151], v[188:191], 0
	v_mfma_f32_16x16x32_bf16 v[24:27], v[164:167], v[188:191], 0
	s_waitcnt lgkmcnt(1)
	v_mfma_f32_16x16x32_bf16 v[12:15], v[148:151], v[200:203], 0
	v_mfma_f32_16x16x32_bf16 v[8:11], v[164:167], v[200:203], 0
	v_mfma_f32_16x16x32_bf16 v[60:63], v[152:155], v[176:179], v[60:63]
	v_mfma_f32_16x16x32_bf16 v[56:59], v[168:171], v[176:179], v[56:59]
	v_mfma_f32_16x16x32_bf16 v[44:47], v[152:155], v[184:187], v[44:47]
	v_mfma_f32_16x16x32_bf16 v[40:43], v[168:171], v[184:187], v[40:43]
	v_mfma_f32_16x16x32_bf16 v[28:31], v[152:155], v[196:199], v[28:31]
	v_mfma_f32_16x16x32_bf16 v[24:27], v[168:171], v[196:199], v[24:27]
	s_waitcnt lgkmcnt(0)
	v_mfma_f32_16x16x32_bf16 v[12:15], v[152:155], v[204:207], v[12:15]
	v_mfma_f32_16x16x32_bf16 v[8:11], v[168:171], v[204:207], v[8:11]
	s_barrier
	s_add_u32 s94, s52, 0x10000
	s_addc_u32 s95, s53, 0
	s_add_i32 s93, s90, s57
	v_lshl_add_u64 v[148:149], s[94:95], 0, v[130:131]
	s_mov_b32 m0, s93
	s_nop 0
	global_load_lds_dwordx4 v[148:149], off
	v_lshl_add_u64 v[148:149], s[94:95], 0, v[134:135]
	s_add_i32 m0, s93, 0x2000
	s_nop 0
	global_load_lds_dwordx4 v[148:149], off
	s_cmp_eq_u32 s98, 0
	s_cbranch_scc1 .Lk1_w4n
	s_mov_b32 s98, 0
	s_waitcnt vmcnt(24)
	s_branch .Lk1_w4j

.Lk1_w4j:
	s_barrier
	v_mfma_f32_16x16x32_bf16 v[52:55], v[208:211], v[172:175], 0
	v_mfma_f32_16x16x32_bf16 v[48:51], v[216:219], v[172:175], 0
	v_mfma_f32_16x16x32_bf16 v[36:39], v[208:211], v[180:183], 0
	v_mfma_f32_16x16x32_bf16 v[32:35], v[216:219], v[180:183], 0
	v_mfma_f32_16x16x32_bf16 v[20:23], v[208:211], v[188:191], 0
	v_mfma_f32_16x16x32_bf16 v[16:19], v[216:219], v[188:191], 0
	v_mfma_f32_16x16x32_bf16 v[4:7], v[208:211], v[200:203], 0
	v_mfma_f32_16x16x32_bf16 v[0:3], v[216:219], v[200:203], 0
	v_mfma_f32_16x16x32_bf16 v[52:55], v[212:215], v[176:179], v[52:55]
	v_mfma_f32_16x16x32_bf16 v[48:51], v[220:223], v[176:179], v[48:51]
	v_mfma_f32_16x16x32_bf16 v[36:39], v[212:215], v[184:187], v[36:39]
	v_mfma_f32_16x16x32_bf16 v[32:35], v[220:223], v[184:187], v[32:35]
	v_mfma_f32_16x16x32_bf16 v[20:23], v[212:215], v[196:199], v[20:23]
	v_mfma_f32_16x16x32_bf16 v[16:19], v[220:223], v[196:199], v[16:19]
	v_mfma_f32_16x16x32_bf16 v[4:7], v[212:215], v[204:207], v[4:7]
	v_mfma_f32_16x16x32_bf16 v[0:3], v[220:223], v[204:207], v[0:3]
	s_add_i32 s93, 0, 0x18000
	v_add_u32_e32 v136, s93, v158
	s_barrier
	ds_read_b128 v[148:151], v136
	ds_read_b128 v[152:155], v136 offset:1024
	ds_read_b128 v[164:167], v136 offset:2048
	ds_read_b128 v[168:171], v136 offset:3072
	s_add_u32 s54, s54, 0x40000
	s_addc_u32 s55, s55, 0
	s_mov_b32 m0, s60
	v_lshl_add_u64 v[208:209], s[54:55], 0, v[128:129]
	ds_read_b128 v[172:175], v160 offset:32768
	ds_read_b128 v[176:179], v160 offset:33792
	ds_read_b128 v[180:183], v160 offset:34816
	ds_read_b128 v[184:187], v160 offset:35840
	ds_read_b128 v[188:191], v160 offset:36864
	ds_read_b128 v[196:199], v160 offset:37888
	ds_read_b128 v[200:203], v160 offset:38912
	ds_read_b128 v[204:207], v160 offset:39936
	global_load_lds_dwordx4 v[208:209], off
	v_lshl_add_u64 v[208:209], s[54:55], 0, v[132:133]
	s_mov_b32 m0, s61
	s_nop 0
	global_load_lds_dwordx4 v[208:209], off
	s_waitcnt lgkmcnt(8)
	s_barrier
	s_waitcnt lgkmcnt(7)
	v_mfma_f32_16x16x32_bf16 v[124:127], v[148:151], v[172:175], v[124:127]
	v_mfma_f32_16x16x32_bf16 v[120:123], v[164:167], v[172:175], v[120:123]
	s_waitcnt lgkmcnt(5)
	v_mfma_f32_16x16x32_bf16 v[108:111], v[148:151], v[180:183], v[108:111]
	v_mfma_f32_16x16x32_bf16 v[104:107], v[164:167], v[180:183], v[104:107]
	s_waitcnt lgkmcnt(3)
	v_mfma_f32_16x16x32_bf16 v[92:95], v[148:151], v[188:191], v[92:95]
	v_mfma_f32_16x16x32_bf16 v[88:91], v[164:167], v[188:191], v[88:91]
	s_waitcnt lgkmcnt(1)
	v_mfma_f32_16x16x32_bf16 v[76:79], v[148:151], v[200:203], v[76:79]
	v_mfma_f32_16x16x32_bf16 v[72:75], v[164:167], v[200:203], v[72:75]
	v_mfma_f32_16x16x32_bf16 v[124:127], v[152:155], v[176:179], v[124:127]
	v_mfma_f32_16x16x32_bf16 v[120:123], v[168:171], v[176:179], v[120:123]
	v_mfma_f32_16x16x32_bf16 v[108:111], v[152:155], v[184:187], v[108:111]
	v_mfma_f32_16x16x32_bf16 v[104:107], v[168:171], v[184:187], v[104:107]
	v_mfma_f32_16x16x32_bf16 v[92:95], v[152:155], v[196:199], v[92:95]
	v_mfma_f32_16x16x32_bf16 v[88:91], v[168:171], v[196:199], v[88:91]
	s_waitcnt lgkmcnt(0)
	v_mfma_f32_16x16x32_bf16 v[76:79], v[152:155], v[204:207], v[76:79]
	v_mfma_f32_16x16x32_bf16 v[72:75], v[168:171], v[204:207], v[72:75]
	s_barrier
	s_add_i32 s54, 0, 0x1c000
	s_add_i32 s55, s93, s57
	v_add_u32_e32 v136, s54, v158
	v_lshl_add_u64 v[156:157], v[156:157], 0, s[0:1]
	s_mov_b32 m0, s55
	ds_read_b128 v[208:211], v136
	ds_read_b128 v[212:215], v136 offset:1024
	ds_read_b128 v[216:219], v136 offset:2048
	ds_read_b128 v[220:223], v136 offset:3072
	global_load_lds_dwordx4 v[156:157], off
	v_lshl_add_u64 v[156:157], v[224:225], 0, s[0:1]
	s_add_i32 m0, s55, 0x2000
	s_nop 0
	global_load_lds_dwordx4 v[156:157], off
	s_barrier
	s_waitcnt lgkmcnt(3)
	v_mfma_f32_16x16x32_bf16 v[116:119], v[208:211], v[172:175], v[116:119]
	s_waitcnt lgkmcnt(1)
	v_mfma_f32_16x16x32_bf16 v[112:115], v[216:219], v[172:175], v[112:115]
	v_mfma_f32_16x16x32_bf16 v[100:103], v[208:211], v[180:183], v[100:103]
	v_mfma_f32_16x16x32_bf16 v[96:99], v[216:219], v[180:183], v[96:99]
	v_mfma_f32_16x16x32_bf16 v[84:87], v[208:211], v[188:191], v[84:87]
	v_mfma_f32_16x16x32_bf16 v[80:83], v[216:219], v[188:191], v[80:83]
	v_mfma_f32_16x16x32_bf16 v[68:71], v[208:211], v[200:203], v[68:71]
	v_mfma_f32_16x16x32_bf16 v[64:67], v[216:219], v[200:203], v[64:67]
	v_mfma_f32_16x16x32_bf16 v[116:119], v[212:215], v[176:179], v[116:119]
	s_waitcnt lgkmcnt(0)
	v_mfma_f32_16x16x32_bf16 v[112:115], v[220:223], v[176:179], v[112:115]
	v_mfma_f32_16x16x32_bf16 v[100:103], v[212:215], v[184:187], v[100:103]
	v_mfma_f32_16x16x32_bf16 v[96:99], v[220:223], v[184:187], v[96:99]
	v_mfma_f32_16x16x32_bf16 v[84:87], v[212:215], v[196:199], v[84:87]
	v_mfma_f32_16x16x32_bf16 v[80:83], v[220:223], v[196:199], v[80:83]
	v_mfma_f32_16x16x32_bf16 v[68:71], v[212:215], v[204:207], v[68:71]
	v_mfma_f32_16x16x32_bf16 v[64:67], v[220:223], v[204:207], v[64:67]
	s_mov_b32 m0, s65
	v_lshl_add_u64 v[156:157], v[226:227], 0, s[0:1]
	s_waitcnt vmcnt(10)
	s_barrier
	ds_read_b128 v[172:175], v160 offset:49152
	ds_read_b128 v[176:179], v160 offset:50176
	ds_read_b128 v[180:183], v160 offset:51200
	ds_read_b128 v[184:187], v160 offset:52224
	ds_read_b128 v[188:191], v160 offset:53248
	ds_read_b128 v[196:199], v160 offset:54272
	ds_read_b128 v[200:203], v160 offset:55296
	ds_read_b128 v[204:207], v160 offset:56320
	global_load_lds_dwordx4 v[156:157], off
	v_lshl_add_u64 v[156:157], v[228:229], 0, s[0:1]
	s_mov_b32 m0, s66
	s_nop 0
	global_load_lds_dwordx4 v[156:157], off
	s_barrier
	s_waitcnt lgkmcnt(7)
	v_mfma_f32_16x16x32_bf16 v[60:63], v[148:151], v[172:175], v[60:63]
	v_mfma_f32_16x16x32_bf16 v[56:59], v[164:167], v[172:175], v[56:59]
	s_waitcnt lgkmcnt(5)
	v_mfma_f32_16x16x32_bf16 v[44:47], v[148:151], v[180:183], v[44:47]
	v_mfma_f32_16x16x32_bf16 v[40:43], v[164:167], v[180:183], v[40:43]
	s_waitcnt lgkmcnt(3)
	v_mfma_f32_16x16x32_bf16 v[28:31], v[148:151], v[188:191], v[28:31]
	v_mfma_f32_16x16x32_bf16 v[24:27], v[164:167], v[188:191], v[24:27]
	s_waitcnt lgkmcnt(1)
	v_mfma_f32_16x16x32_bf16 v[12:15], v[148:151], v[200:203], v[12:15]
	v_mfma_f32_16x16x32_bf16 v[8:11], v[164:167], v[200:203], v[8:11]
	v_mfma_f32_16x16x32_bf16 v[60:63], v[152:155], v[176:179], v[60:63]
	v_mfma_f32_16x16x32_bf16 v[56:59], v[168:171], v[176:179], v[56:59]
	v_mfma_f32_16x16x32_bf16 v[44:47], v[152:155], v[184:187], v[44:47]
	v_mfma_f32_16x16x32_bf16 v[40:43], v[168:171], v[184:187], v[40:43]
	v_mfma_f32_16x16x32_bf16 v[28:31], v[152:155], v[196:199], v[28:31]
	v_mfma_f32_16x16x32_bf16 v[24:27], v[168:171], v[196:199], v[24:27]
	s_waitcnt lgkmcnt(0)
	v_mfma_f32_16x16x32_bf16 v[12:15], v[152:155], v[204:207], v[12:15]
	v_mfma_f32_16x16x32_bf16 v[8:11], v[168:171], v[204:207], v[8:11]
	s_barrier
	s_add_u32 s52, s52, 0x10080
	s_addc_u32 s53, s53, 0
	s_add_i32 s54, s54, s57
	v_lshl_add_u64 v[148:149], s[52:53], 0, v[130:131]
	s_mov_b32 m0, s54
	s_nop 0
	global_load_lds_dwordx4 v[148:149], off
	v_lshl_add_u64 v[148:149], s[52:53], 0, v[134:135]
	s_add_i32 m0, s54, 0x2000
	s_nop 0
	global_load_lds_dwordx4 v[148:149], off
	s_waitcnt vmcnt(6)
	s_barrier
	v_mfma_f32_16x16x32_bf16 v[52:55], v[208:211], v[172:175], v[52:55]
	v_mfma_f32_16x16x32_bf16 v[48:51], v[216:219], v[172:175], v[48:51]
	v_mfma_f32_16x16x32_bf16 v[36:39], v[208:211], v[180:183], v[36:39]
	v_mfma_f32_16x16x32_bf16 v[32:35], v[216:219], v[180:183], v[32:35]
	v_mfma_f32_16x16x32_bf16 v[20:23], v[208:211], v[188:191], v[20:23]
	v_mfma_f32_16x16x32_bf16 v[16:19], v[216:219], v[188:191], v[16:19]
	v_mfma_f32_16x16x32_bf16 v[4:7], v[208:211], v[200:203], v[4:7]
	v_mfma_f32_16x16x32_bf16 v[0:3], v[216:219], v[200:203], v[0:3]
	v_mfma_f32_16x16x32_bf16 v[52:55], v[212:215], v[176:179], v[52:55]
	v_mfma_f32_16x16x32_bf16 v[48:51], v[220:223], v[176:179], v[48:51]
	v_mfma_f32_16x16x32_bf16 v[36:39], v[212:215], v[184:187], v[36:39]
	v_mfma_f32_16x16x32_bf16 v[32:35], v[220:223], v[184:187], v[32:35]
	v_mfma_f32_16x16x32_bf16 v[20:23], v[212:215], v[196:199], v[20:23]
	v_mfma_f32_16x16x32_bf16 v[16:19], v[220:223], v[196:199], v[16:19]
	v_mfma_f32_16x16x32_bf16 v[4:7], v[212:215], v[204:207], v[4:7]
	v_mfma_f32_16x16x32_bf16 v[0:3], v[220:223], v[204:207], v[0:3]
	s_add_i32 s92, s92, 2
	s_add_u32 s50, s50, 0x100
	s_addc_u32 s51, s51, 0
	s_add_u32 s45, s45, 0x100
	s_addc_u32 s91, s91, 0
	s_cmp_gt_u32 s92, 13
	s_barrier
	s_cbranch_scc0 .LBB0_178
.LBB0_178:
	ds_read_b128 v[148:151], v159
	ds_read_b128 v[152:155], v159 offset:1024
	ds_read_b128 v[164:167], v159 offset:2048
	ds_read_b128 v[168:171], v159 offset:3072
	s_add_u32 s52, s50, 0xfffc0080
	s_addc_u32 s53, s51, -1
	s_cmp_eq_u32 s92, 12
	s_cselect_b32 s55, s11, s53
	s_cselect_b32 s54, s13, s52
	s_cselect_b32 s53, s17, s91
	s_cselect_b32 s52, s43, s45
	v_lshl_add_u64 v[156:157], s[50:51], 0, v[140:141]
	s_add_i32 m0, s58, 0xc000
	ds_read_b128 v[172:175], v160
	ds_read_b128 v[176:179], v160 offset:1024
	ds_read_b128 v[180:183], v160 offset:2048
	ds_read_b128 v[184:187], v160 offset:3072
	ds_read_b128 v[188:191], v160 offset:4096
	ds_read_b128 v[196:199], v160 offset:5120
	ds_read_b128 v[200:203], v160 offset:6144
	ds_read_b128 v[204:207], v160 offset:7168
	global_load_lds_dwordx4 v[156:157], off
	v_lshl_add_u64 v[156:157], s[50:51], 0, v[142:143]
	s_add_i32 m0, s58, 0xe000
	s_nop 0
	global_load_lds_dwordx4 v[156:157], off
	s_waitcnt lgkmcnt(8)
	s_barrier
	s_waitcnt lgkmcnt(7)
	v_mfma_f32_16x16x32_bf16 v[124:127], v[148:151], v[172:175], v[124:127]
	v_mfma_f32_16x16x32_bf16 v[120:123], v[164:167], v[172:175], v[120:123]
	s_waitcnt lgkmcnt(5)
	v_mfma_f32_16x16x32_bf16 v[108:111], v[148:151], v[180:183], v[108:111]
	v_mfma_f32_16x16x32_bf16 v[104:107], v[164:167], v[180:183], v[104:107]
	s_waitcnt lgkmcnt(3)
	v_mfma_f32_16x16x32_bf16 v[92:95], v[148:151], v[188:191], v[92:95]
	v_mfma_f32_16x16x32_bf16 v[88:91], v[164:167], v[188:191], v[88:91]
	s_waitcnt lgkmcnt(1)
	v_mfma_f32_16x16x32_bf16 v[76:79], v[148:151], v[200:203], v[76:79]
	v_mfma_f32_16x16x32_bf16 v[72:75], v[164:167], v[200:203], v[72:75]
	v_mfma_f32_16x16x32_bf16 v[124:127], v[152:155], v[176:179], v[124:127]
	v_mfma_f32_16x16x32_bf16 v[120:123], v[168:171], v[176:179], v[120:123]
	v_mfma_f32_16x16x32_bf16 v[108:111], v[152:155], v[184:187], v[108:111]
	v_mfma_f32_16x16x32_bf16 v[104:107], v[168:171], v[184:187], v[104:107]
	v_mfma_f32_16x16x32_bf16 v[92:95], v[152:155], v[196:199], v[92:95]
	v_mfma_f32_16x16x32_bf16 v[88:91], v[168:171], v[196:199], v[88:91]
	s_waitcnt lgkmcnt(0)
	v_mfma_f32_16x16x32_bf16 v[76:79], v[152:155], v[204:207], v[76:79]
	v_mfma_f32_16x16x32_bf16 v[72:75], v[168:171], v[204:207], v[72:75]
	s_barrier
	s_add_i32 s93, s89, s57
	v_lshl_add_u64 v[156:157], s[52:53], 0, v[130:131]
	s_mov_b32 m0, s93
	ds_read_b128 v[208:211], v161
	ds_read_b128 v[212:215], v161 offset:1024
	ds_read_b128 v[216:219], v161 offset:2048
	ds_read_b128 v[220:223], v161 offset:3072
	global_load_lds_dwordx4 v[156:157], off
	v_lshl_add_u64 v[224:225], s[52:53], 0, v[134:135]
	s_add_i32 m0, s93, 0x2000
	s_nop 0
	global_load_lds_dwordx4 v[224:225], off
	s_barrier
	s_waitcnt lgkmcnt(3)
	v_mfma_f32_16x16x32_bf16 v[116:119], v[208:211], v[172:175], v[116:119]
	s_waitcnt lgkmcnt(1)
	v_mfma_f32_16x16x32_bf16 v[112:115], v[216:219], v[172:175], v[112:115]
	v_mfma_f32_16x16x32_bf16 v[100:103], v[208:211], v[180:183], v[100:103]
	v_mfma_f32_16x16x32_bf16 v[96:99], v[216:219], v[180:183], v[96:99]
	v_mfma_f32_16x16x32_bf16 v[84:87], v[208:211], v[188:191], v[84:87]
	v_mfma_f32_16x16x32_bf16 v[80:83], v[216:219], v[188:191], v[80:83]
	v_mfma_f32_16x16x32_bf16 v[68:71], v[208:211], v[200:203], v[68:71]
	v_mfma_f32_16x16x32_bf16 v[64:67], v[216:219], v[200:203], v[64:67]
	v_mfma_f32_16x16x32_bf16 v[116:119], v[212:215], v[176:179], v[116:119]
	s_waitcnt lgkmcnt(0)
	v_mfma_f32_16x16x32_bf16 v[112:115], v[220:223], v[176:179], v[112:115]
	v_mfma_f32_16x16x32_bf16 v[100:103], v[212:215], v[184:187], v[100:103]
	v_mfma_f32_16x16x32_bf16 v[96:99], v[220:223], v[184:187], v[96:99]
	v_mfma_f32_16x16x32_bf16 v[84:87], v[212:215], v[196:199], v[84:87]
	v_mfma_f32_16x16x32_bf16 v[80:83], v[220:223], v[196:199], v[80:83]
	v_mfma_f32_16x16x32_bf16 v[68:71], v[212:215], v[204:207], v[68:71]
	v_mfma_f32_16x16x32_bf16 v[64:67], v[220:223], v[204:207], v[64:67]
	s_mov_b32 m0, s58
	v_lshl_add_u64 v[226:227], s[54:55], 0, v[128:129]
	s_barrier
	ds_read_b128 v[172:175], v160 offset:16384
	ds_read_b128 v[176:179], v160 offset:17408
	ds_read_b128 v[180:183], v160 offset:18432
	ds_read_b128 v[184:187], v160 offset:19456
	ds_read_b128 v[188:191], v160 offset:20480
	ds_read_b128 v[196:199], v160 offset:21504
	ds_read_b128 v[200:203], v160 offset:22528
	ds_read_b128 v[204:207], v160 offset:23552
	global_load_lds_dwordx4 v[226:227], off
	v_lshl_add_u64 v[228:229], s[54:55], 0, v[132:133]
	s_mov_b32 m0, s59
	s_nop 0
	global_load_lds_dwordx4 v[228:229], off
	s_barrier
	s_waitcnt lgkmcnt(7)
	v_mfma_f32_16x16x32_bf16 v[60:63], v[148:151], v[172:175], v[60:63]
	v_mfma_f32_16x16x32_bf16 v[56:59], v[164:167], v[172:175], v[56:59]
	s_waitcnt lgkmcnt(5)
	v_mfma_f32_16x16x32_bf16 v[44:47], v[148:151], v[180:183], v[44:47]
	v_mfma_f32_16x16x32_bf16 v[40:43], v[164:167], v[180:183], v[40:43]
	s_waitcnt lgkmcnt(3)
	v_mfma_f32_16x16x32_bf16 v[28:31], v[148:151], v[188:191], v[28:31]
	v_mfma_f32_16x16x32_bf16 v[24:27], v[164:167], v[188:191], v[24:27]
	s_waitcnt lgkmcnt(1)
	v_mfma_f32_16x16x32_bf16 v[12:15], v[148:151], v[200:203], v[12:15]
	v_mfma_f32_16x16x32_bf16 v[8:11], v[164:167], v[200:203], v[8:11]
	v_mfma_f32_16x16x32_bf16 v[60:63], v[152:155], v[176:179], v[60:63]
	v_mfma_f32_16x16x32_bf16 v[56:59], v[168:171], v[176:179], v[56:59]
	v_mfma_f32_16x16x32_bf16 v[44:47], v[152:155], v[184:187], v[44:47]
	v_mfma_f32_16x16x32_bf16 v[40:43], v[168:171], v[184:187], v[40:43]
	v_mfma_f32_16x16x32_bf16 v[28:31], v[152:155], v[196:199], v[28:31]
	v_mfma_f32_16x16x32_bf16 v[24:27], v[168:171], v[196:199], v[24:27]
	s_waitcnt lgkmcnt(0)
	v_mfma_f32_16x16x32_bf16 v[12:15], v[152:155], v[204:207], v[12:15]
	v_mfma_f32_16x16x32_bf16 v[8:11], v[168:171], v[204:207], v[8:11]
	s_barrier
	s_add_u32 s94, s52, 0x10000
	s_addc_u32 s95, s53, 0
	s_add_i32 s93, s90, s57
	v_lshl_add_u64 v[148:149], s[94:95], 0, v[130:131]
	s_mov_b32 m0, s93
	s_nop 0
	global_load_lds_dwordx4 v[148:149], off
	v_lshl_add_u64 v[148:149], s[94:95], 0, v[134:135]
	s_add_i32 m0, s93, 0x2000
	s_nop 0
	global_load_lds_dwordx4 v[148:149], off
	s_waitcnt vmcnt(6)
	s_barrier
	v_mfma_f32_16x16x32_bf16 v[52:55], v[208:211], v[172:175], v[52:55]
	v_mfma_f32_16x16x32_bf16 v[48:51], v[216:219], v[172:175], v[48:51]
	v_mfma_f32_16x16x32_bf16 v[36:39], v[208:211], v[180:183], v[36:39]
	v_mfma_f32_16x16x32_bf16 v[32:35], v[216:219], v[180:183], v[32:35]
	v_mfma_f32_16x16x32_bf16 v[20:23], v[208:211], v[188:191], v[20:23]
	v_mfma_f32_16x16x32_bf16 v[16:19], v[216:219], v[188:191], v[16:19]
	v_mfma_f32_16x16x32_bf16 v[4:7], v[208:211], v[200:203], v[4:7]
	v_mfma_f32_16x16x32_bf16 v[0:3], v[216:219], v[200:203], v[0:3]
	v_mfma_f32_16x16x32_bf16 v[52:55], v[212:215], v[176:179], v[52:55]
	v_mfma_f32_16x16x32_bf16 v[48:51], v[220:223], v[176:179], v[48:51]
	v_mfma_f32_16x16x32_bf16 v[36:39], v[212:215], v[184:187], v[36:39]
	v_mfma_f32_16x16x32_bf16 v[32:35], v[220:223], v[184:187], v[32:35]
	v_mfma_f32_16x16x32_bf16 v[20:23], v[212:215], v[196:199], v[20:23]
	v_mfma_f32_16x16x32_bf16 v[16:19], v[220:223], v[196:199], v[16:19]
	v_mfma_f32_16x16x32_bf16 v[4:7], v[212:215], v[204:207], v[4:7]
	v_mfma_f32_16x16x32_bf16 v[0:3], v[220:223], v[204:207], v[0:3]
	s_add_i32 s93, 0, 0x18000
	v_add_u32_e32 v136, s93, v158
	s_barrier
	ds_read_b128 v[148:151], v136
	ds_read_b128 v[152:155], v136 offset:1024
	ds_read_b128 v[164:167], v136 offset:2048
	ds_read_b128 v[168:171], v136 offset:3072
	s_add_u32 s54, s54, 0x40000
	s_addc_u32 s55, s55, 0
	s_mov_b32 m0, s60
	v_lshl_add_u64 v[208:209], s[54:55], 0, v[128:129]
	ds_read_b128 v[172:175], v160 offset:32768
	ds_read_b128 v[176:179], v160 offset:33792
	ds_read_b128 v[180:183], v160 offset:34816
	ds_read_b128 v[184:187], v160 offset:35840
	ds_read_b128 v[188:191], v160 offset:36864
	ds_read_b128 v[196:199], v160 offset:37888
	ds_read_b128 v[200:203], v160 offset:38912
	ds_read_b128 v[204:207], v160 offset:39936
	global_load_lds_dwordx4 v[208:209], off
	v_lshl_add_u64 v[208:209], s[54:55], 0, v[132:133]
	s_mov_b32 m0, s61
	s_nop 0
	global_load_lds_dwordx4 v[208:209], off
	s_waitcnt lgkmcnt(8)
	s_barrier
	s_waitcnt lgkmcnt(7)
	v_mfma_f32_16x16x32_bf16 v[124:127], v[148:151], v[172:175], v[124:127]
	v_mfma_f32_16x16x32_bf16 v[120:123], v[164:167], v[172:175], v[120:123]
	s_waitcnt lgkmcnt(5)
	v_mfma_f32_16x16x32_bf16 v[108:111], v[148:151], v[180:183], v[108:111]
	v_mfma_f32_16x16x32_bf16 v[104:107], v[164:167], v[180:183], v[104:107]
	s_waitcnt lgkmcnt(3)
	v_mfma_f32_16x16x32_bf16 v[92:95], v[148:151], v[188:191], v[92:95]
	v_mfma_f32_16x16x32_bf16 v[88:91], v[164:167], v[188:191], v[88:91]
	s_waitcnt lgkmcnt(1)
	v_mfma_f32_16x16x32_bf16 v[76:79], v[148:151], v[200:203], v[76:79]
	v_mfma_f32_16x16x32_bf16 v[72:75], v[164:167], v[200:203], v[72:75]
	v_mfma_f32_16x16x32_bf16 v[124:127], v[152:155], v[176:179], v[124:127]
	v_mfma_f32_16x16x32_bf16 v[120:123], v[168:171], v[176:179], v[120:123]
	v_mfma_f32_16x16x32_bf16 v[108:111], v[152:155], v[184:187], v[108:111]
	v_mfma_f32_16x16x32_bf16 v[104:107], v[168:171], v[184:187], v[104:107]
	v_mfma_f32_16x16x32_bf16 v[92:95], v[152:155], v[196:199], v[92:95]
	v_mfma_f32_16x16x32_bf16 v[88:91], v[168:171], v[196:199], v[88:91]
	s_waitcnt lgkmcnt(0)
	v_mfma_f32_16x16x32_bf16 v[76:79], v[152:155], v[204:207], v[76:79]
	v_mfma_f32_16x16x32_bf16 v[72:75], v[168:171], v[204:207], v[72:75]
	s_barrier
	s_add_i32 s54, 0, 0x1c000
	s_add_i32 s55, s93, s57
	v_add_u32_e32 v136, s54, v158
	v_lshl_add_u64 v[156:157], v[156:157], 0, s[0:1]
	s_mov_b32 m0, s55
	ds_read_b128 v[208:211], v136
	ds_read_b128 v[212:215], v136 offset:1024
	ds_read_b128 v[216:219], v136 offset:2048
	ds_read_b128 v[220:223], v136 offset:3072
	global_load_lds_dwordx4 v[156:157], off
	v_lshl_add_u64 v[156:157], v[224:225], 0, s[0:1]
	s_add_i32 m0, s55, 0x2000
	s_nop 0
	global_load_lds_dwordx4 v[156:157], off
	s_barrier
	s_waitcnt lgkmcnt(3)
	v_mfma_f32_16x16x32_bf16 v[116:119], v[208:211], v[172:175], v[116:119]
	s_waitcnt lgkmcnt(1)
	v_mfma_f32_16x16x32_bf16 v[112:115], v[216:219], v[172:175], v[112:115]
	v_mfma_f32_16x16x32_bf16 v[100:103], v[208:211], v[180:183], v[100:103]
	v_mfma_f32_16x16x32_bf16 v[96:99], v[216:219], v[180:183], v[96:99]
	v_mfma_f32_16x16x32_bf16 v[84:87], v[208:211], v[188:191], v[84:87]
	v_mfma_f32_16x16x32_bf16 v[80:83], v[216:219], v[188:191], v[80:83]
	v_mfma_f32_16x16x32_bf16 v[68:71], v[208:211], v[200:203], v[68:71]
	v_mfma_f32_16x16x32_bf16 v[64:67], v[216:219], v[200:203], v[64:67]
	v_mfma_f32_16x16x32_bf16 v[116:119], v[212:215], v[176:179], v[116:119]
	s_waitcnt lgkmcnt(0)
	v_mfma_f32_16x16x32_bf16 v[112:115], v[220:223], v[176:179], v[112:115]
	v_mfma_f32_16x16x32_bf16 v[100:103], v[212:215], v[184:187], v[100:103]
	v_mfma_f32_16x16x32_bf16 v[96:99], v[220:223], v[184:187], v[96:99]
	v_mfma_f32_16x16x32_bf16 v[84:87], v[212:215], v[196:199], v[84:87]
	v_mfma_f32_16x16x32_bf16 v[80:83], v[220:223], v[196:199], v[80:83]
	v_mfma_f32_16x16x32_bf16 v[68:71], v[212:215], v[204:207], v[68:71]
	v_mfma_f32_16x16x32_bf16 v[64:67], v[220:223], v[204:207], v[64:67]
	s_mov_b32 m0, s65
	v_lshl_add_u64 v[156:157], v[226:227], 0, s[0:1]
	s_barrier
	ds_read_b128 v[172:175], v160 offset:49152
	ds_read_b128 v[176:179], v160 offset:50176
	ds_read_b128 v[180:183], v160 offset:51200
	ds_read_b128 v[184:187], v160 offset:52224
	ds_read_b128 v[188:191], v160 offset:53248
	ds_read_b128 v[196:199], v160 offset:54272
	ds_read_b128 v[200:203], v160 offset:55296
	ds_read_b128 v[204:207], v160 offset:56320
	global_load_lds_dwordx4 v[156:157], off
	v_lshl_add_u64 v[156:157], v[228:229], 0, s[0:1]
	s_mov_b32 m0, s66
	s_nop 0
	global_load_lds_dwordx4 v[156:157], off
	s_barrier
	s_waitcnt lgkmcnt(7)
	v_mfma_f32_16x16x32_bf16 v[60:63], v[148:151], v[172:175], v[60:63]
	v_mfma_f32_16x16x32_bf16 v[56:59], v[164:167], v[172:175], v[56:59]
	s_waitcnt lgkmcnt(5)
	v_mfma_f32_16x16x32_bf16 v[44:47], v[148:151], v[180:183], v[44:47]
	v_mfma_f32_16x16x32_bf16 v[40:43], v[164:167], v[180:183], v[40:43]
	s_waitcnt lgkmcnt(3)
	v_mfma_f32_16x16x32_bf16 v[28:31], v[148:151], v[188:191], v[28:31]
	v_mfma_f32_16x16x32_bf16 v[24:27], v[164:167], v[188:191], v[24:27]
	s_waitcnt lgkmcnt(1)
	v_mfma_f32_16x16x32_bf16 v[12:15], v[148:151], v[200:203], v[12:15]
	v_mfma_f32_16x16x32_bf16 v[8:11], v[164:167], v[200:203], v[8:11]
	v_mfma_f32_16x16x32_bf16 v[60:63], v[152:155], v[176:179], v[60:63]
	v_mfma_f32_16x16x32_bf16 v[56:59], v[168:171], v[176:179], v[56:59]
	v_mfma_f32_16x16x32_bf16 v[44:47], v[152:155], v[184:187], v[44:47]
	v_mfma_f32_16x16x32_bf16 v[40:43], v[168:171], v[184:187], v[40:43]
	v_mfma_f32_16x16x32_bf16 v[28:31], v[152:155], v[196:199], v[28:31]
	v_mfma_f32_16x16x32_bf16 v[24:27], v[168:171], v[196:199], v[24:27]
	s_waitcnt lgkmcnt(0)
	v_mfma_f32_16x16x32_bf16 v[12:15], v[152:155], v[204:207], v[12:15]
	v_mfma_f32_16x16x32_bf16 v[8:11], v[168:171], v[204:207], v[8:11]
	s_barrier
	s_add_u32 s52, s52, 0x10080
	s_addc_u32 s53, s53, 0
	s_add_i32 s54, s54, s57
	v_lshl_add_u64 v[148:149], s[52:53], 0, v[130:131]
	s_mov_b32 m0, s54
	s_nop 0
	global_load_lds_dwordx4 v[148:149], off
	v_lshl_add_u64 v[148:149], s[52:53], 0, v[134:135]
	s_add_i32 m0, s54, 0x2000
	s_nop 0
	global_load_lds_dwordx4 v[148:149], off
	s_waitcnt vmcnt(6)
	s_barrier
	v_mfma_f32_16x16x32_bf16 v[52:55], v[208:211], v[172:175], v[52:55]
	v_mfma_f32_16x16x32_bf16 v[48:51], v[216:219], v[172:175], v[48:51]
	v_mfma_f32_16x16x32_bf16 v[36:39], v[208:211], v[180:183], v[36:39]
	v_mfma_f32_16x16x32_bf16 v[32:35], v[216:219], v[180:183], v[32:35]
	v_mfma_f32_16x16x32_bf16 v[20:23], v[208:211], v[188:191], v[20:23]
	v_mfma_f32_16x16x32_bf16 v[16:19], v[216:219], v[188:191], v[16:19]
	v_mfma_f32_16x16x32_bf16 v[4:7], v[208:211], v[200:203], v[4:7]
	v_mfma_f32_16x16x32_bf16 v[0:3], v[216:219], v[200:203], v[0:3]
	v_mfma_f32_16x16x32_bf16 v[52:55], v[212:215], v[176:179], v[52:55]
	v_mfma_f32_16x16x32_bf16 v[48:51], v[220:223], v[176:179], v[48:51]
	v_mfma_f32_16x16x32_bf16 v[36:39], v[212:215], v[184:187], v[36:39]
	v_mfma_f32_16x16x32_bf16 v[32:35], v[220:223], v[184:187], v[32:35]
	v_mfma_f32_16x16x32_bf16 v[20:23], v[212:215], v[196:199], v[20:23]
	v_mfma_f32_16x16x32_bf16 v[16:19], v[220:223], v[196:199], v[16:19]
	v_mfma_f32_16x16x32_bf16 v[4:7], v[212:215], v[204:207], v[4:7]
	v_mfma_f32_16x16x32_bf16 v[0:3], v[220:223], v[204:207], v[0:3]
	s_add_i32 s92, s92, 2
	s_add_u32 s50, s50, 0x100
	s_addc_u32 s51, s51, 0
	s_add_u32 s45, s45, 0x100
	s_addc_u32 s91, s91, 0
	s_cmp_gt_u32 s92, 13
	s_barrier
	s_cbranch_scc0 .LBB0_178
	v_lshl_add_u32 v148, s12, 8, v139
	v_and_b32_e32 v149, 24, v138
	s_lshl_b32 s11, s10, 8
	s_or_b32 s11, s11, s87
	s_cmp_gt_i32 s10, 11
	s_cbranch_scc1 .Le1_gates
	s_lshr_b32 s13, s10, 1
	s_lshl_b32 s50, s13, 25
	s_add_u32 s50, s20, s50
	s_addc_u32 s51, s21, 0
	s_bfe_u32 s17, s11, 0x30006
	v_ashrrev_i32_e32 v150, 8, v148
	v_and_or_b32 v150, v150, -8, s17
	v_mov_b32_e32 v151, 0
	v_lshlrev_b64 v[150:151], 18, v[150:151]
	v_lshlrev_b32_e32 v136, 7, v148
	v_and_b32_e32 v136, 0x3ff80, v136
	v_lshl_add_u32 v136, v149, 1, v136
	v_lshl_add_u64 v[150:151], v[150:151], 0, v[136:137]
	v_lshl_add_u64 v[150:151], v[150:151], 0, s[50:51]
	s_movk_i32 s11, 0x800
	s_movk_i32 s17, 0x2800
	s_branch .Le1_addr

.LBB0_342:
	ds_read_b128 v[146:149], v143
	ds_read_b128 v[150:153], v143 offset:1024
	ds_read_b128 v[154:157], v143 offset:2048
	ds_read_b128 v[158:161], v143 offset:3072
	s_add_u32 s46, s44, 0xfffc0080
	s_addc_u32 s47, s45, -1
	s_cmp_eq_u32 s67, 12
	s_cselect_b32 s49, s9, s47
	s_cselect_b32 s48, s63, s46
	s_cselect_b32 s47, s7, s66
	s_cselect_b32 s46, s64, s65
	v_lshl_add_u64 v[190:191], s[44:45], 0, v[136:137]
	s_add_i32 m0, s43, 0xc000
	ds_read_b128 v[162:165], v144
	ds_read_b128 v[166:169], v144 offset:1024
	ds_read_b128 v[170:173], v144 offset:2048
	ds_read_b128 v[174:177], v144 offset:3072
	ds_read_b128 v[178:181], v144 offset:4096
	ds_read_b128 v[182:185], v144 offset:5120
	ds_read_b128 v[186:189], v144 offset:6144
	ds_read_b128 v[196:199], v144 offset:7168
	global_load_lds_dwordx4 v[190:191], off
	v_lshl_add_u64 v[190:191], s[44:45], 0, v[138:139]
	s_add_i32 m0, s43, 0xe000
	s_nop 0
	global_load_lds_dwordx4 v[190:191], off
	s_waitcnt lgkmcnt(8)
	s_barrier
	s_waitcnt lgkmcnt(7)
	v_mfma_f32_16x16x32_bf16 v[124:127], v[146:149], v[162:165], v[124:127]
	v_mfma_f32_16x16x32_bf16 v[120:123], v[154:157], v[162:165], v[120:123]
	s_waitcnt lgkmcnt(5)
	v_mfma_f32_16x16x32_bf16 v[108:111], v[146:149], v[170:173], v[108:111]
	v_mfma_f32_16x16x32_bf16 v[104:107], v[154:157], v[170:173], v[104:107]
	s_waitcnt lgkmcnt(3)
	v_mfma_f32_16x16x32_bf16 v[92:95], v[146:149], v[178:181], v[92:95]
	v_mfma_f32_16x16x32_bf16 v[88:91], v[154:157], v[178:181], v[88:91]
	s_waitcnt lgkmcnt(1)
	v_mfma_f32_16x16x32_bf16 v[76:79], v[146:149], v[186:189], v[76:79]
	v_mfma_f32_16x16x32_bf16 v[72:75], v[154:157], v[186:189], v[72:75]
	v_mfma_f32_16x16x32_bf16 v[124:127], v[150:153], v[166:169], v[124:127]
	v_mfma_f32_16x16x32_bf16 v[120:123], v[158:161], v[166:169], v[120:123]
	v_mfma_f32_16x16x32_bf16 v[108:111], v[150:153], v[174:177], v[108:111]
	v_mfma_f32_16x16x32_bf16 v[104:107], v[158:161], v[174:177], v[104:107]
	v_mfma_f32_16x16x32_bf16 v[92:95], v[150:153], v[182:185], v[92:95]
	v_mfma_f32_16x16x32_bf16 v[88:91], v[158:161], v[182:185], v[88:91]
	s_waitcnt lgkmcnt(0)
	v_mfma_f32_16x16x32_bf16 v[76:79], v[150:153], v[196:199], v[76:79]
	v_mfma_f32_16x16x32_bf16 v[72:75], v[158:161], v[196:199], v[72:75]
	s_barrier
	s_add_i32 s84, s60, s50
	v_lshl_add_u64 v[190:191], s[46:47], 0, v[132:133]
	s_mov_b32 m0, s84
	ds_read_b128 v[200:203], v145
	ds_read_b128 v[204:207], v145 offset:1024
	ds_read_b128 v[208:211], v145 offset:2048
	ds_read_b128 v[212:215], v145 offset:3072
	global_load_lds_dwordx4 v[190:191], off
	v_lshl_add_u64 v[216:217], s[46:47], 0, v[128:129]
	s_add_i32 m0, s84, 0x2000
	s_nop 0
	global_load_lds_dwordx4 v[216:217], off
	s_barrier
	s_waitcnt lgkmcnt(3)
	v_mfma_f32_16x16x32_bf16 v[116:119], v[200:203], v[162:165], v[116:119]
	s_waitcnt lgkmcnt(1)
	v_mfma_f32_16x16x32_bf16 v[112:115], v[208:211], v[162:165], v[112:115]
	v_mfma_f32_16x16x32_bf16 v[100:103], v[200:203], v[170:173], v[100:103]
	v_mfma_f32_16x16x32_bf16 v[96:99], v[208:211], v[170:173], v[96:99]
	v_mfma_f32_16x16x32_bf16 v[84:87], v[200:203], v[178:181], v[84:87]
	v_mfma_f32_16x16x32_bf16 v[80:83], v[208:211], v[178:181], v[80:83]
	v_mfma_f32_16x16x32_bf16 v[68:71], v[200:203], v[186:189], v[68:71]
	v_mfma_f32_16x16x32_bf16 v[64:67], v[208:211], v[186:189], v[64:67]
	v_mfma_f32_16x16x32_bf16 v[116:119], v[204:207], v[166:169], v[116:119]
	s_waitcnt lgkmcnt(0)
	v_mfma_f32_16x16x32_bf16 v[112:115], v[212:215], v[166:169], v[112:115]
	v_mfma_f32_16x16x32_bf16 v[100:103], v[204:207], v[174:177], v[100:103]
	v_mfma_f32_16x16x32_bf16 v[96:99], v[212:215], v[174:177], v[96:99]
	v_mfma_f32_16x16x32_bf16 v[84:87], v[204:207], v[182:185], v[84:87]
	v_mfma_f32_16x16x32_bf16 v[80:83], v[212:215], v[182:185], v[80:83]
	v_mfma_f32_16x16x32_bf16 v[68:71], v[204:207], v[196:199], v[68:71]
	v_mfma_f32_16x16x32_bf16 v[64:67], v[212:215], v[196:199], v[64:67]
	s_mov_b32 m0, s43
	v_lshl_add_u64 v[218:219], s[48:49], 0, v[134:135]
	s_barrier
	ds_read_b128 v[162:165], v144 offset:16384
	ds_read_b128 v[166:169], v144 offset:17408
	ds_read_b128 v[170:173], v144 offset:18432
	ds_read_b128 v[174:177], v144 offset:19456
	ds_read_b128 v[178:181], v144 offset:20480
	ds_read_b128 v[182:185], v144 offset:21504
	ds_read_b128 v[186:189], v144 offset:22528
	ds_read_b128 v[196:199], v144 offset:23552
	global_load_lds_dwordx4 v[218:219], off
	v_lshl_add_u64 v[220:221], s[48:49], 0, v[130:131]
	s_mov_b32 m0, s52
	s_nop 0
	global_load_lds_dwordx4 v[220:221], off
	s_barrier
	s_waitcnt lgkmcnt(7)
	v_mfma_f32_16x16x32_bf16 v[60:63], v[146:149], v[162:165], v[60:63]
	v_mfma_f32_16x16x32_bf16 v[56:59], v[154:157], v[162:165], v[56:59]
	s_waitcnt lgkmcnt(5)
	v_mfma_f32_16x16x32_bf16 v[44:47], v[146:149], v[170:173], v[44:47]
	v_mfma_f32_16x16x32_bf16 v[40:43], v[154:157], v[170:173], v[40:43]
	s_waitcnt lgkmcnt(3)
	v_mfma_f32_16x16x32_bf16 v[28:31], v[146:149], v[178:181], v[28:31]
	v_mfma_f32_16x16x32_bf16 v[24:27], v[154:157], v[178:181], v[24:27]
	s_waitcnt lgkmcnt(1)
	v_mfma_f32_16x16x32_bf16 v[12:15], v[146:149], v[186:189], v[12:15]
	v_mfma_f32_16x16x32_bf16 v[8:11], v[154:157], v[186:189], v[8:11]
	v_mfma_f32_16x16x32_bf16 v[60:63], v[150:153], v[166:169], v[60:63]
	v_mfma_f32_16x16x32_bf16 v[56:59], v[158:161], v[166:169], v[56:59]
	v_mfma_f32_16x16x32_bf16 v[44:47], v[150:153], v[174:177], v[44:47]
	v_mfma_f32_16x16x32_bf16 v[40:43], v[158:161], v[174:177], v[40:43]
	v_mfma_f32_16x16x32_bf16 v[28:31], v[150:153], v[182:185], v[28:31]
	v_mfma_f32_16x16x32_bf16 v[24:27], v[158:161], v[182:185], v[24:27]
	s_waitcnt lgkmcnt(0)
	v_mfma_f32_16x16x32_bf16 v[12:15], v[150:153], v[196:199], v[12:15]
	v_mfma_f32_16x16x32_bf16 v[8:11], v[158:161], v[196:199], v[8:11]
	s_barrier
	s_add_u32 s84, s46, 0x10000
	s_addc_u32 s85, s47, 0
	s_add_i32 s89, s61, s50
	v_lshl_add_u64 v[146:147], s[84:85], 0, v[132:133]
	s_mov_b32 m0, s89
	s_nop 0
	global_load_lds_dwordx4 v[146:147], off
	v_lshl_add_u64 v[146:147], s[84:85], 0, v[128:129]
	s_add_i32 m0, s89, 0x2000
	s_nop 0
	global_load_lds_dwordx4 v[146:147], off
	s_waitcnt vmcnt(6)
	s_barrier
	v_mfma_f32_16x16x32_bf16 v[52:55], v[200:203], v[162:165], v[52:55]
	v_mfma_f32_16x16x32_bf16 v[48:51], v[208:211], v[162:165], v[48:51]
	v_mfma_f32_16x16x32_bf16 v[36:39], v[200:203], v[170:173], v[36:39]
	v_mfma_f32_16x16x32_bf16 v[32:35], v[208:211], v[170:173], v[32:35]
	v_mfma_f32_16x16x32_bf16 v[20:23], v[200:203], v[178:181], v[20:23]
	v_mfma_f32_16x16x32_bf16 v[16:19], v[208:211], v[178:181], v[16:19]
	v_mfma_f32_16x16x32_bf16 v[4:7], v[200:203], v[186:189], v[4:7]
	v_mfma_f32_16x16x32_bf16 v[0:3], v[208:211], v[186:189], v[0:3]
	v_mfma_f32_16x16x32_bf16 v[52:55], v[204:207], v[166:169], v[52:55]
	v_mfma_f32_16x16x32_bf16 v[48:51], v[212:215], v[166:169], v[48:51]
	v_mfma_f32_16x16x32_bf16 v[36:39], v[204:207], v[174:177], v[36:39]
	v_mfma_f32_16x16x32_bf16 v[32:35], v[212:215], v[174:177], v[32:35]
	v_mfma_f32_16x16x32_bf16 v[20:23], v[204:207], v[182:185], v[20:23]
	v_mfma_f32_16x16x32_bf16 v[16:19], v[212:215], v[182:185], v[16:19]
	v_mfma_f32_16x16x32_bf16 v[4:7], v[204:207], v[196:199], v[4:7]
	v_mfma_f32_16x16x32_bf16 v[0:3], v[212:215], v[196:199], v[0:3]
	s_add_i32 s84, 0, 0x18000
	v_add_u32_e32 v158, s84, v141
	s_barrier
	ds_read_b128 v[146:149], v158
	ds_read_b128 v[150:153], v158 offset:1024
	ds_read_b128 v[154:157], v158 offset:2048
	ds_read_b128 v[158:161], v158 offset:3072
	s_add_u32 s48, s48, 0x40000
	s_addc_u32 s49, s49, 0
	s_mov_b32 m0, s53
	v_lshl_add_u64 v[200:201], s[48:49], 0, v[134:135]
	ds_read_b128 v[162:165], v144 offset:32768
	ds_read_b128 v[166:169], v144 offset:33792
	ds_read_b128 v[170:173], v144 offset:34816
	ds_read_b128 v[174:177], v144 offset:35840
	ds_read_b128 v[178:181], v144 offset:36864
	ds_read_b128 v[182:185], v144 offset:37888
	ds_read_b128 v[186:189], v144 offset:38912
	ds_read_b128 v[196:199], v144 offset:39936
	global_load_lds_dwordx4 v[200:201], off
	v_lshl_add_u64 v[200:201], s[48:49], 0, v[130:131]
	s_mov_b32 m0, s54
	s_nop 0
	global_load_lds_dwordx4 v[200:201], off
	s_waitcnt lgkmcnt(8)
	s_barrier
	s_waitcnt lgkmcnt(7)
	v_mfma_f32_16x16x32_bf16 v[124:127], v[146:149], v[162:165], v[124:127]
	v_mfma_f32_16x16x32_bf16 v[120:123], v[154:157], v[162:165], v[120:123]
	s_waitcnt lgkmcnt(5)
	v_mfma_f32_16x16x32_bf16 v[108:111], v[146:149], v[170:173], v[108:111]
	v_mfma_f32_16x16x32_bf16 v[104:107], v[154:157], v[170:173], v[104:107]
	s_waitcnt lgkmcnt(3)
	v_mfma_f32_16x16x32_bf16 v[92:95], v[146:149], v[178:181], v[92:95]
	v_mfma_f32_16x16x32_bf16 v[88:91], v[154:157], v[178:181], v[88:91]
	s_waitcnt lgkmcnt(1)
	v_mfma_f32_16x16x32_bf16 v[76:79], v[146:149], v[186:189], v[76:79]
	v_mfma_f32_16x16x32_bf16 v[72:75], v[154:157], v[186:189], v[72:75]
	v_mfma_f32_16x16x32_bf16 v[124:127], v[150:153], v[166:169], v[124:127]
	v_mfma_f32_16x16x32_bf16 v[120:123], v[158:161], v[166:169], v[120:123]
	v_mfma_f32_16x16x32_bf16 v[108:111], v[150:153], v[174:177], v[108:111]
	v_mfma_f32_16x16x32_bf16 v[104:107], v[158:161], v[174:177], v[104:107]
	v_mfma_f32_16x16x32_bf16 v[92:95], v[150:153], v[182:185], v[92:95]
	v_mfma_f32_16x16x32_bf16 v[88:91], v[158:161], v[182:185], v[88:91]
	s_waitcnt lgkmcnt(0)
	v_mfma_f32_16x16x32_bf16 v[76:79], v[150:153], v[196:199], v[76:79]
	v_mfma_f32_16x16x32_bf16 v[72:75], v[158:161], v[196:199], v[72:75]
	s_barrier
	s_add_i32 s48, 0, 0x1c000
	s_add_i32 s49, s84, s50
	v_add_u32_e32 v195, s48, v141
	v_lshl_add_u64 v[190:191], v[190:191], 0, s[0:1]
	s_mov_b32 m0, s49
	ds_read_b128 v[200:203], v195
	ds_read_b128 v[204:207], v195 offset:1024
	ds_read_b128 v[208:211], v195 offset:2048
	ds_read_b128 v[212:215], v195 offset:3072
	global_load_lds_dwordx4 v[190:191], off
	v_lshl_add_u64 v[190:191], v[216:217], 0, s[0:1]
	s_add_i32 m0, s49, 0x2000
	s_nop 0
	global_load_lds_dwordx4 v[190:191], off
	s_barrier
	s_waitcnt lgkmcnt(3)
	v_mfma_f32_16x16x32_bf16 v[116:119], v[200:203], v[162:165], v[116:119]
	s_waitcnt lgkmcnt(1)
	v_mfma_f32_16x16x32_bf16 v[112:115], v[208:211], v[162:165], v[112:115]
	v_mfma_f32_16x16x32_bf16 v[100:103], v[200:203], v[170:173], v[100:103]
	v_mfma_f32_16x16x32_bf16 v[96:99], v[208:211], v[170:173], v[96:99]
	v_mfma_f32_16x16x32_bf16 v[84:87], v[200:203], v[178:181], v[84:87]
	v_mfma_f32_16x16x32_bf16 v[80:83], v[208:211], v[178:181], v[80:83]
	v_mfma_f32_16x16x32_bf16 v[68:71], v[200:203], v[186:189], v[68:71]
	v_mfma_f32_16x16x32_bf16 v[64:67], v[208:211], v[186:189], v[64:67]
	v_mfma_f32_16x16x32_bf16 v[116:119], v[204:207], v[166:169], v[116:119]
	s_waitcnt lgkmcnt(0)
	v_mfma_f32_16x16x32_bf16 v[112:115], v[212:215], v[166:169], v[112:115]
	v_mfma_f32_16x16x32_bf16 v[100:103], v[204:207], v[174:177], v[100:103]
	v_mfma_f32_16x16x32_bf16 v[96:99], v[212:215], v[174:177], v[96:99]
	v_mfma_f32_16x16x32_bf16 v[84:87], v[204:207], v[182:185], v[84:87]
	v_mfma_f32_16x16x32_bf16 v[80:83], v[212:215], v[182:185], v[80:83]
	v_mfma_f32_16x16x32_bf16 v[68:71], v[204:207], v[196:199], v[68:71]
	v_mfma_f32_16x16x32_bf16 v[64:67], v[212:215], v[196:199], v[64:67]
	s_mov_b32 m0, s57
	v_lshl_add_u64 v[190:191], v[218:219], 0, s[0:1]
	s_barrier
	ds_read_b128 v[162:165], v144 offset:49152
	ds_read_b128 v[166:169], v144 offset:50176
	ds_read_b128 v[170:173], v144 offset:51200
	ds_read_b128 v[174:177], v144 offset:52224
	ds_read_b128 v[178:181], v144 offset:53248
	ds_read_b128 v[182:185], v144 offset:54272
	ds_read_b128 v[186:189], v144 offset:55296
	ds_read_b128 v[196:199], v144 offset:56320
	global_load_lds_dwordx4 v[190:191], off
	v_lshl_add_u64 v[190:191], v[220:221], 0, s[0:1]
	s_mov_b32 m0, s58
	s_nop 0
	global_load_lds_dwordx4 v[190:191], off
	s_barrier
	s_waitcnt lgkmcnt(7)
	v_mfma_f32_16x16x32_bf16 v[60:63], v[146:149], v[162:165], v[60:63]
	v_mfma_f32_16x16x32_bf16 v[56:59], v[154:157], v[162:165], v[56:59]
	s_waitcnt lgkmcnt(5)
	v_mfma_f32_16x16x32_bf16 v[44:47], v[146:149], v[170:173], v[44:47]
	v_mfma_f32_16x16x32_bf16 v[40:43], v[154:157], v[170:173], v[40:43]
	s_waitcnt lgkmcnt(3)
	v_mfma_f32_16x16x32_bf16 v[28:31], v[146:149], v[178:181], v[28:31]
	v_mfma_f32_16x16x32_bf16 v[24:27], v[154:157], v[178:181], v[24:27]
	s_waitcnt lgkmcnt(1)
	v_mfma_f32_16x16x32_bf16 v[12:15], v[146:149], v[186:189], v[12:15]
	v_mfma_f32_16x16x32_bf16 v[8:11], v[154:157], v[186:189], v[8:11]
	v_mfma_f32_16x16x32_bf16 v[60:63], v[150:153], v[166:169], v[60:63]
	v_mfma_f32_16x16x32_bf16 v[56:59], v[158:161], v[166:169], v[56:59]
	v_mfma_f32_16x16x32_bf16 v[44:47], v[150:153], v[174:177], v[44:47]
	v_mfma_f32_16x16x32_bf16 v[40:43], v[158:161], v[174:177], v[40:43]
	v_mfma_f32_16x16x32_bf16 v[28:31], v[150:153], v[182:185], v[28:31]
	v_mfma_f32_16x16x32_bf16 v[24:27], v[158:161], v[182:185], v[24:27]
	s_waitcnt lgkmcnt(0)
	v_mfma_f32_16x16x32_bf16 v[12:15], v[150:153], v[196:199], v[12:15]
	v_mfma_f32_16x16x32_bf16 v[8:11], v[158:161], v[196:199], v[8:11]
	s_barrier
	s_add_u32 s46, s46, 0x10080
	s_addc_u32 s47, s47, 0
	s_add_i32 s48, s48, s50
	v_lshl_add_u64 v[146:147], s[46:47], 0, v[132:133]
	s_mov_b32 m0, s48
	s_nop 0
	global_load_lds_dwordx4 v[146:147], off
	v_lshl_add_u64 v[146:147], s[46:47], 0, v[128:129]
	s_add_i32 m0, s48, 0x2000
	s_nop 0
	global_load_lds_dwordx4 v[146:147], off
	s_waitcnt vmcnt(6)
	s_barrier
	v_mfma_f32_16x16x32_bf16 v[52:55], v[200:203], v[162:165], v[52:55]
	v_mfma_f32_16x16x32_bf16 v[48:51], v[208:211], v[162:165], v[48:51]
	v_mfma_f32_16x16x32_bf16 v[36:39], v[200:203], v[170:173], v[36:39]
	v_mfma_f32_16x16x32_bf16 v[32:35], v[208:211], v[170:173], v[32:35]
	v_mfma_f32_16x16x32_bf16 v[20:23], v[200:203], v[178:181], v[20:23]
	v_mfma_f32_16x16x32_bf16 v[16:19], v[208:211], v[178:181], v[16:19]
	v_mfma_f32_16x16x32_bf16 v[4:7], v[200:203], v[186:189], v[4:7]
	v_mfma_f32_16x16x32_bf16 v[0:3], v[208:211], v[186:189], v[0:3]
	v_mfma_f32_16x16x32_bf16 v[52:55], v[204:207], v[166:169], v[52:55]
	v_mfma_f32_16x16x32_bf16 v[48:51], v[212:215], v[166:169], v[48:51]
	v_mfma_f32_16x16x32_bf16 v[36:39], v[204:207], v[174:177], v[36:39]
	v_mfma_f32_16x16x32_bf16 v[32:35], v[212:215], v[174:177], v[32:35]
	v_mfma_f32_16x16x32_bf16 v[20:23], v[204:207], v[182:185], v[20:23]
	v_mfma_f32_16x16x32_bf16 v[16:19], v[212:215], v[182:185], v[16:19]
	v_mfma_f32_16x16x32_bf16 v[4:7], v[204:207], v[196:199], v[4:7]
	v_mfma_f32_16x16x32_bf16 v[0:3], v[212:215], v[196:199], v[0:3]
	s_add_i32 s67, s67, 2
	s_add_u32 s44, s44, 0x100
	s_addc_u32 s45, s45, 0
	s_add_u32 s65, s65, 0x100
	s_addc_u32 s66, s66, 0
	s_cmp_gt_u32 s67, 13
	s_barrier
	s_cbranch_scc0 .LBB0_342
	v_cvt_pk_bf16_f32 v124, v124, v125
	v_cvt_pk_bf16_f32 v120, v120, v121
	v_cvt_pk_bf16_f32 v121, v122, v123
	v_cvt_pk_bf16_f32 v122, v116, v117
	v_cvt_pk_bf16_f32 v112, v112, v113
	v_cvt_pk_bf16_f32 v125, v126, v127
	v_cvt_pk_bf16_f32 v118, v118, v119
	v_cvt_pk_bf16_f32 v113, v114, v115
	v_cndmask_b32_e64 v114, v124, v122, s[2:3]
	v_mov_b32_e32 v123, 0
	v_cndmask_b32_e64 v115, v120, v112, s[2:3]
	v_mov_b32_e32 v126, 0
	v_lshl_add_u32 v148, s42, 8, v140
	v_mov_b32_dpp v123, v114 row_ror:8 row_mask:0xf bank_mask:0xf
	v_cndmask_b32_e64 v114, v125, v118, s[2:3]
	v_mov_b32_e32 v119, 0
	v_mov_b32_dpp v126, v115 row_ror:8 row_mask:0xf bank_mask:0xf
	v_mov_b32_e32 v127, 0
	v_mov_b32_dpp v119, v114 row_ror:8 row_mask:0xf bank_mask:0xf
	v_cndmask_b32_e64 v114, v121, v113, s[2:3]
	v_cndmask_b32_e64 v116, v126, v120, s[2:3]
	v_cndmask_b32_e64 v120, v112, v126, s[2:3]
	v_add_u32_e32 v112, -8, v148
	v_mov_b32_dpp v127, v114 row_ror:8 row_mask:0xf bank_mask:0xf
	v_cndmask_b32_e64 v112, v112, v148, s[2:3]
	v_lshl_or_b32 v146, s62, 8, v142
	v_cndmask_b32_e64 v117, v127, v121, s[2:3]
	v_cndmask_b32_e64 v121, v113, v127, s[2:3]
	v_ashrrev_i32_e32 v113, 31, v112
	v_ashrrev_i32_e32 v147, 31, v146
	v_lshlrev_b64 v[112:113], 11, v[112:113]
	v_cndmask_b32_e64 v115, v119, v125, s[2:3]
	v_cndmask_b32_e64 v114, v123, v124, s[2:3]
	v_cndmask_b32_e64 v119, v118, v119, s[2:3]
	v_cndmask_b32_e64 v118, v122, v123, s[2:3]
	v_lshl_add_u64 v[122:123], s[40:41], 0, v[112:113]
	v_lshlrev_b64 v[112:113], 1, v[146:147]
	v_lshl_add_u64 v[122:123], v[122:123], 0, v[112:113]
	global_store_dwordx4 v[122:123], v[114:117], off
	v_cvt_pk_bf16_f32 v108, v108, v109
	v_cvt_pk_bf16_f32 v100, v100, v101
	v_add_u32_e32 v116, 8, v148
	v_cndmask_b32_e64 v114, v148, v116, s[2:3]
	v_ashrrev_i32_e32 v115, 31, v114
	v_lshlrev_b64 v[114:115], 11, v[114:115]
	v_lshl_add_u64 v[114:115], s[40:41], 0, v[114:115]
	v_cvt_pk_bf16_f32 v109, v110, v111
	v_cvt_pk_bf16_f32 v104, v104, v105
	v_cvt_pk_bf16_f32 v105, v106, v107
	v_cvt_pk_bf16_f32 v101, v102, v103
	v_cvt_pk_bf16_f32 v102, v96, v97
	v_cndmask_b32_e64 v96, v108, v100, s[2:3]
	v_mov_b32_e32 v106, 0
	v_lshl_add_u64 v[114:115], v[114:115], 0, v[112:113]
	v_cvt_pk_bf16_f32 v103, v98, v99
	v_mov_b32_dpp v106, v96 row_ror:8 row_mask:0xf bank_mask:0xf
	v_cndmask_b32_e64 v96, v109, v101, s[2:3]
	v_mov_b32_e32 v107, 0
	v_cndmask_b32_e64 v97, v104, v102, s[2:3]
	v_mov_b32_e32 v110, 0
	global_store_dwordx4 v[114:115], v[118:121], off
	v_or_b32_e32 v114, 16, v148
	v_mov_b32_dpp v107, v96 row_ror:8 row_mask:0xf bank_mask:0xf
	v_cndmask_b32_e64 v96, v105, v103, s[2:3]
	v_mov_b32_dpp v110, v97 row_ror:8 row_mask:0xf bank_mask:0xf
	v_mov_b32_e32 v111, 0
	v_cndmask_b32_e64 v98, v110, v104, s[2:3]
	v_cndmask_b32_e64 v104, v116, v114, s[2:3]
	v_mov_b32_dpp v111, v96 row_ror:8 row_mask:0xf bank_mask:0xf
	v_cndmask_b32_e64 v99, v111, v105, s[2:3]
	v_ashrrev_i32_e32 v105, 31, v104
	v_lshlrev_b64 v[104:105], 11, v[104:105]
	v_lshl_add_u64 v[104:105], s[40:41], 0, v[104:105]
	v_cndmask_b32_e64 v97, v107, v109, s[2:3]
	v_cndmask_b32_e64 v96, v106, v108, s[2:3]
	v_lshl_add_u64 v[104:105], v[104:105], 0, v[112:113]
	global_store_dwordx4 v[104:105], v[96:99], off
	v_cvt_pk_bf16_f32 v92, v92, v93
	v_cvt_pk_bf16_f32 v84, v84, v85
	v_add_u32_e32 v98, 24, v148
	v_cndmask_b32_e64 v96, v114, v98, s[2:3]
	v_ashrrev_i32_e32 v97, 31, v96
	v_lshlrev_b64 v[96:97], 11, v[96:97]
	v_lshl_add_u64 v[96:97], s[40:41], 0, v[96:97]
	v_cvt_pk_bf16_f32 v93, v94, v95
	v_cvt_pk_bf16_f32 v88, v88, v89
	v_cvt_pk_bf16_f32 v89, v90, v91
	v_cvt_pk_bf16_f32 v85, v86, v87
	v_cvt_pk_bf16_f32 v86, v80, v81
	v_cndmask_b32_e64 v80, v92, v84, s[2:3]
	v_mov_b32_e32 v90, 0
	v_cndmask_b32_e64 v103, v103, v111, s[2:3]
	v_cndmask_b32_e64 v102, v102, v110, s[2:3]
	v_cndmask_b32_e64 v101, v101, v107, s[2:3]
	v_cndmask_b32_e64 v100, v100, v106, s[2:3]
	v_lshl_add_u64 v[96:97], v[96:97], 0, v[112:113]
	v_cvt_pk_bf16_f32 v87, v82, v83
	v_mov_b32_dpp v90, v80 row_ror:8 row_mask:0xf bank_mask:0xf
	v_cndmask_b32_e64 v80, v93, v85, s[2:3]
	v_mov_b32_e32 v91, 0
	v_cndmask_b32_e64 v81, v88, v86, s[2:3]
	v_mov_b32_e32 v94, 0
	global_store_dwordx4 v[96:97], v[100:103], off
	v_or_b32_e32 v96, 32, v148
	v_mov_b32_dpp v91, v80 row_ror:8 row_mask:0xf bank_mask:0xf
	v_cndmask_b32_e64 v80, v89, v87, s[2:3]
	v_mov_b32_dpp v94, v81 row_ror:8 row_mask:0xf bank_mask:0xf
	v_mov_b32_e32 v95, 0
	v_cndmask_b32_e64 v82, v94, v88, s[2:3]
	v_cndmask_b32_e64 v88, v98, v96, s[2:3]
	v_mov_b32_dpp v95, v80 row_ror:8 row_mask:0xf bank_mask:0xf
	v_cndmask_b32_e64 v83, v95, v89, s[2:3]
	v_ashrrev_i32_e32 v89, 31, v88
	v_lshlrev_b64 v[88:89], 11, v[88:89]
	v_lshl_add_u64 v[88:89], s[40:41], 0, v[88:89]
	v_cndmask_b32_e64 v81, v91, v93, s[2:3]
	v_cndmask_b32_e64 v80, v90, v92, s[2:3]
	v_lshl_add_u64 v[88:89], v[88:89], 0, v[112:113]
	global_store_dwordx4 v[88:89], v[80:83], off
	v_cvt_pk_bf16_f32 v76, v76, v77
	v_cvt_pk_bf16_f32 v68, v68, v69
	v_add_u32_e32 v82, 40, v148
	v_cndmask_b32_e64 v80, v96, v82, s[2:3]
	v_ashrrev_i32_e32 v81, 31, v80
	v_lshlrev_b64 v[80:81], 11, v[80:81]
	v_lshl_add_u64 v[80:81], s[40:41], 0, v[80:81]
	v_cvt_pk_bf16_f32 v77, v78, v79
	v_cvt_pk_bf16_f32 v72, v72, v73
	v_cvt_pk_bf16_f32 v73, v74, v75
	v_cvt_pk_bf16_f32 v69, v70, v71
	v_cvt_pk_bf16_f32 v70, v64, v65
	v_cndmask_b32_e64 v64, v76, v68, s[2:3]
	v_mov_b32_e32 v74, 0
	v_cndmask_b32_e64 v87, v87, v95, s[2:3]
	v_cndmask_b32_e64 v86, v86, v94, s[2:3]
	v_cndmask_b32_e64 v85, v85, v91, s[2:3]
	v_cndmask_b32_e64 v84, v84, v90, s[2:3]
	v_lshl_add_u64 v[80:81], v[80:81], 0, v[112:113]
	v_cvt_pk_bf16_f32 v71, v66, v67
	v_mov_b32_dpp v74, v64 row_ror:8 row_mask:0xf bank_mask:0xf
	v_cndmask_b32_e64 v64, v77, v69, s[2:3]
	v_mov_b32_e32 v75, 0
	v_cndmask_b32_e64 v65, v72, v70, s[2:3]
	v_mov_b32_e32 v78, 0
	global_store_dwordx4 v[80:81], v[84:87], off
	v_or_b32_e32 v80, 48, v148
	v_mov_b32_dpp v75, v64 row_ror:8 row_mask:0xf bank_mask:0xf
	v_cndmask_b32_e64 v64, v73, v71, s[2:3]
	v_mov_b32_dpp v78, v65 row_ror:8 row_mask:0xf bank_mask:0xf
	v_mov_b32_e32 v79, 0
	v_cndmask_b32_e64 v66, v78, v72, s[2:3]
	v_cndmask_b32_e64 v72, v82, v80, s[2:3]
	v_mov_b32_dpp v79, v64 row_ror:8 row_mask:0xf bank_mask:0xf
	v_cndmask_b32_e64 v67, v79, v73, s[2:3]
	v_ashrrev_i32_e32 v73, 31, v72
	v_lshlrev_b64 v[72:73], 11, v[72:73]
	v_lshl_add_u64 v[72:73], s[40:41], 0, v[72:73]
	v_cndmask_b32_e64 v65, v75, v77, s[2:3]
	v_cndmask_b32_e64 v64, v74, v76, s[2:3]
	v_lshl_add_u64 v[72:73], v[72:73], 0, v[112:113]
	global_store_dwordx4 v[72:73], v[64:67], off
	v_cvt_pk_bf16_f32 v60, v60, v61
	v_cvt_pk_bf16_f32 v56, v56, v57
	v_add_u32_e32 v64, 56, v148
	v_cndmask_b32_e64 v64, v80, v64, s[2:3]
	v_ashrrev_i32_e32 v65, 31, v64
	v_lshlrev_b64 v[64:65], 11, v[64:65]
	v_cvt_pk_bf16_f32 v52, v52, v53
	v_cvt_pk_bf16_f32 v53, v54, v55
	v_cvt_pk_bf16_f32 v54, v48, v49
	v_lshl_add_u64 v[64:65], s[40:41], 0, v[64:65]
	v_cvt_pk_bf16_f32 v61, v62, v63
	v_cvt_pk_bf16_f32 v57, v58, v59
	v_cndmask_b32_e64 v48, v60, v52, s[2:3]
	v_mov_b32_e32 v58, 0
	v_cndmask_b32_e64 v49, v56, v54, s[2:3]
	v_mov_b32_e32 v62, 0
	v_cndmask_b32_e64 v71, v71, v79, s[2:3]
	v_cndmask_b32_e64 v70, v70, v78, s[2:3]
	v_cndmask_b32_e64 v69, v69, v75, s[2:3]
	v_cndmask_b32_e64 v68, v68, v74, s[2:3]
	v_lshl_add_u64 v[64:65], v[64:65], 0, v[112:113]
	v_cvt_pk_bf16_f32 v55, v50, v51
	v_mov_b32_dpp v58, v48 row_ror:8 row_mask:0xf bank_mask:0xf
	v_cndmask_b32_e64 v48, v61, v53, s[2:3]
	v_mov_b32_e32 v59, 0
	v_mov_b32_dpp v62, v49 row_ror:8 row_mask:0xf bank_mask:0xf
	global_store_dwordx4 v[64:65], v[68:71], off
	v_add_u32_e32 v64, 0x80, v148
	v_mov_b32_dpp v59, v48 row_ror:8 row_mask:0xf bank_mask:0xf
	v_cndmask_b32_e64 v48, v57, v55, s[2:3]
	v_mov_b32_e32 v63, 0
	v_cndmask_b32_e64 v50, v62, v56, s[2:3]
	v_add_u32_e32 v56, 0x78, v148
	v_mov_b32_dpp v63, v48 row_ror:8 row_mask:0xf bank_mask:0xf
	v_cndmask_b32_e64 v56, v56, v64, s[2:3]
	v_cndmask_b32_e64 v51, v63, v57, s[2:3]
	v_ashrrev_i32_e32 v57, 31, v56
	v_lshlrev_b64 v[56:57], 11, v[56:57]
	v_lshl_add_u64 v[56:57], s[40:41], 0, v[56:57]
	v_cndmask_b32_e64 v49, v59, v61, s[2:3]
	v_cndmask_b32_e64 v48, v58, v60, s[2:3]
	v_lshl_add_u64 v[56:57], v[56:57], 0, v[112:113]
	global_store_dwordx4 v[56:57], v[48:51], off
	v_cvt_pk_bf16_f32 v44, v44, v45
	v_cvt_pk_bf16_f32 v36, v36, v37
	v_add_u32_e32 v50, 0x88, v148
	v_cndmask_b32_e64 v48, v64, v50, s[2:3]
	v_ashrrev_i32_e32 v49, 31, v48
	v_lshlrev_b64 v[48:49], 11, v[48:49]
	v_lshl_add_u64 v[48:49], s[40:41], 0, v[48:49]
	v_cvt_pk_bf16_f32 v45, v46, v47
	v_cvt_pk_bf16_f32 v40, v40, v41
	v_cvt_pk_bf16_f32 v41, v42, v43
	v_cvt_pk_bf16_f32 v37, v38, v39
	v_cvt_pk_bf16_f32 v38, v32, v33
	v_cndmask_b32_e64 v32, v44, v36, s[2:3]
	v_mov_b32_e32 v42, 0
	v_cndmask_b32_e64 v55, v55, v63, s[2:3]
	v_cndmask_b32_e64 v54, v54, v62, s[2:3]
	v_cndmask_b32_e64 v53, v53, v59, s[2:3]
	v_cndmask_b32_e64 v52, v52, v58, s[2:3]
	v_lshl_add_u64 v[48:49], v[48:49], 0, v[112:113]
	v_cvt_pk_bf16_f32 v39, v34, v35
	v_mov_b32_dpp v42, v32 row_ror:8 row_mask:0xf bank_mask:0xf
	v_cndmask_b32_e64 v32, v45, v37, s[2:3]
	v_mov_b32_e32 v43, 0
	v_cndmask_b32_e64 v33, v40, v38, s[2:3]
	v_mov_b32_e32 v46, 0
	global_store_dwordx4 v[48:49], v[52:55], off
	v_add_u32_e32 v48, 0x90, v148
	v_mov_b32_dpp v43, v32 row_ror:8 row_mask:0xf bank_mask:0xf
	v_cndmask_b32_e64 v32, v41, v39, s[2:3]
	v_mov_b32_dpp v46, v33 row_ror:8 row_mask:0xf bank_mask:0xf
	v_mov_b32_e32 v47, 0
	v_cndmask_b32_e64 v34, v46, v40, s[2:3]
	v_cndmask_b32_e64 v40, v50, v48, s[2:3]
	v_mov_b32_dpp v47, v32 row_ror:8 row_mask:0xf bank_mask:0xf
	v_cndmask_b32_e64 v35, v47, v41, s[2:3]
	v_ashrrev_i32_e32 v41, 31, v40
	v_lshlrev_b64 v[40:41], 11, v[40:41]
	v_lshl_add_u64 v[40:41], s[40:41], 0, v[40:41]
	v_cndmask_b32_e64 v33, v43, v45, s[2:3]
	v_cndmask_b32_e64 v32, v42, v44, s[2:3]
	v_lshl_add_u64 v[40:41], v[40:41], 0, v[112:113]
	global_store_dwordx4 v[40:41], v[32:35], off
	v_cvt_pk_bf16_f32 v28, v28, v29
	v_cvt_pk_bf16_f32 v20, v20, v21
	v_add_u32_e32 v34, 0x98, v148
	v_cndmask_b32_e64 v32, v48, v34, s[2:3]
	v_ashrrev_i32_e32 v33, 31, v32
	v_lshlrev_b64 v[32:33], 11, v[32:33]
	v_lshl_add_u64 v[32:33], s[40:41], 0, v[32:33]
	v_cvt_pk_bf16_f32 v29, v30, v31
	v_cvt_pk_bf16_f32 v24, v24, v25
	v_cvt_pk_bf16_f32 v25, v26, v27
	v_cvt_pk_bf16_f32 v21, v22, v23
	v_cvt_pk_bf16_f32 v22, v16, v17
	v_cndmask_b32_e64 v16, v28, v20, s[2:3]
	v_mov_b32_e32 v26, 0
	v_cndmask_b32_e64 v39, v39, v47, s[2:3]
	v_cndmask_b32_e64 v38, v38, v46, s[2:3]
	v_cndmask_b32_e64 v37, v37, v43, s[2:3]
	v_cndmask_b32_e64 v36, v36, v42, s[2:3]
	v_lshl_add_u64 v[32:33], v[32:33], 0, v[112:113]
	v_cvt_pk_bf16_f32 v23, v18, v19
	v_mov_b32_dpp v26, v16 row_ror:8 row_mask:0xf bank_mask:0xf
	v_cndmask_b32_e64 v16, v29, v21, s[2:3]
	v_mov_b32_e32 v27, 0
	v_cndmask_b32_e64 v17, v24, v22, s[2:3]
	v_mov_b32_e32 v30, 0
	global_store_dwordx4 v[32:33], v[36:39], off
	v_add_u32_e32 v32, 0xa0, v148
	v_mov_b32_dpp v27, v16 row_ror:8 row_mask:0xf bank_mask:0xf
	v_cndmask_b32_e64 v16, v25, v23, s[2:3]
	v_mov_b32_dpp v30, v17 row_ror:8 row_mask:0xf bank_mask:0xf
	v_mov_b32_e32 v31, 0
	v_cndmask_b32_e64 v18, v30, v24, s[2:3]
	v_cndmask_b32_e64 v24, v34, v32, s[2:3]
	v_mov_b32_dpp v31, v16 row_ror:8 row_mask:0xf bank_mask:0xf
	v_cndmask_b32_e64 v19, v31, v25, s[2:3]
	v_ashrrev_i32_e32 v25, 31, v24
	v_lshlrev_b64 v[24:25], 11, v[24:25]
	v_lshl_add_u64 v[24:25], s[40:41], 0, v[24:25]
	v_cndmask_b32_e64 v17, v27, v29, s[2:3]
	v_cndmask_b32_e64 v16, v26, v28, s[2:3]
	v_lshl_add_u64 v[24:25], v[24:25], 0, v[112:113]
	global_store_dwordx4 v[24:25], v[16:19], off
	v_cndmask_b32_e64 v23, v23, v31, s[2:3]
	v_cndmask_b32_e64 v22, v22, v30, s[2:3]
	v_add_u32_e32 v18, 0xa8, v148
	v_cndmask_b32_e64 v16, v32, v18, s[2:3]
	v_ashrrev_i32_e32 v17, 31, v16
	v_lshlrev_b64 v[16:17], 11, v[16:17]
	v_lshl_add_u64 v[16:17], s[40:41], 0, v[16:17]
	v_cndmask_b32_e64 v21, v21, v27, s[2:3]
	v_cndmask_b32_e64 v20, v20, v26, s[2:3]
	v_lshl_add_u64 v[16:17], v[16:17], 0, v[112:113]
	global_store_dwordx4 v[16:17], v[20:23], off
	v_add_u32_e32 v16, 0xb0, v148
	v_cvt_pk_bf16_f32 v12, v12, v13
	v_cvt_pk_bf16_f32 v8, v8, v9
	v_cvt_pk_bf16_f32 v9, v10, v11
	v_cvt_pk_bf16_f32 v10, v4, v5
	v_cvt_pk_bf16_f32 v13, v14, v15
	v_cvt_pk_bf16_f32 v6, v6, v7
	v_cvt_pk_bf16_f32 v7, v0, v1
	v_cndmask_b32_e64 v0, v12, v10, s[2:3]
	v_mov_b32_e32 v14, 0
	v_cndmask_b32_e64 v4, v18, v16, s[2:3]
	v_cvt_pk_bf16_f32 v11, v2, v3
	v_mov_b32_dpp v14, v0 row_ror:8 row_mask:0xf bank_mask:0xf
	v_cndmask_b32_e64 v0, v13, v6, s[2:3]
	v_mov_b32_e32 v15, 0
	v_ashrrev_i32_e32 v5, 31, v4
	v_cndmask_b32_e64 v1, v8, v7, s[2:3]
	v_mov_b32_dpp v15, v0 row_ror:8 row_mask:0xf bank_mask:0xf
	v_cndmask_b32_e64 v0, v9, v11, s[2:3]
	v_mov_b32_e32 v17, 0
	v_mov_b32_e32 v19, 0
	v_lshlrev_b64 v[4:5], 11, v[4:5]
	v_mov_b32_dpp v17, v1 row_ror:8 row_mask:0xf bank_mask:0xf
	v_mov_b32_dpp v19, v0 row_ror:8 row_mask:0xf bank_mask:0xf
	v_lshl_add_u64 v[4:5], s[40:41], 0, v[4:5]
	v_cndmask_b32_e64 v3, v19, v9, s[2:3]
	v_cndmask_b32_e64 v2, v17, v8, s[2:3]
	v_cndmask_b32_e64 v1, v15, v13, s[2:3]
	v_cndmask_b32_e64 v0, v14, v12, s[2:3]
	v_lshl_add_u64 v[4:5], v[4:5], 0, v[112:113]
	global_store_dwordx4 v[4:5], v[0:3], off
	s_and_b64 vcc, exec, s[4:5]
	s_mov_b32 s62, s6
	v_add_u32_e32 v0, 0xb8, v148
	v_cndmask_b32_e64 v0, v16, v0, s[2:3]
	v_ashrrev_i32_e32 v1, 31, v0
	v_lshlrev_b64 v[0:1], 11, v[0:1]
	v_lshl_add_u64 v[0:1], s[40:41], 0, v[0:1]
	v_lshl_add_u64 v[4:5], v[0:1], 0, v[112:113]
	v_cndmask_b32_e64 v3, v11, v19, s[2:3]
	v_cndmask_b32_e64 v2, v7, v17, s[2:3]
	v_cndmask_b32_e64 v1, v6, v15, s[2:3]
	v_cndmask_b32_e64 v0, v10, v14, s[2:3]
	s_mov_b32 s42, s8
	s_mov_b64 s[46:47], s[12:13]
	s_mov_b64 s[44:45], s[10:11]
	global_store_dwordx4 v[4:5], v[0:3], off
	s_cbranch_vccz .LBB0_335
	s_waitcnt vmcnt(0)
	s_cmpk_gt_u32 s17, 0xff
	s_cbranch_scc1 .LBB0_346
	s_barrier

.LBB0_667:
	s_add_u32 s56, s52, s54
	s_addc_u32 s57, s53, s55
	s_add_u32 s56, s56, 0x100
	s_addc_u32 s57, s57, 0
	s_add_u32 vcc_lo, s96, s54
	s_addc_u32 vcc_hi, s97, s55
	s_cmpk_eq_i32 s54, 0x700
	s_cselect_b32 s59, s47, s57
	s_cselect_b32 s58, s94, s56
	s_cselect_b32 s57, s45, vcc_hi
	s_cselect_b32 s56, s95, vcc_lo
	s_add_i32 vcc_lo, 0, 0x10000
	v_add_u32_e32 v1, vcc_lo, v196
	ds_read_b128 v[132:135], v1
	ds_read_b128 v[136:139], v1 offset:1024
	ds_read_b128 v[140:143], v1 offset:2048
	ds_read_b128 v[144:147], v1 offset:3072
	v_lshl_add_u64 v[2:3], v[188:189], 0, s[54:55]
	s_add_i32 m0, s63, 0xc000
	ds_read_b128 v[148:151], v199
	ds_read_b128 v[152:155], v199 offset:1024
	ds_read_b128 v[156:159], v199 offset:2048
	ds_read_b128 v[160:163], v199 offset:3072
	ds_read_b128 v[164:167], v199 offset:4096
	ds_read_b128 v[200:203], v199 offset:5120
	ds_read_b128 v[204:207], v199 offset:6144
	ds_read_b128 v[208:211], v199 offset:7168
	global_load_lds_dwordx4 v[2:3], off
	v_lshl_add_u64 v[2:3], v[190:191], 0, s[54:55]
	s_add_i32 m0, s63, 0xe000
	s_nop 0
	global_load_lds_dwordx4 v[2:3], off
	s_waitcnt lgkmcnt(8)
	s_barrier
	s_waitcnt lgkmcnt(7)
	v_mfma_f32_16x16x32_bf16 v[128:131], v[132:135], v[148:151], v[128:131]
	v_mfma_f32_16x16x32_bf16 v[124:127], v[140:143], v[148:151], v[124:127]
	s_waitcnt lgkmcnt(5)
	v_mfma_f32_16x16x32_bf16 v[112:115], v[132:135], v[156:159], v[112:115]
	v_mfma_f32_16x16x32_bf16 v[108:111], v[140:143], v[156:159], v[108:111]
	s_waitcnt lgkmcnt(3)
	v_mfma_f32_16x16x32_bf16 v[96:99], v[132:135], v[164:167], v[96:99]
	v_mfma_f32_16x16x32_bf16 v[92:95], v[140:143], v[164:167], v[92:95]
	s_waitcnt lgkmcnt(1)
	v_mfma_f32_16x16x32_bf16 v[80:83], v[132:135], v[204:207], v[80:83]
	v_mfma_f32_16x16x32_bf16 v[76:79], v[140:143], v[204:207], v[76:79]
	v_mfma_f32_16x16x32_bf16 v[128:131], v[136:139], v[152:155], v[128:131]
	v_mfma_f32_16x16x32_bf16 v[124:127], v[144:147], v[152:155], v[124:127]
	v_mfma_f32_16x16x32_bf16 v[112:115], v[136:139], v[160:163], v[112:115]
	v_mfma_f32_16x16x32_bf16 v[108:111], v[144:147], v[160:163], v[108:111]
	v_mfma_f32_16x16x32_bf16 v[96:99], v[136:139], v[200:203], v[96:99]
	v_mfma_f32_16x16x32_bf16 v[92:95], v[144:147], v[200:203], v[92:95]
	s_waitcnt lgkmcnt(0)
	v_mfma_f32_16x16x32_bf16 v[80:83], v[136:139], v[208:211], v[80:83]
	v_mfma_f32_16x16x32_bf16 v[76:79], v[144:147], v[208:211], v[76:79]
	s_barrier
	s_add_i32 vcc_lo, vcc_lo, s61
	v_add_u32_e32 v1, s93, v196
	v_lshl_add_u64 v[228:229], s[56:57], 0, v[172:173]
	s_mov_b32 m0, vcc_lo
	ds_read_b128 v[212:215], v1
	ds_read_b128 v[216:219], v1 offset:1024
	ds_read_b128 v[220:223], v1 offset:2048
	ds_read_b128 v[224:227], v1 offset:3072
	global_load_lds_dwordx4 v[228:229], off
	v_lshl_add_u64 v[230:231], s[56:57], 0, v[168:169]
	s_add_i32 m0, vcc_lo, 0x2000
	s_nop 0
	global_load_lds_dwordx4 v[230:231], off
	s_barrier
	s_waitcnt lgkmcnt(3)
	v_mfma_f32_16x16x32_bf16 v[120:123], v[212:215], v[148:151], v[120:123]
	s_waitcnt lgkmcnt(1)
	v_mfma_f32_16x16x32_bf16 v[116:119], v[220:223], v[148:151], v[116:119]
	v_mfma_f32_16x16x32_bf16 v[104:107], v[212:215], v[156:159], v[104:107]
	v_mfma_f32_16x16x32_bf16 v[100:103], v[220:223], v[156:159], v[100:103]
	v_mfma_f32_16x16x32_bf16 v[88:91], v[212:215], v[164:167], v[88:91]
	v_mfma_f32_16x16x32_bf16 v[84:87], v[220:223], v[164:167], v[84:87]
	v_mfma_f32_16x16x32_bf16 v[72:75], v[212:215], v[204:207], v[72:75]
	v_mfma_f32_16x16x32_bf16 v[68:71], v[220:223], v[204:207], v[68:71]
	v_mfma_f32_16x16x32_bf16 v[120:123], v[216:219], v[152:155], v[120:123]
	s_waitcnt lgkmcnt(0)
	v_mfma_f32_16x16x32_bf16 v[116:119], v[224:227], v[152:155], v[116:119]
	v_mfma_f32_16x16x32_bf16 v[104:107], v[216:219], v[160:163], v[104:107]
	v_mfma_f32_16x16x32_bf16 v[100:103], v[224:227], v[160:163], v[100:103]
	v_mfma_f32_16x16x32_bf16 v[88:91], v[216:219], v[200:203], v[88:91]
	v_mfma_f32_16x16x32_bf16 v[84:87], v[224:227], v[200:203], v[84:87]
	v_mfma_f32_16x16x32_bf16 v[72:75], v[216:219], v[208:211], v[72:75]
	v_mfma_f32_16x16x32_bf16 v[68:71], v[224:227], v[208:211], v[68:71]
	s_mov_b32 m0, s63
	v_lshl_add_u64 v[232:233], s[58:59], 0, v[174:175]
	s_barrier
	ds_read_b128 v[148:151], v199 offset:16384
	ds_read_b128 v[152:155], v199 offset:17408
	ds_read_b128 v[156:159], v199 offset:18432
	ds_read_b128 v[160:163], v199 offset:19456
	ds_read_b128 v[164:167], v199 offset:20480
	ds_read_b128 v[200:203], v199 offset:21504
	ds_read_b128 v[204:207], v199 offset:22528
	ds_read_b128 v[208:211], v199 offset:23552
	global_load_lds_dwordx4 v[232:233], off
	v_lshl_add_u64 v[234:235], s[58:59], 0, v[170:171]
	s_mov_b32 m0, s64
	s_nop 0
	global_load_lds_dwordx4 v[234:235], off
	s_barrier
	s_waitcnt lgkmcnt(7)
	v_mfma_f32_16x16x32_bf16 v[64:67], v[132:135], v[148:151], v[64:67]
	v_mfma_f32_16x16x32_bf16 v[60:63], v[140:143], v[148:151], v[60:63]
	s_waitcnt lgkmcnt(5)
	v_mfma_f32_16x16x32_bf16 v[48:51], v[132:135], v[156:159], v[48:51]
	v_mfma_f32_16x16x32_bf16 v[44:47], v[140:143], v[156:159], v[44:47]
	s_waitcnt lgkmcnt(3)
	v_mfma_f32_16x16x32_bf16 v[32:35], v[132:135], v[164:167], v[32:35]
	v_mfma_f32_16x16x32_bf16 v[28:31], v[140:143], v[164:167], v[28:31]
	s_waitcnt lgkmcnt(1)
	v_mfma_f32_16x16x32_bf16 v[16:19], v[132:135], v[204:207], v[16:19]
	v_mfma_f32_16x16x32_bf16 v[12:15], v[140:143], v[204:207], v[12:15]
	v_mfma_f32_16x16x32_bf16 v[64:67], v[136:139], v[152:155], v[64:67]
	v_mfma_f32_16x16x32_bf16 v[60:63], v[144:147], v[152:155], v[60:63]
	v_mfma_f32_16x16x32_bf16 v[48:51], v[136:139], v[160:163], v[48:51]
	v_mfma_f32_16x16x32_bf16 v[44:47], v[144:147], v[160:163], v[44:47]
	v_mfma_f32_16x16x32_bf16 v[32:35], v[136:139], v[200:203], v[32:35]
	v_mfma_f32_16x16x32_bf16 v[28:31], v[144:147], v[200:203], v[28:31]
	s_waitcnt lgkmcnt(0)
	v_mfma_f32_16x16x32_bf16 v[16:19], v[136:139], v[208:211], v[16:19]
	v_mfma_f32_16x16x32_bf16 v[12:15], v[144:147], v[208:211], v[12:15]
	s_barrier
	s_add_u32 vcc_lo, s56, 0x10000
	s_addc_u32 vcc_hi, s57, 0
	s_add_i32 s28, s93, s61
	v_lshl_add_u64 v[2:3], vcc, 0, v[172:173]
	s_mov_b32 m0, s28
	s_nop 0
	global_load_lds_dwordx4 v[2:3], off
	v_lshl_add_u64 v[2:3], vcc, 0, v[168:169]
	s_add_i32 m0, s28, 0x2000
	s_nop 0
	global_load_lds_dwordx4 v[2:3], off
	s_waitcnt vmcnt(6)
	s_barrier
	v_mfma_f32_16x16x32_bf16 v[56:59], v[212:215], v[148:151], v[56:59]
	v_mfma_f32_16x16x32_bf16 v[52:55], v[220:223], v[148:151], v[52:55]
	v_mfma_f32_16x16x32_bf16 v[40:43], v[212:215], v[156:159], v[40:43]
	v_mfma_f32_16x16x32_bf16 v[36:39], v[220:223], v[156:159], v[36:39]
	v_mfma_f32_16x16x32_bf16 v[24:27], v[212:215], v[164:167], v[24:27]
	v_mfma_f32_16x16x32_bf16 v[20:23], v[220:223], v[164:167], v[20:23]
	v_mfma_f32_16x16x32_bf16 v[8:11], v[212:215], v[204:207], v[8:11]
	v_mfma_f32_16x16x32_bf16 v[2:5], v[220:223], v[204:207], v[4:7]
	v_mfma_f32_16x16x32_bf16 v[56:59], v[216:219], v[152:155], v[56:59]
	v_mfma_f32_16x16x32_bf16 v[52:55], v[224:227], v[152:155], v[52:55]
	v_mfma_f32_16x16x32_bf16 v[40:43], v[216:219], v[160:163], v[40:43]
	v_mfma_f32_16x16x32_bf16 v[36:39], v[224:227], v[160:163], v[36:39]
	v_mfma_f32_16x16x32_bf16 v[24:27], v[216:219], v[200:203], v[24:27]
	v_mfma_f32_16x16x32_bf16 v[20:23], v[224:227], v[200:203], v[20:23]
	v_mfma_f32_16x16x32_bf16 v[8:11], v[216:219], v[208:211], v[8:11]
	v_mfma_f32_16x16x32_bf16 v[2:5], v[224:227], v[208:211], v[2:5]
	s_add_i32 s28, 0, 0x18000
	v_add_u32_e32 v1, s28, v196
	s_barrier
	ds_read_b128 v[132:135], v1
	ds_read_b128 v[136:139], v1 offset:1024
	ds_read_b128 v[140:143], v1 offset:2048
	ds_read_b128 v[144:147], v1 offset:3072
	s_add_u32 s58, s58, 0x40000
	s_addc_u32 s59, s59, 0
	s_mov_b32 m0, s65
	v_lshl_add_u64 v[6:7], s[58:59], 0, v[174:175]
	ds_read_b128 v[148:151], v199 offset:32768
	ds_read_b128 v[152:155], v199 offset:33792
	ds_read_b128 v[156:159], v199 offset:34816
	ds_read_b128 v[160:163], v199 offset:35840
	ds_read_b128 v[164:167], v199 offset:36864
	ds_read_b128 v[200:203], v199 offset:37888
	ds_read_b128 v[204:207], v199 offset:38912
	ds_read_b128 v[208:211], v199 offset:39936
	global_load_lds_dwordx4 v[6:7], off
	v_lshl_add_u64 v[6:7], s[58:59], 0, v[170:171]
	s_mov_b32 m0, s66
	s_nop 0
	global_load_lds_dwordx4 v[6:7], off
	s_waitcnt lgkmcnt(8)
	s_barrier
	s_waitcnt lgkmcnt(7)
	v_mfma_f32_16x16x32_bf16 v[128:131], v[132:135], v[148:151], v[128:131]
	v_mfma_f32_16x16x32_bf16 v[124:127], v[140:143], v[148:151], v[124:127]
	s_waitcnt lgkmcnt(5)
	v_mfma_f32_16x16x32_bf16 v[112:115], v[132:135], v[156:159], v[112:115]
	v_mfma_f32_16x16x32_bf16 v[108:111], v[140:143], v[156:159], v[108:111]
	s_waitcnt lgkmcnt(3)
	v_mfma_f32_16x16x32_bf16 v[96:99], v[132:135], v[164:167], v[96:99]
	v_mfma_f32_16x16x32_bf16 v[92:95], v[140:143], v[164:167], v[92:95]
	s_waitcnt lgkmcnt(1)
	v_mfma_f32_16x16x32_bf16 v[80:83], v[132:135], v[204:207], v[80:83]
	v_mfma_f32_16x16x32_bf16 v[76:79], v[140:143], v[204:207], v[76:79]
	v_mfma_f32_16x16x32_bf16 v[128:131], v[136:139], v[152:155], v[128:131]
	v_mfma_f32_16x16x32_bf16 v[124:127], v[144:147], v[152:155], v[124:127]
	v_mfma_f32_16x16x32_bf16 v[112:115], v[136:139], v[160:163], v[112:115]
	v_mfma_f32_16x16x32_bf16 v[108:111], v[144:147], v[160:163], v[108:111]
	v_mfma_f32_16x16x32_bf16 v[96:99], v[136:139], v[200:203], v[96:99]
	v_mfma_f32_16x16x32_bf16 v[92:95], v[144:147], v[200:203], v[92:95]
	s_waitcnt lgkmcnt(0)
	v_mfma_f32_16x16x32_bf16 v[80:83], v[136:139], v[208:211], v[80:83]
	v_mfma_f32_16x16x32_bf16 v[76:79], v[144:147], v[208:211], v[76:79]
	s_barrier
	s_add_i32 s29, 0, 0x1c000
	s_add_i32 s28, s28, s61
	v_add_u32_e32 v1, s29, v196
	v_lshl_add_u64 v[6:7], v[228:229], 0, s[0:1]
	s_mov_b32 m0, s28
	ds_read_b128 v[212:215], v1
	ds_read_b128 v[216:219], v1 offset:1024
	ds_read_b128 v[220:223], v1 offset:2048
	ds_read_b128 v[224:227], v1 offset:3072
	global_load_lds_dwordx4 v[6:7], off
	v_lshl_add_u64 v[6:7], v[230:231], 0, s[0:1]
	s_add_i32 m0, s28, 0x2000
	s_nop 0
	global_load_lds_dwordx4 v[6:7], off
	s_barrier
	s_waitcnt lgkmcnt(3)
	v_mfma_f32_16x16x32_bf16 v[120:123], v[212:215], v[148:151], v[120:123]
	s_waitcnt lgkmcnt(1)
	v_mfma_f32_16x16x32_bf16 v[116:119], v[220:223], v[148:151], v[116:119]
	v_mfma_f32_16x16x32_bf16 v[104:107], v[212:215], v[156:159], v[104:107]
	v_mfma_f32_16x16x32_bf16 v[100:103], v[220:223], v[156:159], v[100:103]
	v_mfma_f32_16x16x32_bf16 v[88:91], v[212:215], v[164:167], v[88:91]
	v_mfma_f32_16x16x32_bf16 v[84:87], v[220:223], v[164:167], v[84:87]
	v_mfma_f32_16x16x32_bf16 v[72:75], v[212:215], v[204:207], v[72:75]
	v_mfma_f32_16x16x32_bf16 v[68:71], v[220:223], v[204:207], v[68:71]
	v_mfma_f32_16x16x32_bf16 v[120:123], v[216:219], v[152:155], v[120:123]
	s_waitcnt lgkmcnt(0)
	v_mfma_f32_16x16x32_bf16 v[116:119], v[224:227], v[152:155], v[116:119]
	v_mfma_f32_16x16x32_bf16 v[104:107], v[216:219], v[160:163], v[104:107]
	v_mfma_f32_16x16x32_bf16 v[100:103], v[224:227], v[160:163], v[100:103]
	v_mfma_f32_16x16x32_bf16 v[88:91], v[216:219], v[200:203], v[88:91]
	v_mfma_f32_16x16x32_bf16 v[84:87], v[224:227], v[200:203], v[84:87]
	v_mfma_f32_16x16x32_bf16 v[72:75], v[216:219], v[208:211], v[72:75]
	v_mfma_f32_16x16x32_bf16 v[68:71], v[224:227], v[208:211], v[68:71]
	s_mov_b32 m0, s81
	v_lshl_add_u64 v[6:7], v[232:233], 0, s[0:1]
	s_barrier
	ds_read_b128 v[148:151], v199 offset:49152
	ds_read_b128 v[152:155], v199 offset:50176
	ds_read_b128 v[156:159], v199 offset:51200
	ds_read_b128 v[160:163], v199 offset:52224
	ds_read_b128 v[164:167], v199 offset:53248
	ds_read_b128 v[200:203], v199 offset:54272
	ds_read_b128 v[204:207], v199 offset:55296
	ds_read_b128 v[208:211], v199 offset:56320
	global_load_lds_dwordx4 v[6:7], off
	v_lshl_add_u64 v[6:7], v[234:235], 0, s[0:1]
	s_mov_b32 m0, s82
	s_nop 0
	global_load_lds_dwordx4 v[6:7], off
	s_barrier
	s_waitcnt lgkmcnt(7)
	v_mfma_f32_16x16x32_bf16 v[64:67], v[132:135], v[148:151], v[64:67]
	v_mfma_f32_16x16x32_bf16 v[60:63], v[140:143], v[148:151], v[60:63]
	s_waitcnt lgkmcnt(5)
	v_mfma_f32_16x16x32_bf16 v[48:51], v[132:135], v[156:159], v[48:51]
	v_mfma_f32_16x16x32_bf16 v[44:47], v[140:143], v[156:159], v[44:47]
	s_waitcnt lgkmcnt(3)
	v_mfma_f32_16x16x32_bf16 v[32:35], v[132:135], v[164:167], v[32:35]
	v_mfma_f32_16x16x32_bf16 v[28:31], v[140:143], v[164:167], v[28:31]
	s_waitcnt lgkmcnt(1)
	v_mfma_f32_16x16x32_bf16 v[16:19], v[132:135], v[204:207], v[16:19]
	v_mfma_f32_16x16x32_bf16 v[12:15], v[140:143], v[204:207], v[12:15]
	v_mfma_f32_16x16x32_bf16 v[64:67], v[136:139], v[152:155], v[64:67]
	v_mfma_f32_16x16x32_bf16 v[60:63], v[144:147], v[152:155], v[60:63]
	v_mfma_f32_16x16x32_bf16 v[48:51], v[136:139], v[160:163], v[48:51]
	v_mfma_f32_16x16x32_bf16 v[44:47], v[144:147], v[160:163], v[44:47]
	v_mfma_f32_16x16x32_bf16 v[32:35], v[136:139], v[200:203], v[32:35]
	v_mfma_f32_16x16x32_bf16 v[28:31], v[144:147], v[200:203], v[28:31]
	s_waitcnt lgkmcnt(0)
	v_mfma_f32_16x16x32_bf16 v[16:19], v[136:139], v[208:211], v[16:19]
	v_mfma_f32_16x16x32_bf16 v[12:15], v[144:147], v[208:211], v[12:15]
	s_barrier
	s_add_u32 s56, s56, 0x10080
	s_addc_u32 s57, s57, 0
	s_add_i32 s28, s29, s61
	v_lshl_add_u64 v[6:7], s[56:57], 0, v[172:173]
	s_mov_b32 m0, s28
	s_nop 0
	global_load_lds_dwordx4 v[6:7], off
	v_lshl_add_u64 v[6:7], s[56:57], 0, v[168:169]
	s_add_i32 m0, s28, 0x2000
	s_nop 0
	global_load_lds_dwordx4 v[6:7], off
	s_waitcnt vmcnt(6)
	s_barrier
	v_mfma_f32_16x16x32_bf16 v[56:59], v[212:215], v[148:151], v[56:59]
	v_mfma_f32_16x16x32_bf16 v[52:55], v[220:223], v[148:151], v[52:55]
	v_mfma_f32_16x16x32_bf16 v[40:43], v[212:215], v[156:159], v[40:43]
	v_mfma_f32_16x16x32_bf16 v[36:39], v[220:223], v[156:159], v[36:39]
	v_mfma_f32_16x16x32_bf16 v[24:27], v[212:215], v[164:167], v[24:27]
	v_mfma_f32_16x16x32_bf16 v[20:23], v[220:223], v[164:167], v[20:23]
	v_mfma_f32_16x16x32_bf16 v[6:9], v[212:215], v[204:207], v[8:11]
	v_mfma_f32_16x16x32_bf16 v[2:5], v[220:223], v[204:207], v[2:5]
	v_mfma_f32_16x16x32_bf16 v[56:59], v[216:219], v[152:155], v[56:59]
	v_mfma_f32_16x16x32_bf16 v[52:55], v[224:227], v[152:155], v[52:55]
	v_mfma_f32_16x16x32_bf16 v[40:43], v[216:219], v[160:163], v[40:43]
	v_mfma_f32_16x16x32_bf16 v[36:39], v[224:227], v[160:163], v[36:39]
	v_mfma_f32_16x16x32_bf16 v[24:27], v[216:219], v[200:203], v[24:27]
	v_mfma_f32_16x16x32_bf16 v[20:23], v[224:227], v[200:203], v[20:23]
	v_mfma_f32_16x16x32_bf16 v[8:11], v[216:219], v[208:211], v[6:9]
	v_mfma_f32_16x16x32_bf16 v[4:7], v[224:227], v[208:211], v[2:5]
	s_add_i32 s17, s17, 2
	s_add_u32 s54, s54, 0x100
	s_addc_u32 s55, s55, 0
	s_cmp_gt_u32 s17, 13
	s_barrier
	s_cbranch_scc1 .LBB0_659

.LBB0_740:
	ds_read_b128 v[64:67], v221
	ds_read_b128 v[68:71], v221 offset:1024
	ds_read_b128 v[84:87], v221 offset:2048
	ds_read_b128 v[92:95], v221 offset:3072
	s_add_u32 s28, s10, 0xfffc0080
	s_addc_u32 s29, s11, -1
	s_cmp_eq_u32 s92, 12
	s_cselect_b32 s65, s9, s29
	s_cselect_b32 s64, s13, s28
	s_cselect_b32 s63, s17, s57
	s_cselect_b32 s62, s44, s55
	v_lshl_add_u64 v[176:177], s[10:11], 0, v[204:205]
	s_add_i32 m0, s78, 0xc000
	ds_read_b128 v[144:147], v222
	ds_read_b128 v[148:151], v222 offset:1024
	ds_read_b128 v[152:155], v222 offset:2048
	ds_read_b128 v[156:159], v222 offset:3072
	ds_read_b128 v[160:163], v222 offset:4096
	ds_read_b128 v[164:167], v222 offset:5120
	ds_read_b128 v[168:171], v222 offset:6144
	ds_read_b128 v[172:175], v222 offset:7168
	global_load_lds_dwordx4 v[176:177], off
	v_lshl_add_u64 v[176:177], s[10:11], 0, v[206:207]
	s_add_i32 m0, s78, 0xe000
	s_nop 0
	global_load_lds_dwordx4 v[176:177], off
	s_waitcnt lgkmcnt(8)
	s_barrier
	s_waitcnt lgkmcnt(7)
	v_mfma_f32_16x16x32_bf16 v[140:143], v[64:67], v[144:147], v[140:143]
	v_mfma_f32_16x16x32_bf16 v[136:139], v[84:87], v[144:147], v[136:139]
	s_waitcnt lgkmcnt(5)
	v_mfma_f32_16x16x32_bf16 v[124:127], v[64:67], v[152:155], v[124:127]
	v_mfma_f32_16x16x32_bf16 v[120:123], v[84:87], v[152:155], v[120:123]
	s_waitcnt lgkmcnt(3)
	v_mfma_f32_16x16x32_bf16 v[108:111], v[64:67], v[160:163], v[108:111]
	v_mfma_f32_16x16x32_bf16 v[104:107], v[84:87], v[160:163], v[104:107]
	s_waitcnt lgkmcnt(1)
	v_mfma_f32_16x16x32_bf16 v[88:91], v[64:67], v[168:171], v[88:91]
	v_mfma_f32_16x16x32_bf16 v[80:83], v[84:87], v[168:171], v[80:83]
	v_mfma_f32_16x16x32_bf16 v[140:143], v[68:71], v[148:151], v[140:143]
	v_mfma_f32_16x16x32_bf16 v[136:139], v[92:95], v[148:151], v[136:139]
	v_mfma_f32_16x16x32_bf16 v[124:127], v[68:71], v[156:159], v[124:127]
	v_mfma_f32_16x16x32_bf16 v[120:123], v[92:95], v[156:159], v[120:123]
	v_mfma_f32_16x16x32_bf16 v[108:111], v[68:71], v[164:167], v[108:111]
	v_mfma_f32_16x16x32_bf16 v[104:107], v[92:95], v[164:167], v[104:107]
	s_waitcnt lgkmcnt(0)
	v_mfma_f32_16x16x32_bf16 v[88:91], v[68:71], v[172:175], v[88:91]
	v_mfma_f32_16x16x32_bf16 v[80:83], v[92:95], v[172:175], v[80:83]
	s_barrier
	s_add_i32 s28, s89, s67
	v_lshl_add_u64 v[212:213], s[62:63], 0, v[198:199]
	s_mov_b32 m0, s28
	ds_read_b128 v[176:179], v223
	ds_read_b128 v[180:183], v223 offset:1024
	ds_read_b128 v[184:187], v223 offset:2048
	ds_read_b128 v[188:191], v223 offset:3072
	global_load_lds_dwordx4 v[212:213], off
	v_lshl_add_u64 v[214:215], s[62:63], 0, v[202:203]
	s_add_i32 m0, s28, 0x2000
	s_nop 0
	global_load_lds_dwordx4 v[214:215], off
	s_barrier
	s_waitcnt lgkmcnt(3)
	v_mfma_f32_16x16x32_bf16 v[132:135], v[176:179], v[144:147], v[132:135]
	s_waitcnt lgkmcnt(1)
	v_mfma_f32_16x16x32_bf16 v[128:131], v[184:187], v[144:147], v[128:131]
	v_mfma_f32_16x16x32_bf16 v[116:119], v[176:179], v[152:155], v[116:119]
	v_mfma_f32_16x16x32_bf16 v[112:115], v[184:187], v[152:155], v[112:115]
	v_mfma_f32_16x16x32_bf16 v[100:103], v[176:179], v[160:163], v[100:103]
	v_mfma_f32_16x16x32_bf16 v[96:99], v[184:187], v[160:163], v[96:99]
	v_mfma_f32_16x16x32_bf16 v[76:79], v[176:179], v[168:171], v[76:79]
	v_mfma_f32_16x16x32_bf16 v[72:75], v[184:187], v[168:171], v[72:75]
	v_mfma_f32_16x16x32_bf16 v[132:135], v[180:183], v[148:151], v[132:135]
	s_waitcnt lgkmcnt(0)
	v_mfma_f32_16x16x32_bf16 v[128:131], v[188:191], v[148:151], v[128:131]
	v_mfma_f32_16x16x32_bf16 v[116:119], v[180:183], v[156:159], v[116:119]
	v_mfma_f32_16x16x32_bf16 v[112:115], v[188:191], v[156:159], v[112:115]
	v_mfma_f32_16x16x32_bf16 v[100:103], v[180:183], v[164:167], v[100:103]
	v_mfma_f32_16x16x32_bf16 v[96:99], v[188:191], v[164:167], v[96:99]
	v_mfma_f32_16x16x32_bf16 v[76:79], v[180:183], v[172:175], v[76:79]
	v_mfma_f32_16x16x32_bf16 v[72:75], v[188:191], v[172:175], v[72:75]
	s_mov_b32 m0, s78
	v_lshl_add_u64 v[216:217], s[64:65], 0, v[196:197]
	s_barrier
	ds_read_b128 v[144:147], v222 offset:16384
	ds_read_b128 v[148:151], v222 offset:17408
	ds_read_b128 v[152:155], v222 offset:18432
	ds_read_b128 v[156:159], v222 offset:19456
	ds_read_b128 v[160:163], v222 offset:20480
	ds_read_b128 v[164:167], v222 offset:21504
	ds_read_b128 v[168:171], v222 offset:22528
	ds_read_b128 v[172:175], v222 offset:23552
	global_load_lds_dwordx4 v[216:217], off
	v_lshl_add_u64 v[226:227], s[64:65], 0, v[200:201]
	s_mov_b32 m0, s79
	s_nop 0
	global_load_lds_dwordx4 v[226:227], off
	s_barrier
	s_waitcnt lgkmcnt(7)
	v_mfma_f32_16x16x32_bf16 v[60:63], v[64:67], v[144:147], v[60:63]
	v_mfma_f32_16x16x32_bf16 v[56:59], v[84:87], v[144:147], v[56:59]
	s_waitcnt lgkmcnt(5)
	v_mfma_f32_16x16x32_bf16 v[44:47], v[64:67], v[152:155], v[44:47]
	v_mfma_f32_16x16x32_bf16 v[40:43], v[84:87], v[152:155], v[40:43]
	s_waitcnt lgkmcnt(3)
	v_mfma_f32_16x16x32_bf16 v[28:31], v[64:67], v[160:163], v[28:31]
	v_mfma_f32_16x16x32_bf16 v[24:27], v[84:87], v[160:163], v[24:27]
	s_waitcnt lgkmcnt(1)
	v_mfma_f32_16x16x32_bf16 v[12:15], v[64:67], v[168:171], v[12:15]
	v_mfma_f32_16x16x32_bf16 v[8:11], v[84:87], v[168:171], v[8:11]
	v_mfma_f32_16x16x32_bf16 v[60:63], v[68:71], v[148:151], v[60:63]
	v_mfma_f32_16x16x32_bf16 v[56:59], v[92:95], v[148:151], v[56:59]
	v_mfma_f32_16x16x32_bf16 v[44:47], v[68:71], v[156:159], v[44:47]
	v_mfma_f32_16x16x32_bf16 v[40:43], v[92:95], v[156:159], v[40:43]
	v_mfma_f32_16x16x32_bf16 v[28:31], v[68:71], v[164:167], v[28:31]
	v_mfma_f32_16x16x32_bf16 v[24:27], v[92:95], v[164:167], v[24:27]
	s_waitcnt lgkmcnt(0)
	v_mfma_f32_16x16x32_bf16 v[12:15], v[68:71], v[172:175], v[12:15]
	v_mfma_f32_16x16x32_bf16 v[8:11], v[92:95], v[172:175], v[8:11]
	s_barrier
	s_add_u32 s94, s62, 0x10000
	s_addc_u32 s95, s63, 0
	s_add_i32 s28, s90, s67
	v_lshl_add_u64 v[64:65], s[94:95], 0, v[198:199]
	s_mov_b32 m0, s28
	s_nop 0
	global_load_lds_dwordx4 v[64:65], off
	v_lshl_add_u64 v[64:65], s[94:95], 0, v[202:203]
	s_add_i32 m0, s28, 0x2000
	s_nop 0
	global_load_lds_dwordx4 v[64:65], off
	s_waitcnt vmcnt(6)
	s_barrier
	v_mfma_f32_16x16x32_bf16 v[52:55], v[176:179], v[144:147], v[52:55]
	v_mfma_f32_16x16x32_bf16 v[48:51], v[184:187], v[144:147], v[48:51]
	v_mfma_f32_16x16x32_bf16 v[36:39], v[176:179], v[152:155], v[36:39]
	v_mfma_f32_16x16x32_bf16 v[32:35], v[184:187], v[152:155], v[32:35]
	v_mfma_f32_16x16x32_bf16 v[20:23], v[176:179], v[160:163], v[20:23]
	v_mfma_f32_16x16x32_bf16 v[16:19], v[184:187], v[160:163], v[16:19]
	v_mfma_f32_16x16x32_bf16 v[4:7], v[176:179], v[168:171], v[4:7]
	v_mfma_f32_16x16x32_bf16 v[0:3], v[184:187], v[168:171], v[0:3]
	v_mfma_f32_16x16x32_bf16 v[52:55], v[180:183], v[148:151], v[52:55]
	v_mfma_f32_16x16x32_bf16 v[48:51], v[188:191], v[148:151], v[48:51]
	v_mfma_f32_16x16x32_bf16 v[36:39], v[180:183], v[156:159], v[36:39]
	v_mfma_f32_16x16x32_bf16 v[32:35], v[188:191], v[156:159], v[32:35]
	v_mfma_f32_16x16x32_bf16 v[20:23], v[180:183], v[164:167], v[20:23]
	v_mfma_f32_16x16x32_bf16 v[16:19], v[188:191], v[164:167], v[16:19]
	v_mfma_f32_16x16x32_bf16 v[4:7], v[180:183], v[172:175], v[4:7]
	v_mfma_f32_16x16x32_bf16 v[0:3], v[188:191], v[172:175], v[0:3]
	s_add_i32 s28, 0, 0x18000
	v_add_u32_e32 v92, s28, v218
	s_barrier
	ds_read_b128 v[64:67], v92
	ds_read_b128 v[68:71], v92 offset:1024
	ds_read_b128 v[84:87], v92 offset:2048
	ds_read_b128 v[92:95], v92 offset:3072
	s_add_u32 s64, s64, 0x40000
	s_addc_u32 s65, s65, 0
	s_mov_b32 m0, s80
	v_lshl_add_u64 v[176:177], s[64:65], 0, v[196:197]
	ds_read_b128 v[144:147], v222 offset:32768
	ds_read_b128 v[148:151], v222 offset:33792
	ds_read_b128 v[152:155], v222 offset:34816
	ds_read_b128 v[156:159], v222 offset:35840
	ds_read_b128 v[160:163], v222 offset:36864
	ds_read_b128 v[164:167], v222 offset:37888
	ds_read_b128 v[168:171], v222 offset:38912
	ds_read_b128 v[172:175], v222 offset:39936
	global_load_lds_dwordx4 v[176:177], off
	v_lshl_add_u64 v[176:177], s[64:65], 0, v[200:201]
	s_mov_b32 m0, s81
	s_nop 0
	global_load_lds_dwordx4 v[176:177], off
	s_waitcnt lgkmcnt(8)
	s_barrier
	s_waitcnt lgkmcnt(7)
	v_mfma_f32_16x16x32_bf16 v[140:143], v[64:67], v[144:147], v[140:143]
	v_mfma_f32_16x16x32_bf16 v[136:139], v[84:87], v[144:147], v[136:139]
	s_waitcnt lgkmcnt(5)
	v_mfma_f32_16x16x32_bf16 v[124:127], v[64:67], v[152:155], v[124:127]
	v_mfma_f32_16x16x32_bf16 v[120:123], v[84:87], v[152:155], v[120:123]
	s_waitcnt lgkmcnt(3)
	v_mfma_f32_16x16x32_bf16 v[108:111], v[64:67], v[160:163], v[108:111]
	v_mfma_f32_16x16x32_bf16 v[104:107], v[84:87], v[160:163], v[104:107]
	s_waitcnt lgkmcnt(1)
	v_mfma_f32_16x16x32_bf16 v[88:91], v[64:67], v[168:171], v[88:91]
	v_mfma_f32_16x16x32_bf16 v[80:83], v[84:87], v[168:171], v[80:83]
	v_mfma_f32_16x16x32_bf16 v[140:143], v[68:71], v[148:151], v[140:143]
	v_mfma_f32_16x16x32_bf16 v[136:139], v[92:95], v[148:151], v[136:139]
	v_mfma_f32_16x16x32_bf16 v[124:127], v[68:71], v[156:159], v[124:127]
	v_mfma_f32_16x16x32_bf16 v[120:123], v[92:95], v[156:159], v[120:123]
	v_mfma_f32_16x16x32_bf16 v[108:111], v[68:71], v[164:167], v[108:111]
	v_mfma_f32_16x16x32_bf16 v[104:107], v[92:95], v[164:167], v[104:107]
	s_waitcnt lgkmcnt(0)
	v_mfma_f32_16x16x32_bf16 v[88:91], v[68:71], v[172:175], v[88:91]
	v_mfma_f32_16x16x32_bf16 v[80:83], v[92:95], v[172:175], v[80:83]
	s_barrier
	s_add_i32 s29, 0, 0x1c000
	s_add_i32 s28, s28, s67
	v_add_u32_e32 v188, s29, v218
	v_lshl_add_u64 v[212:213], v[212:213], 0, s[52:53]
	s_mov_b32 m0, s28
	ds_read_b128 v[176:179], v188
	ds_read_b128 v[180:183], v188 offset:1024
	ds_read_b128 v[184:187], v188 offset:2048
	ds_read_b128 v[188:191], v188 offset:3072
	global_load_lds_dwordx4 v[212:213], off
	v_lshl_add_u64 v[212:213], v[214:215], 0, s[52:53]
	s_add_i32 m0, s28, 0x2000
	s_nop 0
	global_load_lds_dwordx4 v[212:213], off
	s_barrier
	s_waitcnt lgkmcnt(3)
	v_mfma_f32_16x16x32_bf16 v[132:135], v[176:179], v[144:147], v[132:135]
	s_waitcnt lgkmcnt(1)
	v_mfma_f32_16x16x32_bf16 v[128:131], v[184:187], v[144:147], v[128:131]
	v_mfma_f32_16x16x32_bf16 v[116:119], v[176:179], v[152:155], v[116:119]
	v_mfma_f32_16x16x32_bf16 v[112:115], v[184:187], v[152:155], v[112:115]
	v_mfma_f32_16x16x32_bf16 v[100:103], v[176:179], v[160:163], v[100:103]
	v_mfma_f32_16x16x32_bf16 v[96:99], v[184:187], v[160:163], v[96:99]
	v_mfma_f32_16x16x32_bf16 v[76:79], v[176:179], v[168:171], v[76:79]
	v_mfma_f32_16x16x32_bf16 v[72:75], v[184:187], v[168:171], v[72:75]
	v_mfma_f32_16x16x32_bf16 v[132:135], v[180:183], v[148:151], v[132:135]
	s_waitcnt lgkmcnt(0)
	v_mfma_f32_16x16x32_bf16 v[128:131], v[188:191], v[148:151], v[128:131]
	v_mfma_f32_16x16x32_bf16 v[116:119], v[180:183], v[156:159], v[116:119]
	v_mfma_f32_16x16x32_bf16 v[112:115], v[188:191], v[156:159], v[112:115]
	v_mfma_f32_16x16x32_bf16 v[100:103], v[180:183], v[164:167], v[100:103]
	v_mfma_f32_16x16x32_bf16 v[96:99], v[188:191], v[164:167], v[96:99]
	v_mfma_f32_16x16x32_bf16 v[76:79], v[180:183], v[172:175], v[76:79]
	v_mfma_f32_16x16x32_bf16 v[72:75], v[188:191], v[172:175], v[72:75]
	s_mov_b32 m0, s85
	v_lshl_add_u64 v[212:213], v[216:217], 0, s[52:53]
	s_barrier
	ds_read_b128 v[144:147], v222 offset:49152
	ds_read_b128 v[148:151], v222 offset:50176
	ds_read_b128 v[152:155], v222 offset:51200
	ds_read_b128 v[156:159], v222 offset:52224
	ds_read_b128 v[160:163], v222 offset:53248
	ds_read_b128 v[164:167], v222 offset:54272
	ds_read_b128 v[168:171], v222 offset:55296
	ds_read_b128 v[172:175], v222 offset:56320
	global_load_lds_dwordx4 v[212:213], off
	v_lshl_add_u64 v[212:213], v[226:227], 0, s[52:53]
	s_mov_b32 m0, s87
	s_nop 0
	global_load_lds_dwordx4 v[212:213], off
	s_barrier
	s_waitcnt lgkmcnt(7)
	v_mfma_f32_16x16x32_bf16 v[60:63], v[64:67], v[144:147], v[60:63]
	v_mfma_f32_16x16x32_bf16 v[56:59], v[84:87], v[144:147], v[56:59]
	s_waitcnt lgkmcnt(5)
	v_mfma_f32_16x16x32_bf16 v[44:47], v[64:67], v[152:155], v[44:47]
	v_mfma_f32_16x16x32_bf16 v[40:43], v[84:87], v[152:155], v[40:43]
	s_waitcnt lgkmcnt(3)
	v_mfma_f32_16x16x32_bf16 v[28:31], v[64:67], v[160:163], v[28:31]
	v_mfma_f32_16x16x32_bf16 v[24:27], v[84:87], v[160:163], v[24:27]
	s_waitcnt lgkmcnt(1)
	v_mfma_f32_16x16x32_bf16 v[12:15], v[64:67], v[168:171], v[12:15]
	v_mfma_f32_16x16x32_bf16 v[8:11], v[84:87], v[168:171], v[8:11]
	v_mfma_f32_16x16x32_bf16 v[60:63], v[68:71], v[148:151], v[60:63]
	v_mfma_f32_16x16x32_bf16 v[56:59], v[92:95], v[148:151], v[56:59]
	v_mfma_f32_16x16x32_bf16 v[44:47], v[68:71], v[156:159], v[44:47]
	v_mfma_f32_16x16x32_bf16 v[40:43], v[92:95], v[156:159], v[40:43]
	v_mfma_f32_16x16x32_bf16 v[28:31], v[68:71], v[164:167], v[28:31]
	v_mfma_f32_16x16x32_bf16 v[24:27], v[92:95], v[164:167], v[24:27]
	s_waitcnt lgkmcnt(0)
	v_mfma_f32_16x16x32_bf16 v[12:15], v[68:71], v[172:175], v[12:15]
	v_mfma_f32_16x16x32_bf16 v[8:11], v[92:95], v[172:175], v[8:11]
	s_barrier
	s_add_u32 s62, s62, 0x10080
	s_addc_u32 s63, s63, 0
	s_add_i32 s28, s29, s67
	v_lshl_add_u64 v[64:65], s[62:63], 0, v[198:199]
	s_mov_b32 m0, s28
	s_nop 0
	global_load_lds_dwordx4 v[64:65], off
	v_lshl_add_u64 v[64:65], s[62:63], 0, v[202:203]
	s_add_i32 m0, s28, 0x2000
	s_nop 0
	global_load_lds_dwordx4 v[64:65], off
	s_waitcnt vmcnt(6)
	s_barrier
	v_mfma_f32_16x16x32_bf16 v[52:55], v[176:179], v[144:147], v[52:55]
	v_mfma_f32_16x16x32_bf16 v[48:51], v[184:187], v[144:147], v[48:51]
	v_mfma_f32_16x16x32_bf16 v[36:39], v[176:179], v[152:155], v[36:39]
	v_mfma_f32_16x16x32_bf16 v[32:35], v[184:187], v[152:155], v[32:35]
	v_mfma_f32_16x16x32_bf16 v[20:23], v[176:179], v[160:163], v[20:23]
	v_mfma_f32_16x16x32_bf16 v[16:19], v[184:187], v[160:163], v[16:19]
	v_mfma_f32_16x16x32_bf16 v[4:7], v[176:179], v[168:171], v[4:7]
	v_mfma_f32_16x16x32_bf16 v[0:3], v[184:187], v[168:171], v[0:3]
	v_mfma_f32_16x16x32_bf16 v[52:55], v[180:183], v[148:151], v[52:55]
	v_mfma_f32_16x16x32_bf16 v[48:51], v[188:191], v[148:151], v[48:51]
	v_mfma_f32_16x16x32_bf16 v[36:39], v[180:183], v[156:159], v[36:39]
	v_mfma_f32_16x16x32_bf16 v[32:35], v[188:191], v[156:159], v[32:35]
	v_mfma_f32_16x16x32_bf16 v[20:23], v[180:183], v[164:167], v[20:23]
	v_mfma_f32_16x16x32_bf16 v[16:19], v[188:191], v[164:167], v[16:19]
	v_mfma_f32_16x16x32_bf16 v[4:7], v[180:183], v[172:175], v[4:7]
	v_mfma_f32_16x16x32_bf16 v[0:3], v[188:191], v[172:175], v[0:3]
	s_add_i32 s92, s92, 2
	s_add_u32 s10, s10, 0x100
	s_addc_u32 s11, s11, 0
	s_add_u32 s55, s55, 0x100
	s_addc_u32 s57, s57, 0
	s_cmp_gt_u32 s92, 13
	s_barrier
	s_cbranch_scc0 .LBB0_740
	v_lshl_add_u32 v212, s8, 8, v195
	v_lshl_or_b32 v214, s12, 8, v219
	v_ashrrev_i32_e32 v213, 31, v212
	v_ashrrev_i32_e32 v215, 31, v214
	s_mov_b64 s[8:9], -1
	s_and_b64 vcc, exec, s[48:49]
	s_cbranch_vccz .LBB0_743
	v_lshlrev_b64 v[64:65], 12, v[212:213]
	v_lshl_add_u64 v[64:65], s[36:37], 0, v[64:65]
	v_lshl_add_u64 v[64:65], v[214:215], 2, v[64:65]
	global_load_dwordx4 v[160:163], v[64:65], off offset:16
	global_load_dwordx4 v[164:167], v[64:65], off
	global_load_dwordx4 v[168:171], v[64:65], off offset:144
	global_load_dwordx4 v[172:175], v[64:65], off offset:128
	s_mov_b64 s[8:9], 0

.LBB0_904:
	ds_read_b128 v[146:149], v169
	ds_read_b128 v[150:153], v169 offset:1024
	ds_read_b128 v[154:157], v169 offset:2048
	ds_read_b128 v[174:177], v169 offset:3072
	s_add_u32 s28, s0, 0xfffc0080
	s_addc_u32 s29, s1, -1
	s_cmp_eq_u32 s78, 12
	s_cselect_b32 s53, s7, s29
	s_cselect_b32 s52, s45, s28
	s_cselect_b32 s51, s37, s77
	s_cselect_b32 s50, s67, s76
	v_lshl_add_u64 v[158:159], s[0:1], 0, v[138:139]
	s_add_i32 m0, s54, 0xc000
	ds_read_b128 v[178:181], v171
	ds_read_b128 v[182:185], v171 offset:1024
	ds_read_b128 v[186:189], v171 offset:2048
	ds_read_b128 v[196:199], v171 offset:3072
	ds_read_b128 v[200:203], v171 offset:4096
	ds_read_b128 v[204:207], v171 offset:5120
	ds_read_b128 v[208:211], v171 offset:6144
	ds_read_b128 v[212:215], v171 offset:7168
	global_load_lds_dwordx4 v[158:159], off
	v_lshl_add_u64 v[158:159], s[0:1], 0, v[140:141]
	s_add_i32 m0, s54, 0xe000
	s_nop 0
	global_load_lds_dwordx4 v[158:159], off
	s_waitcnt lgkmcnt(8)
	s_barrier
	s_waitcnt lgkmcnt(7)
	v_mfma_f32_16x16x32_bf16 v[124:127], v[146:149], v[178:181], v[124:127]
	v_mfma_f32_16x16x32_bf16 v[120:123], v[154:157], v[178:181], v[120:123]
	s_waitcnt lgkmcnt(5)
	v_mfma_f32_16x16x32_bf16 v[108:111], v[146:149], v[186:189], v[108:111]
	v_mfma_f32_16x16x32_bf16 v[104:107], v[154:157], v[186:189], v[104:107]
	s_waitcnt lgkmcnt(3)
	v_mfma_f32_16x16x32_bf16 v[92:95], v[146:149], v[200:203], v[92:95]
	v_mfma_f32_16x16x32_bf16 v[88:91], v[154:157], v[200:203], v[88:91]
	s_waitcnt lgkmcnt(1)
	v_mfma_f32_16x16x32_bf16 v[76:79], v[146:149], v[208:211], v[76:79]
	v_mfma_f32_16x16x32_bf16 v[72:75], v[154:157], v[208:211], v[72:75]
	v_mfma_f32_16x16x32_bf16 v[124:127], v[150:153], v[182:185], v[124:127]
	v_mfma_f32_16x16x32_bf16 v[120:123], v[174:177], v[182:185], v[120:123]
	v_mfma_f32_16x16x32_bf16 v[108:111], v[150:153], v[196:199], v[108:111]
	v_mfma_f32_16x16x32_bf16 v[104:107], v[174:177], v[196:199], v[104:107]
	v_mfma_f32_16x16x32_bf16 v[92:95], v[150:153], v[204:207], v[92:95]
	v_mfma_f32_16x16x32_bf16 v[88:91], v[174:177], v[204:207], v[88:91]
	s_waitcnt lgkmcnt(0)
	v_mfma_f32_16x16x32_bf16 v[76:79], v[150:153], v[212:215], v[76:79]
	v_mfma_f32_16x16x32_bf16 v[72:75], v[174:177], v[212:215], v[72:75]
	s_barrier
	s_add_i32 s28, s63, s13
	v_lshl_add_u64 v[158:159], s[50:51], 0, v[132:133]
	s_mov_b32 m0, s28
	ds_read_b128 v[216:219], v172
	ds_read_b128 v[220:223], v172 offset:1024
	ds_read_b128 v[224:227], v172 offset:2048
	ds_read_b128 v[228:231], v172 offset:3072
	global_load_lds_dwordx4 v[158:159], off
	v_lshl_add_u64 v[164:165], s[50:51], 0, v[128:129]
	s_add_i32 m0, s28, 0x2000
	s_nop 0
	global_load_lds_dwordx4 v[164:165], off
	s_barrier
	s_waitcnt lgkmcnt(3)
	v_mfma_f32_16x16x32_bf16 v[116:119], v[216:219], v[178:181], v[116:119]
	s_waitcnt lgkmcnt(1)
	v_mfma_f32_16x16x32_bf16 v[112:115], v[224:227], v[178:181], v[112:115]
	v_mfma_f32_16x16x32_bf16 v[100:103], v[216:219], v[186:189], v[100:103]
	v_mfma_f32_16x16x32_bf16 v[96:99], v[224:227], v[186:189], v[96:99]
	v_mfma_f32_16x16x32_bf16 v[84:87], v[216:219], v[200:203], v[84:87]
	v_mfma_f32_16x16x32_bf16 v[80:83], v[224:227], v[200:203], v[80:83]
	v_mfma_f32_16x16x32_bf16 v[68:71], v[216:219], v[208:211], v[68:71]
	v_mfma_f32_16x16x32_bf16 v[64:67], v[224:227], v[208:211], v[64:67]
	v_mfma_f32_16x16x32_bf16 v[116:119], v[220:223], v[182:185], v[116:119]
	s_waitcnt lgkmcnt(0)
	v_mfma_f32_16x16x32_bf16 v[112:115], v[228:231], v[182:185], v[112:115]
	v_mfma_f32_16x16x32_bf16 v[100:103], v[220:223], v[196:199], v[100:103]
	v_mfma_f32_16x16x32_bf16 v[96:99], v[228:231], v[196:199], v[96:99]
	v_mfma_f32_16x16x32_bf16 v[84:87], v[220:223], v[204:207], v[84:87]
	v_mfma_f32_16x16x32_bf16 v[80:83], v[228:231], v[204:207], v[80:83]
	v_mfma_f32_16x16x32_bf16 v[68:71], v[220:223], v[212:215], v[68:71]
	v_mfma_f32_16x16x32_bf16 v[64:67], v[228:231], v[212:215], v[64:67]
	s_mov_b32 m0, s54
	v_lshl_add_u64 v[190:191], s[52:53], 0, v[134:135]
	s_barrier
	ds_read_b128 v[178:181], v171 offset:16384
	ds_read_b128 v[182:185], v171 offset:17408
	ds_read_b128 v[186:189], v171 offset:18432
	ds_read_b128 v[196:199], v171 offset:19456
	ds_read_b128 v[200:203], v171 offset:20480
	ds_read_b128 v[204:207], v171 offset:21504
	ds_read_b128 v[208:211], v171 offset:22528
	ds_read_b128 v[212:215], v171 offset:23552
	global_load_lds_dwordx4 v[190:191], off
	v_lshl_add_u64 v[232:233], s[52:53], 0, v[130:131]
	s_mov_b32 m0, s55
	s_nop 0
	global_load_lds_dwordx4 v[232:233], off
	s_barrier
	s_waitcnt lgkmcnt(7)
	v_mfma_f32_16x16x32_bf16 v[60:63], v[146:149], v[178:181], v[60:63]
	v_mfma_f32_16x16x32_bf16 v[56:59], v[154:157], v[178:181], v[56:59]
	s_waitcnt lgkmcnt(5)
	v_mfma_f32_16x16x32_bf16 v[44:47], v[146:149], v[186:189], v[44:47]
	v_mfma_f32_16x16x32_bf16 v[40:43], v[154:157], v[186:189], v[40:43]
	s_waitcnt lgkmcnt(3)
	v_mfma_f32_16x16x32_bf16 v[28:31], v[146:149], v[200:203], v[28:31]
	v_mfma_f32_16x16x32_bf16 v[24:27], v[154:157], v[200:203], v[24:27]
	s_waitcnt lgkmcnt(1)
	v_mfma_f32_16x16x32_bf16 v[12:15], v[146:149], v[208:211], v[12:15]
	v_mfma_f32_16x16x32_bf16 v[8:11], v[154:157], v[208:211], v[8:11]
	v_mfma_f32_16x16x32_bf16 v[60:63], v[150:153], v[182:185], v[60:63]
	v_mfma_f32_16x16x32_bf16 v[56:59], v[174:177], v[182:185], v[56:59]
	v_mfma_f32_16x16x32_bf16 v[44:47], v[150:153], v[196:199], v[44:47]
	v_mfma_f32_16x16x32_bf16 v[40:43], v[174:177], v[196:199], v[40:43]
	v_mfma_f32_16x16x32_bf16 v[28:31], v[150:153], v[204:207], v[28:31]
	v_mfma_f32_16x16x32_bf16 v[24:27], v[174:177], v[204:207], v[24:27]
	s_waitcnt lgkmcnt(0)
	v_mfma_f32_16x16x32_bf16 v[12:15], v[150:153], v[212:215], v[12:15]
	v_mfma_f32_16x16x32_bf16 v[8:11], v[174:177], v[212:215], v[8:11]
	s_barrier
	s_add_u32 s80, s50, 0x10000
	s_addc_u32 s81, s51, 0
	s_add_i32 s28, s64, s13
	v_lshl_add_u64 v[146:147], s[80:81], 0, v[132:133]
	s_mov_b32 m0, s28
	s_nop 0
	global_load_lds_dwordx4 v[146:147], off
	v_lshl_add_u64 v[146:147], s[80:81], 0, v[128:129]
	s_add_i32 m0, s28, 0x2000
	s_nop 0
	global_load_lds_dwordx4 v[146:147], off
	s_waitcnt vmcnt(6)
	s_barrier
	v_mfma_f32_16x16x32_bf16 v[52:55], v[216:219], v[178:181], v[52:55]
	v_mfma_f32_16x16x32_bf16 v[48:51], v[224:227], v[178:181], v[48:51]
	v_mfma_f32_16x16x32_bf16 v[36:39], v[216:219], v[186:189], v[36:39]
	v_mfma_f32_16x16x32_bf16 v[32:35], v[224:227], v[186:189], v[32:35]
	v_mfma_f32_16x16x32_bf16 v[20:23], v[216:219], v[200:203], v[20:23]
	v_mfma_f32_16x16x32_bf16 v[16:19], v[224:227], v[200:203], v[16:19]
	v_mfma_f32_16x16x32_bf16 v[4:7], v[216:219], v[208:211], v[4:7]
	v_mfma_f32_16x16x32_bf16 v[0:3], v[224:227], v[208:211], v[0:3]
	v_mfma_f32_16x16x32_bf16 v[52:55], v[220:223], v[182:185], v[52:55]
	v_mfma_f32_16x16x32_bf16 v[48:51], v[228:231], v[182:185], v[48:51]
	v_mfma_f32_16x16x32_bf16 v[36:39], v[220:223], v[196:199], v[36:39]
	v_mfma_f32_16x16x32_bf16 v[32:35], v[228:231], v[196:199], v[32:35]
	v_mfma_f32_16x16x32_bf16 v[20:23], v[220:223], v[204:207], v[20:23]
	v_mfma_f32_16x16x32_bf16 v[16:19], v[228:231], v[204:207], v[16:19]
	v_mfma_f32_16x16x32_bf16 v[4:7], v[220:223], v[212:215], v[4:7]
	v_mfma_f32_16x16x32_bf16 v[0:3], v[228:231], v[212:215], v[0:3]
	s_add_i32 s28, 0, 0x18000
	v_add_u32_e32 v160, s28, v163
	s_barrier
	ds_read_b128 v[146:149], v160
	ds_read_b128 v[150:153], v160 offset:1024
	ds_read_b128 v[154:157], v160 offset:2048
	ds_read_b128 v[174:177], v160 offset:3072
	s_add_u32 s52, s52, 0x40000
	s_addc_u32 s53, s53, 0
	s_mov_b32 m0, s56
	v_lshl_add_u64 v[216:217], s[52:53], 0, v[134:135]
	ds_read_b128 v[178:181], v171 offset:32768
	ds_read_b128 v[182:185], v171 offset:33792
	ds_read_b128 v[186:189], v171 offset:34816
	ds_read_b128 v[196:199], v171 offset:35840
	ds_read_b128 v[200:203], v171 offset:36864
	ds_read_b128 v[204:207], v171 offset:37888
	ds_read_b128 v[208:211], v171 offset:38912
	ds_read_b128 v[212:215], v171 offset:39936
	global_load_lds_dwordx4 v[216:217], off
	v_lshl_add_u64 v[216:217], s[52:53], 0, v[130:131]
	s_mov_b32 m0, s57
	s_nop 0
	global_load_lds_dwordx4 v[216:217], off
	s_waitcnt lgkmcnt(8)
	s_barrier
	s_waitcnt lgkmcnt(7)
	v_mfma_f32_16x16x32_bf16 v[124:127], v[146:149], v[178:181], v[124:127]
	v_mfma_f32_16x16x32_bf16 v[120:123], v[154:157], v[178:181], v[120:123]
	s_waitcnt lgkmcnt(5)
	v_mfma_f32_16x16x32_bf16 v[108:111], v[146:149], v[186:189], v[108:111]
	v_mfma_f32_16x16x32_bf16 v[104:107], v[154:157], v[186:189], v[104:107]
	s_waitcnt lgkmcnt(3)
	v_mfma_f32_16x16x32_bf16 v[92:95], v[146:149], v[200:203], v[92:95]
	v_mfma_f32_16x16x32_bf16 v[88:91], v[154:157], v[200:203], v[88:91]
	s_waitcnt lgkmcnt(1)
	v_mfma_f32_16x16x32_bf16 v[76:79], v[146:149], v[208:211], v[76:79]
	v_mfma_f32_16x16x32_bf16 v[72:75], v[154:157], v[208:211], v[72:75]
	v_mfma_f32_16x16x32_bf16 v[124:127], v[150:153], v[182:185], v[124:127]
	v_mfma_f32_16x16x32_bf16 v[120:123], v[174:177], v[182:185], v[120:123]
	v_mfma_f32_16x16x32_bf16 v[108:111], v[150:153], v[196:199], v[108:111]
	v_mfma_f32_16x16x32_bf16 v[104:107], v[174:177], v[196:199], v[104:107]
	v_mfma_f32_16x16x32_bf16 v[92:95], v[150:153], v[204:207], v[92:95]
	v_mfma_f32_16x16x32_bf16 v[88:91], v[174:177], v[204:207], v[88:91]
	s_waitcnt lgkmcnt(0)
	v_mfma_f32_16x16x32_bf16 v[76:79], v[150:153], v[212:215], v[76:79]
	v_mfma_f32_16x16x32_bf16 v[72:75], v[174:177], v[212:215], v[72:75]
	s_barrier
	s_add_i32 s29, 0, 0x1c000
	s_add_i32 s28, s28, s13
	v_add_u32_e32 v160, s29, v163
	v_lshl_add_u64 v[158:159], v[158:159], 0, s[8:9]
	s_mov_b32 m0, s28
	ds_read_b128 v[216:219], v160
	ds_read_b128 v[220:223], v160 offset:1024
	ds_read_b128 v[224:227], v160 offset:2048
	ds_read_b128 v[228:231], v160 offset:3072
	global_load_lds_dwordx4 v[158:159], off
	v_lshl_add_u64 v[158:159], v[164:165], 0, s[8:9]
	s_add_i32 m0, s28, 0x2000
	s_nop 0
	global_load_lds_dwordx4 v[158:159], off
	s_barrier
	s_waitcnt lgkmcnt(3)
	v_mfma_f32_16x16x32_bf16 v[116:119], v[216:219], v[178:181], v[116:119]
	s_waitcnt lgkmcnt(1)
	v_mfma_f32_16x16x32_bf16 v[112:115], v[224:227], v[178:181], v[112:115]
	v_mfma_f32_16x16x32_bf16 v[100:103], v[216:219], v[186:189], v[100:103]
	v_mfma_f32_16x16x32_bf16 v[96:99], v[224:227], v[186:189], v[96:99]
	v_mfma_f32_16x16x32_bf16 v[84:87], v[216:219], v[200:203], v[84:87]
	v_mfma_f32_16x16x32_bf16 v[80:83], v[224:227], v[200:203], v[80:83]
	v_mfma_f32_16x16x32_bf16 v[68:71], v[216:219], v[208:211], v[68:71]
	v_mfma_f32_16x16x32_bf16 v[64:67], v[224:227], v[208:211], v[64:67]
	v_mfma_f32_16x16x32_bf16 v[116:119], v[220:223], v[182:185], v[116:119]
	s_waitcnt lgkmcnt(0)
	v_mfma_f32_16x16x32_bf16 v[112:115], v[228:231], v[182:185], v[112:115]
	v_mfma_f32_16x16x32_bf16 v[100:103], v[220:223], v[196:199], v[100:103]
	v_mfma_f32_16x16x32_bf16 v[96:99], v[228:231], v[196:199], v[96:99]
	v_mfma_f32_16x16x32_bf16 v[84:87], v[220:223], v[204:207], v[84:87]
	v_mfma_f32_16x16x32_bf16 v[80:83], v[228:231], v[204:207], v[80:83]
	v_mfma_f32_16x16x32_bf16 v[68:71], v[220:223], v[212:215], v[68:71]
	v_mfma_f32_16x16x32_bf16 v[64:67], v[228:231], v[212:215], v[64:67]
	s_mov_b32 m0, s60
	v_lshl_add_u64 v[158:159], v[190:191], 0, s[8:9]
	s_barrier
	ds_read_b128 v[178:181], v171 offset:49152
	ds_read_b128 v[182:185], v171 offset:50176
	ds_read_b128 v[186:189], v171 offset:51200
	ds_read_b128 v[196:199], v171 offset:52224
	ds_read_b128 v[200:203], v171 offset:53248
	ds_read_b128 v[204:207], v171 offset:54272
	ds_read_b128 v[208:211], v171 offset:55296
	ds_read_b128 v[212:215], v171 offset:56320
	global_load_lds_dwordx4 v[158:159], off
	v_lshl_add_u64 v[158:159], v[232:233], 0, s[8:9]
	s_mov_b32 m0, s61
	s_nop 0
	global_load_lds_dwordx4 v[158:159], off
	s_barrier
	s_waitcnt lgkmcnt(7)
	v_mfma_f32_16x16x32_bf16 v[60:63], v[146:149], v[178:181], v[60:63]
	v_mfma_f32_16x16x32_bf16 v[56:59], v[154:157], v[178:181], v[56:59]
	s_waitcnt lgkmcnt(5)
	v_mfma_f32_16x16x32_bf16 v[44:47], v[146:149], v[186:189], v[44:47]
	v_mfma_f32_16x16x32_bf16 v[40:43], v[154:157], v[186:189], v[40:43]
	s_waitcnt lgkmcnt(3)
	v_mfma_f32_16x16x32_bf16 v[28:31], v[146:149], v[200:203], v[28:31]
	v_mfma_f32_16x16x32_bf16 v[24:27], v[154:157], v[200:203], v[24:27]
	s_waitcnt lgkmcnt(1)
	v_mfma_f32_16x16x32_bf16 v[12:15], v[146:149], v[208:211], v[12:15]
	v_mfma_f32_16x16x32_bf16 v[8:11], v[154:157], v[208:211], v[8:11]
	v_mfma_f32_16x16x32_bf16 v[60:63], v[150:153], v[182:185], v[60:63]
	v_mfma_f32_16x16x32_bf16 v[56:59], v[174:177], v[182:185], v[56:59]
	v_mfma_f32_16x16x32_bf16 v[44:47], v[150:153], v[196:199], v[44:47]
	v_mfma_f32_16x16x32_bf16 v[40:43], v[174:177], v[196:199], v[40:43]
	v_mfma_f32_16x16x32_bf16 v[28:31], v[150:153], v[204:207], v[28:31]
	v_mfma_f32_16x16x32_bf16 v[24:27], v[174:177], v[204:207], v[24:27]
	s_waitcnt lgkmcnt(0)
	v_mfma_f32_16x16x32_bf16 v[12:15], v[150:153], v[212:215], v[12:15]
	v_mfma_f32_16x16x32_bf16 v[8:11], v[174:177], v[212:215], v[8:11]
	s_barrier
	s_add_u32 s50, s50, 0x10080
	s_addc_u32 s51, s51, 0
	s_add_i32 s28, s29, s13
	v_lshl_add_u64 v[146:147], s[50:51], 0, v[132:133]
	s_mov_b32 m0, s28
	s_nop 0
	global_load_lds_dwordx4 v[146:147], off
	v_lshl_add_u64 v[146:147], s[50:51], 0, v[128:129]
	s_add_i32 m0, s28, 0x2000
	s_nop 0
	global_load_lds_dwordx4 v[146:147], off
	s_waitcnt vmcnt(6)
	s_barrier
	v_mfma_f32_16x16x32_bf16 v[52:55], v[216:219], v[178:181], v[52:55]
	v_mfma_f32_16x16x32_bf16 v[48:51], v[224:227], v[178:181], v[48:51]
	v_mfma_f32_16x16x32_bf16 v[36:39], v[216:219], v[186:189], v[36:39]
	v_mfma_f32_16x16x32_bf16 v[32:35], v[224:227], v[186:189], v[32:35]
	v_mfma_f32_16x16x32_bf16 v[20:23], v[216:219], v[200:203], v[20:23]
	v_mfma_f32_16x16x32_bf16 v[16:19], v[224:227], v[200:203], v[16:19]
	v_mfma_f32_16x16x32_bf16 v[4:7], v[216:219], v[208:211], v[4:7]
	v_mfma_f32_16x16x32_bf16 v[0:3], v[224:227], v[208:211], v[0:3]
	v_mfma_f32_16x16x32_bf16 v[52:55], v[220:223], v[182:185], v[52:55]
	v_mfma_f32_16x16x32_bf16 v[48:51], v[228:231], v[182:185], v[48:51]
	v_mfma_f32_16x16x32_bf16 v[36:39], v[220:223], v[196:199], v[36:39]
	v_mfma_f32_16x16x32_bf16 v[32:35], v[228:231], v[196:199], v[32:35]
	v_mfma_f32_16x16x32_bf16 v[20:23], v[220:223], v[204:207], v[20:23]
	v_mfma_f32_16x16x32_bf16 v[16:19], v[228:231], v[204:207], v[16:19]
	v_mfma_f32_16x16x32_bf16 v[4:7], v[220:223], v[212:215], v[4:7]
	v_mfma_f32_16x16x32_bf16 v[0:3], v[228:231], v[212:215], v[0:3]
	s_add_i32 s78, s78, 2
	s_add_u32 s0, s0, 0x100
	s_addc_u32 s1, s1, 0
	s_add_u32 s76, s76, 0x100
	s_addc_u32 s77, s77, 0
	s_cmp_gt_u32 s78, 13
	s_barrier
	s_cbranch_scc0 .LBB0_904
	v_lshl_add_u32 v146, s6, 8, v161
	v_or_b32_e32 v164, 16, v146
	v_ashrrev_i32_e32 v165, 31, v164
	v_lshlrev_b64 v[148:149], 6, v[164:165]
	v_or_b32_e32 v158, 32, v146
	v_lshl_add_u64 v[148:149], v[136:137], 0, v[148:149]
	v_ashrrev_i32_e32 v159, 31, v158
	v_or_b32_e32 v156, 48, v146
	global_load_dwordx4 v[174:177], v[148:149], off
	v_lshlrev_b64 v[148:149], 6, v[158:159]
	v_ashrrev_i32_e32 v157, 31, v156
	v_add_u32_e32 v154, 0x80, v146
	v_lshl_add_u64 v[148:149], v[136:137], 0, v[148:149]
	v_lshlrev_b64 v[150:151], 6, v[156:157]
	v_ashrrev_i32_e32 v155, 31, v154
	v_lshl_add_u64 v[150:151], v[136:137], 0, v[150:151]
	global_load_dwordx4 v[178:181], v[148:149], off
	global_load_dwordx4 v[182:185], v[150:151], off
	v_lshlrev_b64 v[148:149], 6, v[154:155]
	v_lshl_add_u64 v[148:149], v[136:137], 0, v[148:149]
	global_load_dwordx4 v[186:189], v[148:149], off
	v_ashrrev_i32_e32 v147, 31, v146
	v_lshlrev_b64 v[148:149], 6, v[146:147]
	v_add_u32_e32 v152, 0x90, v146
	v_lshl_add_u64 v[148:149], v[136:137], 0, v[148:149]
	v_ashrrev_i32_e32 v153, 31, v152
	global_load_dwordx4 v[196:199], v[148:149], off
	v_lshlrev_b64 v[148:149], 6, v[152:153]
	v_lshl_add_u64 v[148:149], v[136:137], 0, v[148:149]
	global_load_dwordx4 v[200:203], v[148:149], off
	v_add_u32_e32 v148, 0xa0, v146
	v_ashrrev_i32_e32 v149, 31, v148
	v_lshlrev_b64 v[150:151], 6, v[148:149]
	v_lshl_add_u64 v[150:151], v[136:137], 0, v[150:151]
	global_load_dwordx4 v[204:207], v[150:151], off
	v_add_u32_e32 v150, 0xb0, v146
	v_ashrrev_i32_e32 v151, 31, v150
	v_lshlrev_b64 v[208:209], 6, v[150:151]
	v_lshl_add_u64 v[208:209], v[136:137], 0, v[208:209]
	global_load_dwordx4 v[208:211], v[208:209], off
	v_and_b32_e32 v149, 64, v173
	v_xor_b32_e32 v147, 16, v173
	v_add_u32_e32 v149, 64, v149
	v_cmp_lt_i32_e32 vcc, v147, v149
	v_xor_b32_e32 v153, 32, v173
	v_mov_b64_e32 v[190:191], s[12:13]
	v_cndmask_b32_e32 v147, v173, v147, vcc
	v_lshlrev_b32_e32 v147, 2, v147
	v_cmp_lt_i32_e32 vcc, v153, v149
	s_waitcnt vmcnt(0)
	v_mov_b32_e32 v212, v175
	v_mov_b32_e32 v213, v176
	v_mov_b32_e32 v175, v177
	v_pk_add_f32 v[174:175], v[212:213], v[174:175]
	v_cndmask_b32_e32 v149, v173, v153, vcc
	v_lshlrev_b32_e32 v149, 2, v149
	v_mov_b32_e32 v176, v179
	v_mov_b32_e32 v177, v180
	v_mov_b32_e32 v179, v181
	v_mov_b32_e32 v180, v183
	v_mov_b32_e32 v181, v184
	v_mov_b32_e32 v183, v185
	v_mov_b32_e32 v184, v187
	v_mov_b32_e32 v185, v188
	v_mov_b32_e32 v187, v189
	v_pk_add_f32 v[176:177], v[176:177], v[178:179]
	v_pk_add_f32 v[178:179], v[180:181], v[182:183]
	v_pk_add_f32 v[180:181], v[184:185], v[186:187]
	v_mov_b32_e32 v182, v176
	v_mov_b32_e32 v183, v174
	v_mov_b32_e32 v174, v177
	v_mov_b32_e32 v176, v180
	v_mov_b32_e32 v177, v178
	v_mov_b32_e32 v178, v181
	v_pk_add_f32 v[174:175], v[182:183], v[174:175]
	v_pk_add_f32 v[176:177], v[176:177], v[178:179]
	ds_bpermute_b32 v179, v147, v175
	ds_bpermute_b32 v178, v147, v174
	ds_bpermute_b32 v181, v147, v177
	ds_bpermute_b32 v180, v147, v176
	v_mov_b32_e32 v184, v201
	v_mov_b32_e32 v185, v202
	s_waitcnt lgkmcnt(0)
	v_pk_add_f32 v[174:175], v[174:175], v[178:179]
	ds_bpermute_b32 v179, v149, v175
	v_pk_add_f32 v[176:177], v[176:177], v[180:181]
	ds_bpermute_b32 v178, v149, v174
	ds_bpermute_b32 v181, v149, v177
	ds_bpermute_b32 v180, v149, v176
	v_mov_b32_e32 v201, v203
	v_mov_b32_e32 v182, v197
	s_waitcnt lgkmcnt(2)
	v_pk_add_f32 v[174:175], v[174:175], v[178:179]
	v_pk_add_f32 v[178:179], v[184:185], v[200:201]
	s_waitcnt lgkmcnt(0)
	v_pk_add_f32 v[176:177], v[176:177], v[180:181]
	v_pk_fma_f32 v[174:175], v[174:175], s[10:11], v[190:191] op_sel_hi:[1,0,0]
	v_mov_b32_e32 v180, v205
	v_mov_b32_e32 v181, v206
	v_mov_b32_e32 v205, v207
	v_mul_f32_e32 v151, 0x4b800000, v175
	v_cmp_gt_f32_e32 vcc, s65, v175
	v_pk_add_f32 v[180:181], v[180:181], v[204:205]
	v_mov_b32_e32 v185, v178
	v_cndmask_b32_e32 v151, v175, v151, vcc
	v_mov_b32_e32 v184, v180
	v_mov_b32_e32 v178, v181
	v_rsq_f32_e32 v151, v151
	v_pk_add_f32 v[178:179], v[184:185], v[178:179]
	ds_bpermute_b32 v181, v147, v179
	ds_bpermute_b32 v180, v147, v178
	v_pk_fma_f32 v[176:177], v[176:177], s[10:11], v[190:191] op_sel_hi:[1,0,0]
	v_mul_f32_e32 v153, 0x4b800000, v174
	v_cmp_gt_f32_e64 s[0:1], s65, v174
	v_mul_f32_e32 v157, 0x45800000, v151
	v_mul_f32_e32 v155, 0x4b800000, v177
	v_cndmask_b32_e64 v153, v174, v153, s[0:1]
	v_cmp_gt_f32_e64 s[6:7], s65, v177
	v_cndmask_b32_e32 v174, v151, v157, vcc
	v_mul_f32_e32 v151, 0x4b800000, v176
	v_cmp_gt_f32_e32 vcc, s65, v176
	v_cndmask_b32_e64 v155, v177, v155, s[6:7]
	v_rsq_f32_e32 v153, v153
	v_cndmask_b32_e32 v151, v176, v151, vcc
	s_waitcnt lgkmcnt(0)
	v_pk_add_f32 v[176:177], v[178:179], v[180:181]
	ds_bpermute_b32 v179, v149, v177
	ds_bpermute_b32 v178, v149, v176
	v_rsq_f32_e32 v155, v155
	v_mul_f32_e32 v159, 0x45800000, v153
	v_cndmask_b32_e64 v180, v153, v159, s[0:1]
	v_rsq_f32_e32 v151, v151
	s_waitcnt lgkmcnt(0)
	v_pk_add_f32 v[176:177], v[176:177], v[178:179]
	v_mul_f32_e32 v153, 0x45800000, v155
	v_pk_fma_f32 v[176:177], v[176:177], s[10:11], v[190:191] op_sel_hi:[1,0,0]
	v_cndmask_b32_e64 v170, v155, v153, s[6:7]
	v_mul_f32_e32 v155, 0x4b800000, v177
	v_cmp_gt_f32_e64 s[0:1], s65, v177
	v_mul_f32_e32 v157, 0x4b800000, v176
	v_cmp_gt_f32_e64 s[6:7], s65, v176
	v_cndmask_b32_e64 v155, v177, v155, s[0:1]
	v_rsq_f32_e32 v155, v155
	v_cndmask_b32_e64 v157, v176, v157, s[6:7]
	v_rsq_f32_e32 v157, v157
	v_mul_f32_e32 v153, 0x45800000, v151
	v_cndmask_b32_e32 v168, v151, v153, vcc
	v_mul_f32_e32 v151, 0x45800000, v155
	v_mov_b32_e32 v183, v198
	v_mov_b32_e32 v197, v199
	v_cndmask_b32_e64 v166, v155, v151, s[0:1]
	v_mul_f32_e32 v151, 0x45800000, v157
	v_mov_b32_e32 v176, v209
	v_mov_b32_e32 v177, v210
	v_mov_b32_e32 v209, v211
	v_pk_add_f32 v[182:183], v[182:183], v[196:197]
	v_cndmask_b32_e64 v162, v157, v151, s[6:7]
	v_pk_add_f32 v[176:177], v[176:177], v[208:209]
	v_mov_b32_e32 v178, v182
	v_mov_b32_e32 v179, v176
	v_mov_b32_e32 v176, v183
	v_pk_add_f32 v[176:177], v[178:179], v[176:177]
	ds_bpermute_b32 v178, v147, v176
	ds_bpermute_b32 v179, v147, v177
	v_lshl_or_b32 v182, s66, 8, v167
	v_pk_mul_f32 v[100:101], v[100:101], v[174:175] op_sel_hi:[1,0]
	v_pk_mul_f32 v[108:109], v[108:109], v[174:175] op_sel_hi:[1,0]
	v_ashrrev_i32_e32 v183, 31, v182
	s_waitcnt lgkmcnt(0)
	v_pk_add_f32 v[176:177], v[176:177], v[178:179]
	ds_bpermute_b32 v178, v149, v176
	ds_bpermute_b32 v179, v149, v177
	v_pk_mul_f32 v[96:97], v[96:97], v[174:175] op_sel_hi:[1,0]
	v_pk_mul_f32 v[102:103], v[102:103], v[174:175] op_sel_hi:[1,0]
	v_pk_mul_f32 v[110:111], v[110:111], v[174:175] op_sel_hi:[1,0]
	v_cvt_pk_bf16_f32 v108, v108, v109
	s_waitcnt lgkmcnt(0)
	v_pk_add_f32 v[176:177], v[176:177], v[178:179]
	v_pk_mul_f32 v[106:107], v[106:107], v[174:175] op_sel_hi:[1,0]
	v_pk_fma_f32 v[176:177], v[176:177], s[10:11], v[190:191] op_sel_hi:[1,0,0]
	v_pk_mul_f32 v[104:105], v[104:105], v[174:175] op_sel_hi:[1,0]
	v_mul_f32_e32 v147, 0x4b800000, v177
	v_cmp_gt_f32_e32 vcc, s65, v177
	v_mul_f32_e32 v149, 0x4b800000, v176
	v_cmp_gt_f32_e64 s[0:1], s65, v176
	v_cndmask_b32_e32 v147, v177, v147, vcc
	v_rsq_f32_e32 v147, v147
	v_cndmask_b32_e64 v149, v176, v149, s[0:1]
	v_rsq_f32_e32 v149, v149
	v_cvt_pk_bf16_f32 v100, v100, v101
	v_mul_f32_e32 v151, 0x45800000, v147
	v_cndmask_b32_e32 v160, v147, v151, vcc
	v_mul_f32_e32 v147, 0x45800000, v149
	v_cndmask_b32_e64 v176, v149, v147, s[0:1]
	v_pk_mul_f32 v[112:113], v[112:113], v[176:177] op_sel_hi:[1,0]
	v_pk_mul_f32 v[116:117], v[116:117], v[176:177] op_sel_hi:[1,0]
	v_pk_mul_f32 v[124:125], v[124:125], v[176:177] op_sel_hi:[1,0]
	v_pk_mul_f32 v[122:123], v[122:123], v[176:177] op_sel_hi:[1,0]
	v_pk_mul_f32 v[120:121], v[120:121], v[176:177] op_sel_hi:[1,0]
	v_pk_mul_f32 v[114:115], v[114:115], v[176:177] op_sel_hi:[1,0]
	v_pk_mul_f32 v[118:119], v[118:119], v[176:177] op_sel_hi:[1,0]
	v_pk_mul_f32 v[126:127], v[126:127], v[176:177] op_sel_hi:[1,0]
	v_cvt_pk_bf16_f32 v124, v124, v125
	v_cvt_pk_bf16_f32 v120, v120, v121
	v_cvt_pk_bf16_f32 v121, v122, v123
	v_cvt_pk_bf16_f32 v122, v116, v117
	v_cvt_pk_bf16_f32 v112, v112, v113
	v_cvt_pk_bf16_f32 v125, v126, v127
	v_cvt_pk_bf16_f32 v118, v118, v119
	v_cvt_pk_bf16_f32 v113, v114, v115
	v_cndmask_b32_e64 v114, v124, v122, s[2:3]
	v_mov_b32_e32 v123, 0
	v_cndmask_b32_e64 v115, v120, v112, s[2:3]
	v_mov_b32_e32 v126, 0
	v_mov_b32_dpp v123, v114 row_ror:8 row_mask:0xf bank_mask:0xf
	v_cndmask_b32_e64 v114, v125, v118, s[2:3]
	v_mov_b32_e32 v119, 0
	v_mov_b32_dpp v126, v115 row_ror:8 row_mask:0xf bank_mask:0xf
	v_mov_b32_e32 v127, 0
	v_mov_b32_dpp v119, v114 row_ror:8 row_mask:0xf bank_mask:0xf
	v_cndmask_b32_e64 v114, v121, v113, s[2:3]
	v_cndmask_b32_e64 v116, v126, v120, s[2:3]
	v_cndmask_b32_e64 v120, v112, v126, s[2:3]
	v_add_u32_e32 v112, -8, v146
	v_mov_b32_dpp v127, v114 row_ror:8 row_mask:0xf bank_mask:0xf
	v_cndmask_b32_e64 v112, v112, v146, s[2:3]
	v_cndmask_b32_e64 v117, v127, v121, s[2:3]
	v_cndmask_b32_e64 v121, v113, v127, s[2:3]
	v_ashrrev_i32_e32 v113, 31, v112
	v_lshlrev_b64 v[112:113], 10, v[112:113]
	v_cndmask_b32_e64 v115, v119, v125, s[2:3]
	v_cndmask_b32_e64 v114, v123, v124, s[2:3]
	v_cndmask_b32_e64 v119, v118, v119, s[2:3]
	v_cndmask_b32_e64 v118, v122, v123, s[2:3]
	v_lshl_add_u64 v[122:123], s[38:39], 0, v[112:113]
	v_lshlrev_b64 v[112:113], 1, v[182:183]
	v_pk_mul_f32 v[98:99], v[98:99], v[174:175] op_sel_hi:[1,0]
	v_cvt_pk_bf16_f32 v109, v110, v111
	v_cvt_pk_bf16_f32 v104, v104, v105
	v_cvt_pk_bf16_f32 v105, v106, v107
	v_cvt_pk_bf16_f32 v101, v102, v103
	v_cvt_pk_bf16_f32 v102, v96, v97
	v_cndmask_b32_e64 v96, v108, v100, s[2:3]
	v_mov_b32_e32 v106, 0
	v_lshl_add_u64 v[122:123], v[122:123], 0, v[112:113]
	v_cvt_pk_bf16_f32 v103, v98, v99
	v_mov_b32_dpp v106, v96 row_ror:8 row_mask:0xf bank_mask:0xf
	v_cndmask_b32_e64 v96, v109, v101, s[2:3]
	v_mov_b32_e32 v107, 0
	v_cndmask_b32_e64 v97, v104, v102, s[2:3]
	v_mov_b32_e32 v110, 0
	global_store_dwordx4 v[122:123], v[114:117], off
	v_mov_b32_dpp v107, v96 row_ror:8 row_mask:0xf bank_mask:0xf
	v_cndmask_b32_e64 v96, v105, v103, s[2:3]
	v_add_u32_e32 v116, 8, v146
	v_mov_b32_dpp v110, v97 row_ror:8 row_mask:0xf bank_mask:0xf
	v_mov_b32_e32 v111, 0
	v_cndmask_b32_e64 v114, v146, v116, s[2:3]
	v_cndmask_b32_e64 v98, v110, v104, s[2:3]
	v_mov_b32_dpp v111, v96 row_ror:8 row_mask:0xf bank_mask:0xf
	v_cndmask_b32_e64 v104, v116, v164, s[2:3]
	v_ashrrev_i32_e32 v115, 31, v114
	v_cndmask_b32_e64 v99, v111, v105, s[2:3]
	v_ashrrev_i32_e32 v105, 31, v104
	v_pk_mul_f32 v[84:85], v[84:85], v[180:181] op_sel_hi:[1,0]
	v_pk_mul_f32 v[92:93], v[92:93], v[180:181] op_sel_hi:[1,0]
	v_lshlrev_b64 v[114:115], 10, v[114:115]
	v_lshlrev_b64 v[104:105], 10, v[104:105]
	v_pk_mul_f32 v[80:81], v[80:81], v[180:181] op_sel_hi:[1,0]
	v_pk_mul_f32 v[86:87], v[86:87], v[180:181] op_sel_hi:[1,0]
	v_pk_mul_f32 v[94:95], v[94:95], v[180:181] op_sel_hi:[1,0]
	v_cvt_pk_bf16_f32 v92, v92, v93
	v_pk_mul_f32 v[90:91], v[90:91], v[180:181] op_sel_hi:[1,0]
	v_pk_mul_f32 v[88:89], v[88:89], v[180:181] op_sel_hi:[1,0]
	v_cvt_pk_bf16_f32 v84, v84, v85
	v_lshl_add_u64 v[114:115], s[38:39], 0, v[114:115]
	v_lshl_add_u64 v[104:105], s[38:39], 0, v[104:105]
	v_pk_mul_f32 v[82:83], v[82:83], v[180:181] op_sel_hi:[1,0]
	v_cvt_pk_bf16_f32 v93, v94, v95
	v_cvt_pk_bf16_f32 v88, v88, v89
	v_cvt_pk_bf16_f32 v89, v90, v91
	v_cvt_pk_bf16_f32 v85, v86, v87
	v_cvt_pk_bf16_f32 v86, v80, v81
	v_cndmask_b32_e64 v80, v92, v84, s[2:3]
	v_mov_b32_e32 v90, 0
	v_lshl_add_u64 v[114:115], v[114:115], 0, v[112:113]
	v_cndmask_b32_e64 v97, v107, v109, s[2:3]
	v_cndmask_b32_e64 v96, v106, v108, s[2:3]
	v_lshl_add_u64 v[104:105], v[104:105], 0, v[112:113]
	v_cvt_pk_bf16_f32 v87, v82, v83
	v_mov_b32_dpp v90, v80 row_ror:8 row_mask:0xf bank_mask:0xf
	v_cndmask_b32_e64 v80, v93, v85, s[2:3]
	v_mov_b32_e32 v91, 0
	v_cndmask_b32_e64 v81, v88, v86, s[2:3]
	v_mov_b32_e32 v94, 0
	global_store_dwordx4 v[114:115], v[118:121], off
	global_store_dwordx4 v[104:105], v[96:99], off
	v_mov_b32_dpp v91, v80 row_ror:8 row_mask:0xf bank_mask:0xf
	v_cndmask_b32_e64 v80, v89, v87, s[2:3]
	v_add_u32_e32 v98, 24, v146
	v_mov_b32_dpp v94, v81 row_ror:8 row_mask:0xf bank_mask:0xf
	v_mov_b32_e32 v95, 0
	v_cndmask_b32_e64 v96, v164, v98, s[2:3]
	v_cndmask_b32_e64 v82, v94, v88, s[2:3]
	v_mov_b32_dpp v95, v80 row_ror:8 row_mask:0xf bank_mask:0xf
	v_cndmask_b32_e64 v88, v98, v158, s[2:3]
	v_ashrrev_i32_e32 v97, 31, v96
	v_cndmask_b32_e64 v83, v95, v89, s[2:3]
	v_ashrrev_i32_e32 v89, 31, v88
	v_pk_mul_f32 v[68:69], v[68:69], v[170:171] op_sel_hi:[1,0]
	v_pk_mul_f32 v[76:77], v[76:77], v[170:171] op_sel_hi:[1,0]
	v_lshlrev_b64 v[96:97], 10, v[96:97]
	v_lshlrev_b64 v[88:89], 10, v[88:89]
	v_pk_mul_f32 v[64:65], v[64:65], v[170:171] op_sel_hi:[1,0]
	v_pk_mul_f32 v[70:71], v[70:71], v[170:171] op_sel_hi:[1,0]
	v_pk_mul_f32 v[78:79], v[78:79], v[170:171] op_sel_hi:[1,0]
	v_cvt_pk_bf16_f32 v76, v76, v77
	v_pk_mul_f32 v[74:75], v[74:75], v[170:171] op_sel_hi:[1,0]
	v_pk_mul_f32 v[72:73], v[72:73], v[170:171] op_sel_hi:[1,0]
	v_cvt_pk_bf16_f32 v68, v68, v69
	v_lshl_add_u64 v[96:97], s[38:39], 0, v[96:97]
	v_lshl_add_u64 v[88:89], s[38:39], 0, v[88:89]
	v_pk_mul_f32 v[66:67], v[66:67], v[170:171] op_sel_hi:[1,0]
	v_cvt_pk_bf16_f32 v77, v78, v79
	v_cvt_pk_bf16_f32 v72, v72, v73
	v_cvt_pk_bf16_f32 v73, v74, v75
	v_cvt_pk_bf16_f32 v69, v70, v71
	v_cvt_pk_bf16_f32 v70, v64, v65
	v_cndmask_b32_e64 v64, v76, v68, s[2:3]
	v_mov_b32_e32 v74, 0
	v_cndmask_b32_e64 v103, v103, v111, s[2:3]
	v_cndmask_b32_e64 v102, v102, v110, s[2:3]
	v_cndmask_b32_e64 v101, v101, v107, s[2:3]
	v_cndmask_b32_e64 v100, v100, v106, s[2:3]
	v_lshl_add_u64 v[96:97], v[96:97], 0, v[112:113]
	v_cndmask_b32_e64 v81, v91, v93, s[2:3]
	v_cndmask_b32_e64 v80, v90, v92, s[2:3]
	v_lshl_add_u64 v[88:89], v[88:89], 0, v[112:113]
	v_cvt_pk_bf16_f32 v71, v66, v67
	v_mov_b32_dpp v74, v64 row_ror:8 row_mask:0xf bank_mask:0xf
	v_cndmask_b32_e64 v64, v77, v69, s[2:3]
	v_mov_b32_e32 v75, 0
	v_cndmask_b32_e64 v65, v72, v70, s[2:3]
	v_mov_b32_e32 v78, 0
	global_store_dwordx4 v[96:97], v[100:103], off
	global_store_dwordx4 v[88:89], v[80:83], off
	v_mov_b32_dpp v75, v64 row_ror:8 row_mask:0xf bank_mask:0xf
	v_cndmask_b32_e64 v64, v73, v71, s[2:3]
	v_add_u32_e32 v82, 40, v146
	v_mov_b32_dpp v78, v65 row_ror:8 row_mask:0xf bank_mask:0xf
	v_mov_b32_e32 v79, 0
	v_cndmask_b32_e64 v80, v158, v82, s[2:3]
	v_cndmask_b32_e64 v66, v78, v72, s[2:3]
	v_mov_b32_dpp v79, v64 row_ror:8 row_mask:0xf bank_mask:0xf
	v_cndmask_b32_e64 v72, v82, v156, s[2:3]
	v_ashrrev_i32_e32 v81, 31, v80
	v_cndmask_b32_e64 v67, v79, v73, s[2:3]
	v_ashrrev_i32_e32 v73, 31, v72
	v_pk_mul_f32 v[48:49], v[48:49], v[168:169] op_sel_hi:[1,0]
	v_pk_mul_f32 v[54:55], v[54:55], v[168:169] op_sel_hi:[1,0]
	v_pk_mul_f32 v[52:53], v[52:53], v[168:169] op_sel_hi:[1,0]
	v_pk_mul_f32 v[60:61], v[60:61], v[168:169] op_sel_hi:[1,0]
	v_pk_mul_f32 v[56:57], v[56:57], v[168:169] op_sel_hi:[1,0]
	v_lshlrev_b64 v[80:81], 10, v[80:81]
	v_lshlrev_b64 v[72:73], 10, v[72:73]
	v_pk_mul_f32 v[62:63], v[62:63], v[168:169] op_sel_hi:[1,0]
	v_cvt_pk_bf16_f32 v60, v60, v61
	v_pk_mul_f32 v[58:59], v[58:59], v[168:169] op_sel_hi:[1,0]
	v_cvt_pk_bf16_f32 v56, v56, v57
	v_cvt_pk_bf16_f32 v52, v52, v53
	v_cvt_pk_bf16_f32 v53, v54, v55
	v_cvt_pk_bf16_f32 v54, v48, v49
	v_lshl_add_u64 v[80:81], s[38:39], 0, v[80:81]
	v_lshl_add_u64 v[72:73], s[38:39], 0, v[72:73]
	v_pk_mul_f32 v[50:51], v[50:51], v[168:169] op_sel_hi:[1,0]
	v_cvt_pk_bf16_f32 v61, v62, v63
	v_cvt_pk_bf16_f32 v57, v58, v59
	v_cndmask_b32_e64 v48, v60, v52, s[2:3]
	v_mov_b32_e32 v58, 0
	v_cndmask_b32_e64 v49, v56, v54, s[2:3]
	v_mov_b32_e32 v62, 0
	v_cndmask_b32_e64 v87, v87, v95, s[2:3]
	v_cndmask_b32_e64 v86, v86, v94, s[2:3]
	v_cndmask_b32_e64 v85, v85, v91, s[2:3]
	v_cndmask_b32_e64 v84, v84, v90, s[2:3]
	v_lshl_add_u64 v[80:81], v[80:81], 0, v[112:113]
	v_cndmask_b32_e64 v65, v75, v77, s[2:3]
	v_cndmask_b32_e64 v64, v74, v76, s[2:3]
	v_lshl_add_u64 v[72:73], v[72:73], 0, v[112:113]
	v_cvt_pk_bf16_f32 v55, v50, v51
	v_mov_b32_dpp v58, v48 row_ror:8 row_mask:0xf bank_mask:0xf
	v_cndmask_b32_e64 v48, v61, v53, s[2:3]
	v_mov_b32_e32 v59, 0
	v_mov_b32_dpp v62, v49 row_ror:8 row_mask:0xf bank_mask:0xf
	global_store_dwordx4 v[80:81], v[84:87], off
	global_store_dwordx4 v[72:73], v[64:67], off
	v_mov_b32_dpp v59, v48 row_ror:8 row_mask:0xf bank_mask:0xf
	v_cndmask_b32_e64 v48, v57, v55, s[2:3]
	v_add_u32_e32 v64, 56, v146
	v_mov_b32_e32 v63, 0
	v_cndmask_b32_e64 v50, v62, v56, s[2:3]
	v_add_u32_e32 v56, 0x78, v146
	v_cndmask_b32_e64 v64, v156, v64, s[2:3]
	v_mov_b32_dpp v63, v48 row_ror:8 row_mask:0xf bank_mask:0xf
	v_cndmask_b32_e64 v56, v56, v154, s[2:3]
	v_ashrrev_i32_e32 v65, 31, v64
	v_cndmask_b32_e64 v51, v63, v57, s[2:3]
	v_ashrrev_i32_e32 v57, 31, v56
	v_pk_mul_f32 v[36:37], v[36:37], v[166:167] op_sel_hi:[1,0]
	v_pk_mul_f32 v[44:45], v[44:45], v[166:167] op_sel_hi:[1,0]
	v_lshlrev_b64 v[64:65], 10, v[64:65]
	v_lshlrev_b64 v[56:57], 10, v[56:57]
	v_pk_mul_f32 v[32:33], v[32:33], v[166:167] op_sel_hi:[1,0]
	v_pk_mul_f32 v[38:39], v[38:39], v[166:167] op_sel_hi:[1,0]
	v_pk_mul_f32 v[46:47], v[46:47], v[166:167] op_sel_hi:[1,0]
	v_cvt_pk_bf16_f32 v44, v44, v45
	v_pk_mul_f32 v[42:43], v[42:43], v[166:167] op_sel_hi:[1,0]
	v_pk_mul_f32 v[40:41], v[40:41], v[166:167] op_sel_hi:[1,0]
	v_cvt_pk_bf16_f32 v36, v36, v37
	v_lshl_add_u64 v[64:65], s[38:39], 0, v[64:65]
	v_lshl_add_u64 v[56:57], s[38:39], 0, v[56:57]
	v_pk_mul_f32 v[34:35], v[34:35], v[166:167] op_sel_hi:[1,0]
	v_cvt_pk_bf16_f32 v45, v46, v47
	v_cvt_pk_bf16_f32 v40, v40, v41
	v_cvt_pk_bf16_f32 v41, v42, v43
	v_cvt_pk_bf16_f32 v37, v38, v39
	v_cvt_pk_bf16_f32 v38, v32, v33
	v_cndmask_b32_e64 v32, v44, v36, s[2:3]
	v_mov_b32_e32 v42, 0
	v_cndmask_b32_e64 v71, v71, v79, s[2:3]
	v_cndmask_b32_e64 v70, v70, v78, s[2:3]
	v_cndmask_b32_e64 v69, v69, v75, s[2:3]
	v_cndmask_b32_e64 v68, v68, v74, s[2:3]
	v_lshl_add_u64 v[64:65], v[64:65], 0, v[112:113]
	v_cndmask_b32_e64 v49, v59, v61, s[2:3]
	v_cndmask_b32_e64 v48, v58, v60, s[2:3]
	v_lshl_add_u64 v[56:57], v[56:57], 0, v[112:113]
	v_cvt_pk_bf16_f32 v39, v34, v35
	v_mov_b32_dpp v42, v32 row_ror:8 row_mask:0xf bank_mask:0xf
	v_cndmask_b32_e64 v32, v45, v37, s[2:3]
	v_mov_b32_e32 v43, 0
	v_cndmask_b32_e64 v33, v40, v38, s[2:3]
	v_mov_b32_e32 v46, 0
	global_store_dwordx4 v[64:65], v[68:71], off
	global_store_dwordx4 v[56:57], v[48:51], off
	v_mov_b32_dpp v43, v32 row_ror:8 row_mask:0xf bank_mask:0xf
	v_cndmask_b32_e64 v32, v41, v39, s[2:3]
	v_add_u32_e32 v50, 0x88, v146
	v_mov_b32_dpp v46, v33 row_ror:8 row_mask:0xf bank_mask:0xf
	v_mov_b32_e32 v47, 0
	v_cndmask_b32_e64 v34, v46, v40, s[2:3]
	v_cndmask_b32_e64 v40, v50, v152, s[2:3]
	v_mov_b32_dpp v47, v32 row_ror:8 row_mask:0xf bank_mask:0xf
	v_cndmask_b32_e64 v35, v47, v41, s[2:3]
	v_ashrrev_i32_e32 v41, 31, v40
	v_pk_mul_f32 v[20:21], v[20:21], v[162:163] op_sel_hi:[1,0]
	v_pk_mul_f32 v[28:29], v[28:29], v[162:163] op_sel_hi:[1,0]
	v_lshlrev_b64 v[40:41], 10, v[40:41]
	v_pk_mul_f32 v[16:17], v[16:17], v[162:163] op_sel_hi:[1,0]
	v_pk_mul_f32 v[22:23], v[22:23], v[162:163] op_sel_hi:[1,0]
	v_pk_mul_f32 v[30:31], v[30:31], v[162:163] op_sel_hi:[1,0]
	v_cvt_pk_bf16_f32 v28, v28, v29
	v_pk_mul_f32 v[26:27], v[26:27], v[162:163] op_sel_hi:[1,0]
	v_pk_mul_f32 v[24:25], v[24:25], v[162:163] op_sel_hi:[1,0]
	v_cvt_pk_bf16_f32 v20, v20, v21
	v_lshl_add_u64 v[40:41], s[38:39], 0, v[40:41]
	v_pk_mul_f32 v[18:19], v[18:19], v[162:163] op_sel_hi:[1,0]
	v_cvt_pk_bf16_f32 v29, v30, v31
	v_cvt_pk_bf16_f32 v24, v24, v25
	v_cvt_pk_bf16_f32 v25, v26, v27
	v_cvt_pk_bf16_f32 v21, v22, v23
	v_cvt_pk_bf16_f32 v22, v16, v17
	v_cndmask_b32_e64 v16, v28, v20, s[2:3]
	v_mov_b32_e32 v26, 0
	v_cndmask_b32_e64 v33, v43, v45, s[2:3]
	v_cndmask_b32_e64 v32, v42, v44, s[2:3]
	v_lshl_add_u64 v[40:41], v[40:41], 0, v[112:113]
	v_cvt_pk_bf16_f32 v23, v18, v19
	v_mov_b32_dpp v26, v16 row_ror:8 row_mask:0xf bank_mask:0xf
	v_cndmask_b32_e64 v16, v29, v21, s[2:3]
	v_mov_b32_e32 v27, 0
	v_cndmask_b32_e64 v17, v24, v22, s[2:3]
	v_mov_b32_e32 v30, 0
	global_store_dwordx4 v[40:41], v[32:35], off
	v_mov_b32_dpp v27, v16 row_ror:8 row_mask:0xf bank_mask:0xf
	v_cndmask_b32_e64 v16, v25, v23, s[2:3]
	v_add_u32_e32 v34, 0x98, v146
	v_mov_b32_dpp v30, v17 row_ror:8 row_mask:0xf bank_mask:0xf
	v_mov_b32_e32 v31, 0
	v_cndmask_b32_e64 v18, v30, v24, s[2:3]
	v_cndmask_b32_e64 v24, v34, v148, s[2:3]
	v_mov_b32_dpp v31, v16 row_ror:8 row_mask:0xf bank_mask:0xf
	v_cndmask_b32_e64 v19, v31, v25, s[2:3]
	v_ashrrev_i32_e32 v25, 31, v24
	v_lshlrev_b64 v[24:25], 10, v[24:25]
	v_lshl_add_u64 v[24:25], s[38:39], 0, v[24:25]
	v_cndmask_b32_e64 v17, v27, v29, s[2:3]
	v_cndmask_b32_e64 v16, v26, v28, s[2:3]
	v_lshl_add_u64 v[24:25], v[24:25], 0, v[112:113]
	global_store_dwordx4 v[24:25], v[16:19], off
	v_pk_mul_f32 v[4:5], v[4:5], v[160:161] op_sel_hi:[1,0]
	v_pk_mul_f32 v[12:13], v[12:13], v[160:161] op_sel_hi:[1,0]
	v_add_u32_e32 v18, 0xa8, v146
	v_cndmask_b32_e64 v16, v148, v18, s[2:3]
	v_ashrrev_i32_e32 v17, 31, v16
	v_pk_mul_f32 v[10:11], v[10:11], v[160:161] op_sel_hi:[1,0]
	v_pk_mul_f32 v[8:9], v[8:9], v[160:161] op_sel_hi:[1,0]
	v_lshlrev_b64 v[16:17], 10, v[16:17]
	v_pk_mul_f32 v[0:1], v[0:1], v[160:161] op_sel_hi:[1,0]
	v_pk_mul_f32 v[6:7], v[6:7], v[160:161] op_sel_hi:[1,0]
	v_pk_mul_f32 v[14:15], v[14:15], v[160:161] op_sel_hi:[1,0]
	v_cvt_pk_bf16_f32 v12, v12, v13
	v_cvt_pk_bf16_f32 v8, v8, v9
	v_cvt_pk_bf16_f32 v9, v10, v11
	v_cvt_pk_bf16_f32 v10, v4, v5
	v_lshl_add_u64 v[16:17], s[38:39], 0, v[16:17]
	v_pk_mul_f32 v[2:3], v[2:3], v[160:161] op_sel_hi:[1,0]
	v_cvt_pk_bf16_f32 v13, v14, v15
	v_cvt_pk_bf16_f32 v6, v6, v7
	v_cvt_pk_bf16_f32 v7, v0, v1
	v_cndmask_b32_e64 v0, v12, v10, s[2:3]
	v_mov_b32_e32 v14, 0
	v_cndmask_b32_e64 v4, v18, v150, s[2:3]
	v_cndmask_b32_e64 v23, v23, v31, s[2:3]
	v_cndmask_b32_e64 v22, v22, v30, s[2:3]
	v_cndmask_b32_e64 v21, v21, v27, s[2:3]
	v_cndmask_b32_e64 v20, v20, v26, s[2:3]
	v_lshl_add_u64 v[16:17], v[16:17], 0, v[112:113]
	v_cvt_pk_bf16_f32 v11, v2, v3
	v_mov_b32_dpp v14, v0 row_ror:8 row_mask:0xf bank_mask:0xf
	v_cndmask_b32_e64 v0, v13, v6, s[2:3]
	v_mov_b32_e32 v15, 0
	v_ashrrev_i32_e32 v5, 31, v4
	global_store_dwordx4 v[16:17], v[20:23], off
	v_mov_b32_dpp v15, v0 row_ror:8 row_mask:0xf bank_mask:0xf
	v_cndmask_b32_e64 v0, v9, v11, s[2:3]
	v_cndmask_b32_e64 v1, v8, v7, s[2:3]
	v_mov_b32_e32 v16, 0
	v_mov_b32_e32 v17, 0
	v_lshlrev_b64 v[4:5], 10, v[4:5]
	v_mov_b32_dpp v16, v1 row_ror:8 row_mask:0xf bank_mask:0xf
	v_mov_b32_dpp v17, v0 row_ror:8 row_mask:0xf bank_mask:0xf
	v_lshl_add_u64 v[4:5], s[38:39], 0, v[4:5]
	v_cndmask_b32_e64 v3, v17, v9, s[2:3]
	v_cndmask_b32_e64 v2, v16, v8, s[2:3]
	v_cndmask_b32_e64 v1, v15, v13, s[2:3]
	v_cndmask_b32_e64 v0, v14, v12, s[2:3]
	v_lshl_add_u64 v[4:5], v[4:5], 0, v[112:113]
	global_store_dwordx4 v[4:5], v[0:3], off
	v_cndmask_b32_e64 v48, v154, v50, s[2:3]
	v_cndmask_b32_e64 v32, v152, v34, s[2:3]
	v_add_u32_e32 v0, 0xb8, v146
	v_cndmask_b32_e64 v0, v150, v0, s[2:3]
	v_ashrrev_i32_e32 v49, 31, v48
	v_ashrrev_i32_e32 v33, 31, v32
	v_ashrrev_i32_e32 v1, 31, v0
	v_lshlrev_b64 v[48:49], 10, v[48:49]
	v_lshlrev_b64 v[32:33], 10, v[32:33]
	v_lshlrev_b64 v[0:1], 10, v[0:1]
	v_lshl_add_u64 v[48:49], s[38:39], 0, v[48:49]
	v_lshl_add_u64 v[32:33], s[38:39], 0, v[32:33]
	v_lshl_add_u64 v[0:1], s[38:39], 0, v[0:1]
	v_cndmask_b32_e64 v55, v55, v63, s[2:3]
	v_cndmask_b32_e64 v54, v54, v62, s[2:3]
	v_cndmask_b32_e64 v53, v53, v59, s[2:3]
	v_cndmask_b32_e64 v52, v52, v58, s[2:3]
	v_lshl_add_u64 v[48:49], v[48:49], 0, v[112:113]
	v_cndmask_b32_e64 v39, v39, v47, s[2:3]
	v_cndmask_b32_e64 v38, v38, v46, s[2:3]
	v_cndmask_b32_e64 v37, v37, v43, s[2:3]
	v_cndmask_b32_e64 v36, v36, v42, s[2:3]
	v_lshl_add_u64 v[32:33], v[32:33], 0, v[112:113]
	v_lshl_add_u64 v[4:5], v[0:1], 0, v[112:113]
	v_cndmask_b32_e64 v3, v11, v17, s[2:3]
	v_cndmask_b32_e64 v2, v7, v16, s[2:3]
	v_cndmask_b32_e64 v1, v6, v15, s[2:3]
	v_cndmask_b32_e64 v0, v10, v14, s[2:3]
	s_and_b64 vcc, exec, s[4:5]
	s_mov_b32 s66, s36
	s_mov_b32 s6, s44
	s_mov_b64 s[50:51], s[48:49]
	s_mov_b64 s[52:53], s[46:47]
	global_store_dwordx4 v[48:49], v[52:55], off
	global_store_dwordx4 v[32:33], v[36:39], off
	global_store_dwordx4 v[4:5], v[0:3], off
	s_cbranch_vccz .LBB0_897
	s_waitcnt vmcnt(0)
	s_cmpk_gt_u32 s11, 0xff
	s_cbranch_scc1 .LBB0_908
	s_barrier

.LBB0_997:
	ds_read_b128 v[128:131], v164
	ds_read_b128 v[132:135], v164 offset:1024
	ds_read_b128 v[152:155], v164 offset:2048
	ds_read_b128 v[156:159], v164 offset:3072
	s_add_u32 s28, s48, 0xfffe0080
	s_addc_u32 s29, s49, -1
	s_cmp_eq_u32 s79, 4
	s_cselect_b32 s53, s9, s29
	s_cselect_b32 s52, s41, s28
	s_cselect_b32 s51, s39, s78
	s_cselect_b32 s50, s76, s77
	v_lshl_add_u64 v[204:205], s[48:49], 0, v[144:145]
	s_add_i32 m0, s55, 0xc000
	ds_read_b128 v[168:171], v165
	ds_read_b128 v[172:175], v165 offset:1024
	ds_read_b128 v[176:179], v165 offset:2048
	ds_read_b128 v[180:183], v165 offset:3072
	ds_read_b128 v[184:187], v165 offset:4096
	ds_read_b128 v[188:191], v165 offset:5120
	ds_read_b128 v[196:199], v165 offset:6144
	ds_read_b128 v[200:203], v165 offset:7168
	global_load_lds_dwordx4 v[204:205], off
	v_lshl_add_u64 v[204:205], s[48:49], 0, v[146:147]
	s_add_i32 m0, s55, 0xe000
	s_nop 0
	global_load_lds_dwordx4 v[204:205], off
	s_waitcnt lgkmcnt(8)
	s_barrier
	s_waitcnt lgkmcnt(7)
	v_mfma_f32_16x16x32_bf16 v[124:127], v[128:131], v[168:171], v[124:127]
	v_mfma_f32_16x16x32_bf16 v[120:123], v[152:155], v[168:171], v[120:123]
	s_waitcnt lgkmcnt(5)
	v_mfma_f32_16x16x32_bf16 v[108:111], v[128:131], v[176:179], v[108:111]
	v_mfma_f32_16x16x32_bf16 v[104:107], v[152:155], v[176:179], v[104:107]
	s_waitcnt lgkmcnt(3)
	v_mfma_f32_16x16x32_bf16 v[92:95], v[128:131], v[184:187], v[92:95]
	v_mfma_f32_16x16x32_bf16 v[88:91], v[152:155], v[184:187], v[88:91]
	s_waitcnt lgkmcnt(1)
	v_mfma_f32_16x16x32_bf16 v[76:79], v[128:131], v[196:199], v[76:79]
	v_mfma_f32_16x16x32_bf16 v[72:75], v[152:155], v[196:199], v[72:75]
	v_mfma_f32_16x16x32_bf16 v[124:127], v[132:135], v[172:175], v[124:127]
	v_mfma_f32_16x16x32_bf16 v[120:123], v[156:159], v[172:175], v[120:123]
	v_mfma_f32_16x16x32_bf16 v[108:111], v[132:135], v[180:183], v[108:111]
	v_mfma_f32_16x16x32_bf16 v[104:107], v[156:159], v[180:183], v[104:107]
	v_mfma_f32_16x16x32_bf16 v[92:95], v[132:135], v[188:191], v[92:95]
	v_mfma_f32_16x16x32_bf16 v[88:91], v[156:159], v[188:191], v[88:91]
	s_waitcnt lgkmcnt(0)
	v_mfma_f32_16x16x32_bf16 v[76:79], v[132:135], v[200:203], v[76:79]
	v_mfma_f32_16x16x32_bf16 v[72:75], v[156:159], v[200:203], v[72:75]
	s_barrier
	s_add_i32 s28, s65, s54
	v_lshl_add_u64 v[220:221], s[50:51], 0, v[138:139]
	s_mov_b32 m0, s28
	ds_read_b128 v[204:207], v166
	ds_read_b128 v[208:211], v166 offset:1024
	ds_read_b128 v[212:215], v166 offset:2048
	ds_read_b128 v[216:219], v166 offset:3072
	global_load_lds_dwordx4 v[220:221], off
	v_lshl_add_u64 v[222:223], s[50:51], 0, v[142:143]
	s_add_i32 m0, s28, 0x2000
	s_nop 0
	global_load_lds_dwordx4 v[222:223], off
	s_barrier
	s_waitcnt lgkmcnt(3)
	v_mfma_f32_16x16x32_bf16 v[116:119], v[204:207], v[168:171], v[116:119]
	s_waitcnt lgkmcnt(1)
	v_mfma_f32_16x16x32_bf16 v[112:115], v[212:215], v[168:171], v[112:115]
	v_mfma_f32_16x16x32_bf16 v[100:103], v[204:207], v[176:179], v[100:103]
	v_mfma_f32_16x16x32_bf16 v[96:99], v[212:215], v[176:179], v[96:99]
	v_mfma_f32_16x16x32_bf16 v[84:87], v[204:207], v[184:187], v[84:87]
	v_mfma_f32_16x16x32_bf16 v[80:83], v[212:215], v[184:187], v[80:83]
	v_mfma_f32_16x16x32_bf16 v[68:71], v[204:207], v[196:199], v[68:71]
	v_mfma_f32_16x16x32_bf16 v[64:67], v[212:215], v[196:199], v[64:67]
	v_mfma_f32_16x16x32_bf16 v[116:119], v[208:211], v[172:175], v[116:119]
	s_waitcnt lgkmcnt(0)
	v_mfma_f32_16x16x32_bf16 v[112:115], v[216:219], v[172:175], v[112:115]
	v_mfma_f32_16x16x32_bf16 v[100:103], v[208:211], v[180:183], v[100:103]
	v_mfma_f32_16x16x32_bf16 v[96:99], v[216:219], v[180:183], v[96:99]
	v_mfma_f32_16x16x32_bf16 v[84:87], v[208:211], v[188:191], v[84:87]
	v_mfma_f32_16x16x32_bf16 v[80:83], v[216:219], v[188:191], v[80:83]
	v_mfma_f32_16x16x32_bf16 v[68:71], v[208:211], v[200:203], v[68:71]
	v_mfma_f32_16x16x32_bf16 v[64:67], v[216:219], v[200:203], v[64:67]
	s_mov_b32 m0, s55
	v_lshl_add_u64 v[224:225], s[52:53], 0, v[136:137]
	s_barrier
	ds_read_b128 v[168:171], v165 offset:16384
	ds_read_b128 v[172:175], v165 offset:17408
	ds_read_b128 v[176:179], v165 offset:18432
	ds_read_b128 v[180:183], v165 offset:19456
	ds_read_b128 v[184:187], v165 offset:20480
	ds_read_b128 v[188:191], v165 offset:21504
	ds_read_b128 v[196:199], v165 offset:22528
	ds_read_b128 v[200:203], v165 offset:23552
	global_load_lds_dwordx4 v[224:225], off
	v_lshl_add_u64 v[226:227], s[52:53], 0, v[140:141]
	s_mov_b32 m0, s56
	s_nop 0
	global_load_lds_dwordx4 v[226:227], off
	s_barrier
	s_waitcnt lgkmcnt(7)
	v_mfma_f32_16x16x32_bf16 v[60:63], v[128:131], v[168:171], v[60:63]
	v_mfma_f32_16x16x32_bf16 v[56:59], v[152:155], v[168:171], v[56:59]
	s_waitcnt lgkmcnt(5)
	v_mfma_f32_16x16x32_bf16 v[44:47], v[128:131], v[176:179], v[44:47]
	v_mfma_f32_16x16x32_bf16 v[40:43], v[152:155], v[176:179], v[40:43]
	s_waitcnt lgkmcnt(3)
	v_mfma_f32_16x16x32_bf16 v[28:31], v[128:131], v[184:187], v[28:31]
	v_mfma_f32_16x16x32_bf16 v[24:27], v[152:155], v[184:187], v[24:27]
	s_waitcnt lgkmcnt(1)
	v_mfma_f32_16x16x32_bf16 v[12:15], v[128:131], v[196:199], v[12:15]
	v_mfma_f32_16x16x32_bf16 v[8:11], v[152:155], v[196:199], v[8:11]
	v_mfma_f32_16x16x32_bf16 v[60:63], v[132:135], v[172:175], v[60:63]
	v_mfma_f32_16x16x32_bf16 v[56:59], v[156:159], v[172:175], v[56:59]
	v_mfma_f32_16x16x32_bf16 v[44:47], v[132:135], v[180:183], v[44:47]
	v_mfma_f32_16x16x32_bf16 v[40:43], v[156:159], v[180:183], v[40:43]
	v_mfma_f32_16x16x32_bf16 v[28:31], v[132:135], v[188:191], v[28:31]
	v_mfma_f32_16x16x32_bf16 v[24:27], v[156:159], v[188:191], v[24:27]
	s_waitcnt lgkmcnt(0)
	v_mfma_f32_16x16x32_bf16 v[12:15], v[132:135], v[200:203], v[12:15]
	v_mfma_f32_16x16x32_bf16 v[8:11], v[156:159], v[200:203], v[8:11]
	s_barrier
	s_add_u32 s80, s50, 0x8000
	s_addc_u32 s81, s51, 0
	s_add_i32 s28, s66, s54
	v_lshl_add_u64 v[128:129], s[80:81], 0, v[138:139]
	s_mov_b32 m0, s28
	s_nop 0
	global_load_lds_dwordx4 v[128:129], off
	v_lshl_add_u64 v[128:129], s[80:81], 0, v[142:143]
	s_add_i32 m0, s28, 0x2000
	s_nop 0
	global_load_lds_dwordx4 v[128:129], off
	s_waitcnt vmcnt(6)
	s_barrier
	v_mfma_f32_16x16x32_bf16 v[52:55], v[204:207], v[168:171], v[52:55]
	v_mfma_f32_16x16x32_bf16 v[48:51], v[212:215], v[168:171], v[48:51]
	v_mfma_f32_16x16x32_bf16 v[36:39], v[204:207], v[176:179], v[36:39]
	v_mfma_f32_16x16x32_bf16 v[32:35], v[212:215], v[176:179], v[32:35]
	v_mfma_f32_16x16x32_bf16 v[20:23], v[204:207], v[184:187], v[20:23]
	v_mfma_f32_16x16x32_bf16 v[16:19], v[212:215], v[184:187], v[16:19]
	v_mfma_f32_16x16x32_bf16 v[4:7], v[204:207], v[196:199], v[4:7]
	v_mfma_f32_16x16x32_bf16 v[0:3], v[212:215], v[196:199], v[0:3]
	v_mfma_f32_16x16x32_bf16 v[52:55], v[208:211], v[172:175], v[52:55]
	v_mfma_f32_16x16x32_bf16 v[48:51], v[216:219], v[172:175], v[48:51]
	v_mfma_f32_16x16x32_bf16 v[36:39], v[208:211], v[180:183], v[36:39]
	v_mfma_f32_16x16x32_bf16 v[32:35], v[216:219], v[180:183], v[32:35]
	v_mfma_f32_16x16x32_bf16 v[20:23], v[208:211], v[188:191], v[20:23]
	v_mfma_f32_16x16x32_bf16 v[16:19], v[216:219], v[188:191], v[16:19]
	v_mfma_f32_16x16x32_bf16 v[4:7], v[208:211], v[200:203], v[4:7]
	v_mfma_f32_16x16x32_bf16 v[0:3], v[216:219], v[200:203], v[0:3]
	s_add_i32 s28, 0, 0x18000
	v_add_u32_e32 v156, s28, v161
	s_barrier
	ds_read_b128 v[128:131], v156
	ds_read_b128 v[132:135], v156 offset:1024
	ds_read_b128 v[152:155], v156 offset:2048
	ds_read_b128 v[156:159], v156 offset:3072
	s_add_u32 s52, s52, 0x20000
	s_addc_u32 s53, s53, 0
	s_mov_b32 m0, s57
	v_lshl_add_u64 v[204:205], s[52:53], 0, v[136:137]
	ds_read_b128 v[168:171], v165 offset:32768
	ds_read_b128 v[172:175], v165 offset:33792
	ds_read_b128 v[176:179], v165 offset:34816
	ds_read_b128 v[180:183], v165 offset:35840
	ds_read_b128 v[184:187], v165 offset:36864
	ds_read_b128 v[188:191], v165 offset:37888
	ds_read_b128 v[196:199], v165 offset:38912
	ds_read_b128 v[200:203], v165 offset:39936
	global_load_lds_dwordx4 v[204:205], off
	v_lshl_add_u64 v[204:205], s[52:53], 0, v[140:141]
	s_mov_b32 m0, s58
	s_nop 0
	global_load_lds_dwordx4 v[204:205], off
	s_waitcnt lgkmcnt(8)
	s_barrier
	s_waitcnt lgkmcnt(7)
	v_mfma_f32_16x16x32_bf16 v[124:127], v[128:131], v[168:171], v[124:127]
	v_mfma_f32_16x16x32_bf16 v[120:123], v[152:155], v[168:171], v[120:123]
	s_waitcnt lgkmcnt(5)
	v_mfma_f32_16x16x32_bf16 v[108:111], v[128:131], v[176:179], v[108:111]
	v_mfma_f32_16x16x32_bf16 v[104:107], v[152:155], v[176:179], v[104:107]
	s_waitcnt lgkmcnt(3)
	v_mfma_f32_16x16x32_bf16 v[92:95], v[128:131], v[184:187], v[92:95]
	v_mfma_f32_16x16x32_bf16 v[88:91], v[152:155], v[184:187], v[88:91]
	s_waitcnt lgkmcnt(1)
	v_mfma_f32_16x16x32_bf16 v[76:79], v[128:131], v[196:199], v[76:79]
	v_mfma_f32_16x16x32_bf16 v[72:75], v[152:155], v[196:199], v[72:75]
	v_mfma_f32_16x16x32_bf16 v[124:127], v[132:135], v[172:175], v[124:127]
	v_mfma_f32_16x16x32_bf16 v[120:123], v[156:159], v[172:175], v[120:123]
	v_mfma_f32_16x16x32_bf16 v[108:111], v[132:135], v[180:183], v[108:111]
	v_mfma_f32_16x16x32_bf16 v[104:107], v[156:159], v[180:183], v[104:107]
	v_mfma_f32_16x16x32_bf16 v[92:95], v[132:135], v[188:191], v[92:95]
	v_mfma_f32_16x16x32_bf16 v[88:91], v[156:159], v[188:191], v[88:91]
	s_waitcnt lgkmcnt(0)
	v_mfma_f32_16x16x32_bf16 v[76:79], v[132:135], v[200:203], v[76:79]
	v_mfma_f32_16x16x32_bf16 v[72:75], v[156:159], v[200:203], v[72:75]
	s_barrier
	s_add_i32 s29, 0, 0x1c000
	s_add_i32 s28, s28, s54
	v_add_u32_e32 v195, s29, v161
	v_lshl_add_u64 v[220:221], v[220:221], 0, s[36:37]
	s_mov_b32 m0, s28
	ds_read_b128 v[204:207], v195
	ds_read_b128 v[208:211], v195 offset:1024
	ds_read_b128 v[212:215], v195 offset:2048
	ds_read_b128 v[216:219], v195 offset:3072
	global_load_lds_dwordx4 v[220:221], off
	v_lshl_add_u64 v[220:221], v[222:223], 0, s[36:37]
	s_add_i32 m0, s28, 0x2000
	s_nop 0
	global_load_lds_dwordx4 v[220:221], off
	s_barrier
	s_waitcnt lgkmcnt(3)
	v_mfma_f32_16x16x32_bf16 v[116:119], v[204:207], v[168:171], v[116:119]
	s_waitcnt lgkmcnt(1)
	v_mfma_f32_16x16x32_bf16 v[112:115], v[212:215], v[168:171], v[112:115]
	v_mfma_f32_16x16x32_bf16 v[100:103], v[204:207], v[176:179], v[100:103]
	v_mfma_f32_16x16x32_bf16 v[96:99], v[212:215], v[176:179], v[96:99]
	v_mfma_f32_16x16x32_bf16 v[84:87], v[204:207], v[184:187], v[84:87]
	v_mfma_f32_16x16x32_bf16 v[80:83], v[212:215], v[184:187], v[80:83]
	v_mfma_f32_16x16x32_bf16 v[68:71], v[204:207], v[196:199], v[68:71]
	v_mfma_f32_16x16x32_bf16 v[64:67], v[212:215], v[196:199], v[64:67]
	v_mfma_f32_16x16x32_bf16 v[116:119], v[208:211], v[172:175], v[116:119]
	s_waitcnt lgkmcnt(0)
	v_mfma_f32_16x16x32_bf16 v[112:115], v[216:219], v[172:175], v[112:115]
	v_mfma_f32_16x16x32_bf16 v[100:103], v[208:211], v[180:183], v[100:103]
	v_mfma_f32_16x16x32_bf16 v[96:99], v[216:219], v[180:183], v[96:99]
	v_mfma_f32_16x16x32_bf16 v[84:87], v[208:211], v[188:191], v[84:87]
	v_mfma_f32_16x16x32_bf16 v[80:83], v[216:219], v[188:191], v[80:83]
	v_mfma_f32_16x16x32_bf16 v[68:71], v[208:211], v[200:203], v[68:71]
	v_mfma_f32_16x16x32_bf16 v[64:67], v[216:219], v[200:203], v[64:67]
	s_mov_b32 m0, s62
	v_lshl_add_u64 v[220:221], v[224:225], 0, s[36:37]
	s_barrier
	ds_read_b128 v[168:171], v165 offset:49152
	ds_read_b128 v[172:175], v165 offset:50176
	ds_read_b128 v[176:179], v165 offset:51200
	ds_read_b128 v[180:183], v165 offset:52224
	ds_read_b128 v[184:187], v165 offset:53248
	ds_read_b128 v[188:191], v165 offset:54272
	ds_read_b128 v[196:199], v165 offset:55296
	ds_read_b128 v[200:203], v165 offset:56320
	global_load_lds_dwordx4 v[220:221], off
	v_lshl_add_u64 v[220:221], v[226:227], 0, s[36:37]
	s_mov_b32 m0, s63
	s_nop 0
	global_load_lds_dwordx4 v[220:221], off
	s_barrier
	s_waitcnt lgkmcnt(7)
	v_mfma_f32_16x16x32_bf16 v[60:63], v[128:131], v[168:171], v[60:63]
	v_mfma_f32_16x16x32_bf16 v[56:59], v[152:155], v[168:171], v[56:59]
	s_waitcnt lgkmcnt(5)
	v_mfma_f32_16x16x32_bf16 v[44:47], v[128:131], v[176:179], v[44:47]
	v_mfma_f32_16x16x32_bf16 v[40:43], v[152:155], v[176:179], v[40:43]
	s_waitcnt lgkmcnt(3)
	v_mfma_f32_16x16x32_bf16 v[28:31], v[128:131], v[184:187], v[28:31]
	v_mfma_f32_16x16x32_bf16 v[24:27], v[152:155], v[184:187], v[24:27]
	s_waitcnt lgkmcnt(1)
	v_mfma_f32_16x16x32_bf16 v[12:15], v[128:131], v[196:199], v[12:15]
	v_mfma_f32_16x16x32_bf16 v[8:11], v[152:155], v[196:199], v[8:11]
	v_mfma_f32_16x16x32_bf16 v[60:63], v[132:135], v[172:175], v[60:63]
	v_mfma_f32_16x16x32_bf16 v[56:59], v[156:159], v[172:175], v[56:59]
	v_mfma_f32_16x16x32_bf16 v[44:47], v[132:135], v[180:183], v[44:47]
	v_mfma_f32_16x16x32_bf16 v[40:43], v[156:159], v[180:183], v[40:43]
	v_mfma_f32_16x16x32_bf16 v[28:31], v[132:135], v[188:191], v[28:31]
	v_mfma_f32_16x16x32_bf16 v[24:27], v[156:159], v[188:191], v[24:27]
	s_waitcnt lgkmcnt(0)
	v_mfma_f32_16x16x32_bf16 v[12:15], v[132:135], v[200:203], v[12:15]
	v_mfma_f32_16x16x32_bf16 v[8:11], v[156:159], v[200:203], v[8:11]
	s_barrier
	s_add_u32 s50, s50, 0x8080
	s_addc_u32 s51, s51, 0
	s_add_i32 s28, s29, s54
	v_lshl_add_u64 v[128:129], s[50:51], 0, v[138:139]
	s_mov_b32 m0, s28
	s_nop 0
	global_load_lds_dwordx4 v[128:129], off
	v_lshl_add_u64 v[128:129], s[50:51], 0, v[142:143]
	s_add_i32 m0, s28, 0x2000
	s_nop 0
	global_load_lds_dwordx4 v[128:129], off
	s_waitcnt vmcnt(6)
	s_barrier
	v_mfma_f32_16x16x32_bf16 v[52:55], v[204:207], v[168:171], v[52:55]
	v_mfma_f32_16x16x32_bf16 v[48:51], v[212:215], v[168:171], v[48:51]
	v_mfma_f32_16x16x32_bf16 v[36:39], v[204:207], v[176:179], v[36:39]
	v_mfma_f32_16x16x32_bf16 v[32:35], v[212:215], v[176:179], v[32:35]
	v_mfma_f32_16x16x32_bf16 v[20:23], v[204:207], v[184:187], v[20:23]
	v_mfma_f32_16x16x32_bf16 v[16:19], v[212:215], v[184:187], v[16:19]
	v_mfma_f32_16x16x32_bf16 v[4:7], v[204:207], v[196:199], v[4:7]
	v_mfma_f32_16x16x32_bf16 v[0:3], v[212:215], v[196:199], v[0:3]
	v_mfma_f32_16x16x32_bf16 v[52:55], v[208:211], v[172:175], v[52:55]
	v_mfma_f32_16x16x32_bf16 v[48:51], v[216:219], v[172:175], v[48:51]
	v_mfma_f32_16x16x32_bf16 v[36:39], v[208:211], v[180:183], v[36:39]
	v_mfma_f32_16x16x32_bf16 v[32:35], v[216:219], v[180:183], v[32:35]
	v_mfma_f32_16x16x32_bf16 v[20:23], v[208:211], v[188:191], v[20:23]
	v_mfma_f32_16x16x32_bf16 v[16:19], v[216:219], v[188:191], v[16:19]
	v_mfma_f32_16x16x32_bf16 v[4:7], v[208:211], v[200:203], v[4:7]
	v_mfma_f32_16x16x32_bf16 v[0:3], v[216:219], v[200:203], v[0:3]
	s_add_i32 s79, s79, 2
	s_add_u32 s48, s48, 0x100
	s_addc_u32 s49, s49, 0
	s_add_u32 s77, s77, 0x100
	s_addc_u32 s78, s78, 0
	s_cmp_gt_u32 s79, 5
	s_barrier
	s_cbranch_scc0 .LBB0_997
	v_lshl_add_u32 v152, s8, 8, v160
	v_lshl_or_b32 v156, s10, 8, v162
	v_ashrrev_i32_e32 v153, 31, v152
	v_lshlrev_b64 v[128:129], 11, v[152:153]
	v_ashrrev_i32_e32 v157, 31, v156
	v_lshl_add_u64 v[128:129], s[42:43], 0, v[128:129]
	v_lshlrev_b64 v[130:131], 1, v[156:157]
	v_or_b32_e32 v158, 16, v152
	v_lshl_add_u64 v[128:129], v[128:129], 0, v[130:131]
	v_ashrrev_i32_e32 v159, 31, v158
	global_load_dwordx4 v[168:171], v[128:129], off
	global_load_dwordx4 v[172:175], v[128:129], off offset:64
	v_lshlrev_b64 v[128:129], 11, v[158:159]
	v_lshl_add_u64 v[128:129], s[42:43], 0, v[128:129]
	v_lshl_add_u64 v[128:129], v[128:129], 0, v[130:131]
	global_load_dwordx4 v[132:135], v[128:129], off
	s_nop 0
	global_load_dwordx4 v[128:131], v[128:129], off offset:64
	v_cndmask_b32_e64 v155, 0, 1, s[12:13]
	v_or_b32_e32 v154, v156, v163
	v_cmp_ne_u32_e64 s[8:9], 1, v155
	v_ashrrev_i32_e32 v155, 31, v154
	s_andn2_b64 vcc, exec, s[12:13]
	v_lshlrev_b64 v[154:155], 1, v[154:155]
	s_waitcnt vmcnt(0)
	v_lshlrev_b32_e32 v176, 16, v168
	v_and_b32_e32 v177, 0xffff0000, v168
	v_lshlrev_b32_e32 v168, 16, v169
	v_and_b32_e32 v169, 0xffff0000, v169
	v_lshlrev_b32_e32 v178, 16, v170
	v_and_b32_e32 v179, 0xffff0000, v170
	v_lshlrev_b32_e32 v170, 16, v171
	v_and_b32_e32 v171, 0xffff0000, v171
	v_lshlrev_b32_e32 v180, 16, v172
	v_and_b32_e32 v181, 0xffff0000, v172
	v_lshlrev_b32_e32 v172, 16, v173
	v_and_b32_e32 v173, 0xffff0000, v173
	v_lshlrev_b32_e32 v182, 16, v174
	v_and_b32_e32 v183, 0xffff0000, v174
	v_lshlrev_b32_e32 v174, 16, v175
	v_and_b32_e32 v175, 0xffff0000, v175
	v_pk_add_f32 v[126:127], v[126:127], v[168:169]
	v_pk_add_f32 v[124:125], v[124:125], v[176:177]
	v_pk_add_f32 v[122:123], v[122:123], v[170:171]
	v_pk_add_f32 v[120:121], v[120:121], v[178:179]
	v_pk_add_f32 v[118:119], v[118:119], v[172:173]
	v_pk_add_f32 v[116:117], v[116:117], v[180:181]
	v_pk_add_f32 v[114:115], v[114:115], v[174:175]
	v_pk_add_f32 v[112:113], v[112:113], v[182:183]
	v_add_u32_e32 v169, 8, v152
	s_cbranch_vccnz .LBB0_1000
	v_cvt_pk_bf16_f32 v168, v124, v125
	v_cvt_pk_bf16_f32 v174, v116, v117
	v_cvt_pk_bf16_f32 v170, v126, v127
	v_cvt_pk_bf16_f32 v171, v120, v121
	v_cvt_pk_bf16_f32 v175, v118, v119
	v_cvt_pk_bf16_f32 v176, v112, v113
	v_cndmask_b32_e64 v173, v168, v174, s[4:5]
	v_mov_b32_e32 v178, 0
	v_cvt_pk_bf16_f32 v172, v122, v123
	v_cvt_pk_bf16_f32 v177, v114, v115
	v_mov_b32_dpp v178, v173 row_ror:8 row_mask:0xf bank_mask:0xf
	v_cndmask_b32_e64 v173, v170, v175, s[4:5]
	v_mov_b32_e32 v179, 0
	v_cndmask_b32_e64 v180, v171, v176, s[4:5]
	v_mov_b32_e32 v181, 0
	v_mov_b32_dpp v179, v173 row_ror:8 row_mask:0xf bank_mask:0xf
	v_cndmask_b32_e64 v173, v172, v177, s[4:5]
	v_mov_b32_dpp v181, v180 row_ror:8 row_mask:0xf bank_mask:0xf
	v_mov_b32_e32 v180, 0
	v_cndmask_b32_e64 v174, v174, v178, s[4:5]
	v_cndmask_b32_e64 v175, v175, v179, s[4:5]
	v_mov_b32_dpp v180, v173 row_ror:8 row_mask:0xf bank_mask:0xf
	v_cndmask_b32_e64 v173, v180, v172, s[4:5]
	v_cndmask_b32_e64 v172, v181, v171, s[4:5]
	v_cndmask_b32_e64 v171, v179, v170, s[4:5]
	v_cndmask_b32_e64 v170, v178, v168, s[4:5]
	v_add_u32_e32 v168, -8, v152
	v_cndmask_b32_e64 v178, v168, v152, s[4:5]
	v_ashrrev_i32_e32 v179, 31, v178
	v_lshlrev_b64 v[178:179], 11, v[178:179]
	v_lshl_add_u64 v[178:179], s[68:69], 0, v[178:179]
	v_lshl_add_u64 v[178:179], v[178:179], 0, v[154:155]
	global_store_dwordx4 v[178:179], v[170:173], off
	v_cndmask_b32_e64 v177, v177, v180, s[4:5]
	v_cndmask_b32_e64 v176, v176, v181, s[4:5]
	v_cndmask_b32_e64 v170, v152, v169, s[4:5]
	v_ashrrev_i32_e32 v171, 31, v170
	v_lshlrev_b64 v[170:171], 11, v[170:171]
	v_lshl_add_u64 v[170:171], s[68:69], 0, v[170:171]
	v_lshl_add_u64 v[170:171], v[170:171], 0, v[154:155]
	global_store_dwordx4 v[170:171], v[174:177], off

.LBB0_1092:
	s_ashr_i32 s37, s36, 31
	v_cmp_lt_i64_e32 vcc, s[0:1], v[142:143]
	s_lshl_b64 s[0:1], s[36:37], 19
	s_add_u32 s38, s68, s0
	s_addc_u32 s39, s69, s1
	s_and_b64 s[0:1], vcc, exec
	s_cselect_b32 s37, s39, s45
	s_cselect_b32 s60, s38, s44
	s_ashr_i32 s13, s12, 31
	s_lshl_b64 s[0:1], s[12:13], 19
	s_add_u32 s40, s70, s0
	s_addc_u32 s41, s71, s1
	s_and_b64 s[0:1], vcc, exec
	s_cselect_b32 s13, s41, s43
	s_cselect_b32 s61, s40, s42
	s_add_u32 s0, s44, 0x40080
	s_addc_u32 s1, s45, 0
	s_add_u32 s62, s42, 0x100
	s_addc_u32 s63, s43, 0
	s_mov_b32 s64, -2
	ds_read_b128 v[146:149], v167
	ds_read_b128 v[150:153], v167 offset:1024
	ds_read_b128 v[178:181], v167 offset:2048
	ds_read_b128 v[182:185], v167 offset:3072
	s_add_u32 s28, s0, 0xfffc0080
	s_addc_u32 s29, s1, -1
	s_cmp_eq_u32 s64, 12
	s_cselect_b32 s45, s37, s29
	s_cselect_b32 s44, s60, s28
	s_cselect_b32 s43, s13, s63
	s_cselect_b32 s42, s61, s62
	v_lshl_add_u64 v[156:157], s[0:1], 0, v[138:139]
	s_add_i32 m0, s47, 0xc000
	ds_read_b128 v[186:189], v171
	ds_read_b128 v[196:199], v171 offset:1024
	ds_read_b128 v[200:203], v171 offset:2048
	ds_read_b128 v[204:207], v171 offset:3072
	ds_read_b128 v[208:211], v171 offset:4096
	ds_read_b128 v[212:215], v171 offset:5120
	ds_read_b128 v[216:219], v171 offset:6144
	ds_read_b128 v[220:223], v171 offset:7168
	global_load_lds_dwordx4 v[156:157], off
	v_lshl_add_u64 v[156:157], s[0:1], 0, v[140:141]
	s_add_i32 m0, s47, 0xe000
	s_nop 0
	global_load_lds_dwordx4 v[156:157], off
	s_waitcnt lgkmcnt(8)
	s_barrier
	s_waitcnt lgkmcnt(7)
	v_mfma_f32_16x16x32_bf16 v[124:127], v[146:149], v[186:189], 0
	v_mfma_f32_16x16x32_bf16 v[120:123], v[178:181], v[186:189], 0
	s_waitcnt lgkmcnt(5)
	v_mfma_f32_16x16x32_bf16 v[108:111], v[146:149], v[200:203], 0
	v_mfma_f32_16x16x32_bf16 v[104:107], v[178:181], v[200:203], 0
	s_waitcnt lgkmcnt(3)
	v_mfma_f32_16x16x32_bf16 v[92:95], v[146:149], v[208:211], 0
	v_mfma_f32_16x16x32_bf16 v[88:91], v[178:181], v[208:211], 0
	s_waitcnt lgkmcnt(1)
	v_mfma_f32_16x16x32_bf16 v[76:79], v[146:149], v[216:219], 0
	v_mfma_f32_16x16x32_bf16 v[72:75], v[178:181], v[216:219], 0
	v_mfma_f32_16x16x32_bf16 v[124:127], v[150:153], v[196:199], v[124:127]
	v_mfma_f32_16x16x32_bf16 v[120:123], v[182:185], v[196:199], v[120:123]
	v_mfma_f32_16x16x32_bf16 v[108:111], v[150:153], v[204:207], v[108:111]
	v_mfma_f32_16x16x32_bf16 v[104:107], v[182:185], v[204:207], v[104:107]
	v_mfma_f32_16x16x32_bf16 v[92:95], v[150:153], v[212:215], v[92:95]
	v_mfma_f32_16x16x32_bf16 v[88:91], v[182:185], v[212:215], v[88:91]
	s_waitcnt lgkmcnt(0)
	v_mfma_f32_16x16x32_bf16 v[76:79], v[150:153], v[220:223], v[76:79]
	v_mfma_f32_16x16x32_bf16 v[72:75], v[182:185], v[220:223], v[72:75]
	s_barrier
	s_add_i32 s28, s56, s11
	v_lshl_add_u64 v[156:157], s[42:43], 0, v[132:133]
	s_mov_b32 m0, s28
	ds_read_b128 v[224:227], v175
	ds_read_b128 v[228:231], v175 offset:1024
	ds_read_b128 v[232:235], v175 offset:2048
	ds_read_b128 v[236:239], v175 offset:3072
	global_load_lds_dwordx4 v[156:157], off
	v_lshl_add_u64 v[160:161], s[42:43], 0, v[128:129]
	s_add_i32 m0, s28, 0x2000
	s_nop 0
	global_load_lds_dwordx4 v[160:161], off
	s_barrier
	s_waitcnt lgkmcnt(3)
	v_mfma_f32_16x16x32_bf16 v[116:119], v[224:227], v[186:189], 0
	s_waitcnt lgkmcnt(1)
	v_mfma_f32_16x16x32_bf16 v[112:115], v[232:235], v[186:189], 0
	v_mfma_f32_16x16x32_bf16 v[100:103], v[224:227], v[200:203], 0
	v_mfma_f32_16x16x32_bf16 v[96:99], v[232:235], v[200:203], 0
	v_mfma_f32_16x16x32_bf16 v[84:87], v[224:227], v[208:211], 0
	v_mfma_f32_16x16x32_bf16 v[80:83], v[232:235], v[208:211], 0
	v_mfma_f32_16x16x32_bf16 v[68:71], v[224:227], v[216:219], 0
	v_mfma_f32_16x16x32_bf16 v[64:67], v[232:235], v[216:219], 0
	v_mfma_f32_16x16x32_bf16 v[116:119], v[228:231], v[196:199], v[116:119]
	s_waitcnt lgkmcnt(0)
	v_mfma_f32_16x16x32_bf16 v[112:115], v[236:239], v[196:199], v[112:115]
	v_mfma_f32_16x16x32_bf16 v[100:103], v[228:231], v[204:207], v[100:103]
	v_mfma_f32_16x16x32_bf16 v[96:99], v[236:239], v[204:207], v[96:99]
	v_mfma_f32_16x16x32_bf16 v[84:87], v[228:231], v[212:215], v[84:87]
	v_mfma_f32_16x16x32_bf16 v[80:83], v[236:239], v[212:215], v[80:83]
	v_mfma_f32_16x16x32_bf16 v[68:71], v[228:231], v[220:223], v[68:71]
	v_mfma_f32_16x16x32_bf16 v[64:67], v[236:239], v[220:223], v[64:67]
	s_mov_b32 m0, s47
	v_lshl_add_u64 v[164:165], s[44:45], 0, v[134:135]
	s_barrier
	ds_read_b128 v[186:189], v171 offset:16384
	ds_read_b128 v[196:199], v171 offset:17408
	ds_read_b128 v[200:203], v171 offset:18432
	ds_read_b128 v[204:207], v171 offset:19456
	ds_read_b128 v[208:211], v171 offset:20480
	ds_read_b128 v[212:215], v171 offset:21504
	ds_read_b128 v[216:219], v171 offset:22528
	ds_read_b128 v[220:223], v171 offset:23552
	global_load_lds_dwordx4 v[164:165], off
	v_lshl_add_u64 v[168:169], s[44:45], 0, v[130:131]
	s_mov_b32 m0, s48
	s_nop 0
	global_load_lds_dwordx4 v[168:169], off
	s_barrier
	s_waitcnt lgkmcnt(7)
	v_mfma_f32_16x16x32_bf16 v[60:63], v[146:149], v[186:189], 0
	v_mfma_f32_16x16x32_bf16 v[56:59], v[178:181], v[186:189], 0
	s_waitcnt lgkmcnt(5)
	v_mfma_f32_16x16x32_bf16 v[44:47], v[146:149], v[200:203], 0
	v_mfma_f32_16x16x32_bf16 v[40:43], v[178:181], v[200:203], 0
	s_waitcnt lgkmcnt(3)
	v_mfma_f32_16x16x32_bf16 v[28:31], v[146:149], v[208:211], 0
	v_mfma_f32_16x16x32_bf16 v[24:27], v[178:181], v[208:211], 0
	s_waitcnt lgkmcnt(1)
	v_mfma_f32_16x16x32_bf16 v[12:15], v[146:149], v[216:219], 0
	v_mfma_f32_16x16x32_bf16 v[8:11], v[178:181], v[216:219], 0
	v_mfma_f32_16x16x32_bf16 v[60:63], v[150:153], v[196:199], v[60:63]
	v_mfma_f32_16x16x32_bf16 v[56:59], v[182:185], v[196:199], v[56:59]
	v_mfma_f32_16x16x32_bf16 v[44:47], v[150:153], v[204:207], v[44:47]
	v_mfma_f32_16x16x32_bf16 v[40:43], v[182:185], v[204:207], v[40:43]
	v_mfma_f32_16x16x32_bf16 v[28:31], v[150:153], v[212:215], v[28:31]
	v_mfma_f32_16x16x32_bf16 v[24:27], v[182:185], v[212:215], v[24:27]
	s_waitcnt lgkmcnt(0)
	v_mfma_f32_16x16x32_bf16 v[12:15], v[150:153], v[220:223], v[12:15]
	v_mfma_f32_16x16x32_bf16 v[8:11], v[182:185], v[220:223], v[8:11]
	s_barrier
	s_add_u32 s66, s42, 0x40000
	s_addc_u32 s67, s43, 0
	s_add_i32 s28, s57, s11
	v_lshl_add_u64 v[146:147], s[66:67], 0, v[132:133]
	s_mov_b32 m0, s28
	s_nop 0
	global_load_lds_dwordx4 v[146:147], off
	v_lshl_add_u64 v[146:147], s[66:67], 0, v[128:129]
	s_add_i32 m0, s28, 0x2000
	s_nop 0
	global_load_lds_dwordx4 v[146:147], off
	s_waitcnt vmcnt(6)
	s_barrier
	v_mfma_f32_16x16x32_bf16 v[52:55], v[224:227], v[186:189], 0
	v_mfma_f32_16x16x32_bf16 v[48:51], v[232:235], v[186:189], 0
	v_mfma_f32_16x16x32_bf16 v[36:39], v[224:227], v[200:203], 0
	v_mfma_f32_16x16x32_bf16 v[32:35], v[232:235], v[200:203], 0
	v_mfma_f32_16x16x32_bf16 v[20:23], v[224:227], v[208:211], 0
	v_mfma_f32_16x16x32_bf16 v[16:19], v[232:235], v[208:211], 0
	v_mfma_f32_16x16x32_bf16 v[4:7], v[224:227], v[216:219], 0
	v_mfma_f32_16x16x32_bf16 v[0:3], v[232:235], v[216:219], 0
	v_mfma_f32_16x16x32_bf16 v[52:55], v[228:231], v[196:199], v[52:55]
	v_mfma_f32_16x16x32_bf16 v[48:51], v[236:239], v[196:199], v[48:51]
	v_mfma_f32_16x16x32_bf16 v[36:39], v[228:231], v[204:207], v[36:39]
	v_mfma_f32_16x16x32_bf16 v[32:35], v[236:239], v[204:207], v[32:35]
	v_mfma_f32_16x16x32_bf16 v[20:23], v[228:231], v[212:215], v[20:23]
	v_mfma_f32_16x16x32_bf16 v[16:19], v[236:239], v[212:215], v[16:19]
	v_mfma_f32_16x16x32_bf16 v[4:7], v[228:231], v[220:223], v[4:7]
	v_mfma_f32_16x16x32_bf16 v[0:3], v[236:239], v[220:223], v[0:3]
	s_add_i32 s28, 0, 0x18000
	v_add_u32_e32 v154, s28, v159
	s_barrier
	ds_read_b128 v[146:149], v154
	ds_read_b128 v[150:153], v154 offset:1024
	ds_read_b128 v[178:181], v154 offset:2048
	ds_read_b128 v[182:185], v154 offset:3072
	s_add_u32 s44, s44, 0x40000
	s_addc_u32 s45, s45, 0
	s_mov_b32 m0, s49
	v_lshl_add_u64 v[172:173], s[44:45], 0, v[134:135]
	ds_read_b128 v[186:189], v171 offset:32768
	ds_read_b128 v[196:199], v171 offset:33792
	ds_read_b128 v[200:203], v171 offset:34816
	ds_read_b128 v[204:207], v171 offset:35840
	ds_read_b128 v[208:211], v171 offset:36864
	ds_read_b128 v[212:215], v171 offset:37888
	ds_read_b128 v[216:219], v171 offset:38912
	ds_read_b128 v[220:223], v171 offset:39936
	global_load_lds_dwordx4 v[172:173], off
	v_lshl_add_u64 v[172:173], s[44:45], 0, v[130:131]
	s_mov_b32 m0, s50
	s_nop 0
	global_load_lds_dwordx4 v[172:173], off
	s_waitcnt lgkmcnt(8)
	s_barrier
	s_waitcnt lgkmcnt(7)
	v_mfma_f32_16x16x32_bf16 v[124:127], v[146:149], v[186:189], v[124:127]
	v_mfma_f32_16x16x32_bf16 v[120:123], v[178:181], v[186:189], v[120:123]
	s_waitcnt lgkmcnt(5)
	v_mfma_f32_16x16x32_bf16 v[108:111], v[146:149], v[200:203], v[108:111]
	v_mfma_f32_16x16x32_bf16 v[104:107], v[178:181], v[200:203], v[104:107]
	s_waitcnt lgkmcnt(3)
	v_mfma_f32_16x16x32_bf16 v[92:95], v[146:149], v[208:211], v[92:95]
	v_mfma_f32_16x16x32_bf16 v[88:91], v[178:181], v[208:211], v[88:91]
	s_waitcnt lgkmcnt(1)
	v_mfma_f32_16x16x32_bf16 v[76:79], v[146:149], v[216:219], v[76:79]
	v_mfma_f32_16x16x32_bf16 v[72:75], v[178:181], v[216:219], v[72:75]
	v_mfma_f32_16x16x32_bf16 v[124:127], v[150:153], v[196:199], v[124:127]
	v_mfma_f32_16x16x32_bf16 v[120:123], v[182:185], v[196:199], v[120:123]
	v_mfma_f32_16x16x32_bf16 v[108:111], v[150:153], v[204:207], v[108:111]
	v_mfma_f32_16x16x32_bf16 v[104:107], v[182:185], v[204:207], v[104:107]
	v_mfma_f32_16x16x32_bf16 v[92:95], v[150:153], v[212:215], v[92:95]
	v_mfma_f32_16x16x32_bf16 v[88:91], v[182:185], v[212:215], v[88:91]
	s_waitcnt lgkmcnt(0)
	v_mfma_f32_16x16x32_bf16 v[76:79], v[150:153], v[220:223], v[76:79]
	v_mfma_f32_16x16x32_bf16 v[72:75], v[182:185], v[220:223], v[72:75]
	s_barrier
	s_add_i32 s29, 0, 0x1c000
	s_add_i32 s28, s28, s11
	v_add_u32_e32 v154, s29, v159
	v_lshl_add_u64 v[156:157], v[156:157], 0, s[6:7]
	s_mov_b32 m0, s28
	ds_read_b128 v[224:227], v154
	ds_read_b128 v[228:231], v154 offset:1024
	ds_read_b128 v[232:235], v154 offset:2048
	ds_read_b128 v[236:239], v154 offset:3072
	global_load_lds_dwordx4 v[156:157], off
	v_lshl_add_u64 v[156:157], v[160:161], 0, s[6:7]
	s_add_i32 m0, s28, 0x2000
	s_nop 0
	global_load_lds_dwordx4 v[156:157], off
	s_barrier
	s_waitcnt lgkmcnt(3)
	v_mfma_f32_16x16x32_bf16 v[116:119], v[224:227], v[186:189], v[116:119]
	s_waitcnt lgkmcnt(1)
	v_mfma_f32_16x16x32_bf16 v[112:115], v[232:235], v[186:189], v[112:115]
	v_mfma_f32_16x16x32_bf16 v[100:103], v[224:227], v[200:203], v[100:103]
	v_mfma_f32_16x16x32_bf16 v[96:99], v[232:235], v[200:203], v[96:99]
	v_mfma_f32_16x16x32_bf16 v[84:87], v[224:227], v[208:211], v[84:87]
	v_mfma_f32_16x16x32_bf16 v[80:83], v[232:235], v[208:211], v[80:83]
	v_mfma_f32_16x16x32_bf16 v[68:71], v[224:227], v[216:219], v[68:71]
	v_mfma_f32_16x16x32_bf16 v[64:67], v[232:235], v[216:219], v[64:67]
	v_mfma_f32_16x16x32_bf16 v[116:119], v[228:231], v[196:199], v[116:119]
	s_waitcnt lgkmcnt(0)
	v_mfma_f32_16x16x32_bf16 v[112:115], v[236:239], v[196:199], v[112:115]
	v_mfma_f32_16x16x32_bf16 v[100:103], v[228:231], v[204:207], v[100:103]
	v_mfma_f32_16x16x32_bf16 v[96:99], v[236:239], v[204:207], v[96:99]
	v_mfma_f32_16x16x32_bf16 v[84:87], v[228:231], v[212:215], v[84:87]
	v_mfma_f32_16x16x32_bf16 v[80:83], v[236:239], v[212:215], v[80:83]
	v_mfma_f32_16x16x32_bf16 v[68:71], v[228:231], v[220:223], v[68:71]
	v_mfma_f32_16x16x32_bf16 v[64:67], v[236:239], v[220:223], v[64:67]
	s_mov_b32 m0, s53
	v_lshl_add_u64 v[156:157], v[164:165], 0, s[6:7]
	s_barrier
	ds_read_b128 v[186:189], v171 offset:49152
	ds_read_b128 v[196:199], v171 offset:50176
	ds_read_b128 v[200:203], v171 offset:51200
	ds_read_b128 v[204:207], v171 offset:52224
	ds_read_b128 v[208:211], v171 offset:53248
	ds_read_b128 v[212:215], v171 offset:54272
	ds_read_b128 v[216:219], v171 offset:55296
	ds_read_b128 v[220:223], v171 offset:56320
	global_load_lds_dwordx4 v[156:157], off
	v_lshl_add_u64 v[156:157], v[168:169], 0, s[6:7]
	s_mov_b32 m0, s54
	s_nop 0
	global_load_lds_dwordx4 v[156:157], off
	s_barrier
	s_waitcnt lgkmcnt(7)
	v_mfma_f32_16x16x32_bf16 v[60:63], v[146:149], v[186:189], v[60:63]
	v_mfma_f32_16x16x32_bf16 v[56:59], v[178:181], v[186:189], v[56:59]
	s_waitcnt lgkmcnt(5)
	v_mfma_f32_16x16x32_bf16 v[44:47], v[146:149], v[200:203], v[44:47]
	v_mfma_f32_16x16x32_bf16 v[40:43], v[178:181], v[200:203], v[40:43]
	s_waitcnt lgkmcnt(3)
	v_mfma_f32_16x16x32_bf16 v[28:31], v[146:149], v[208:211], v[28:31]
	v_mfma_f32_16x16x32_bf16 v[24:27], v[178:181], v[208:211], v[24:27]
	s_waitcnt lgkmcnt(1)
	v_mfma_f32_16x16x32_bf16 v[12:15], v[146:149], v[216:219], v[12:15]
	v_mfma_f32_16x16x32_bf16 v[8:11], v[178:181], v[216:219], v[8:11]
	v_mfma_f32_16x16x32_bf16 v[60:63], v[150:153], v[196:199], v[60:63]
	v_mfma_f32_16x16x32_bf16 v[56:59], v[182:185], v[196:199], v[56:59]
	v_mfma_f32_16x16x32_bf16 v[44:47], v[150:153], v[204:207], v[44:47]
	v_mfma_f32_16x16x32_bf16 v[40:43], v[182:185], v[204:207], v[40:43]
	v_mfma_f32_16x16x32_bf16 v[28:31], v[150:153], v[212:215], v[28:31]
	v_mfma_f32_16x16x32_bf16 v[24:27], v[182:185], v[212:215], v[24:27]
	s_waitcnt lgkmcnt(0)
	v_mfma_f32_16x16x32_bf16 v[12:15], v[150:153], v[220:223], v[12:15]
	v_mfma_f32_16x16x32_bf16 v[8:11], v[182:185], v[220:223], v[8:11]
	s_barrier
	s_add_u32 s42, s42, 0x40080
	s_addc_u32 s43, s43, 0
	s_add_i32 s28, s29, s11
	v_lshl_add_u64 v[146:147], s[42:43], 0, v[132:133]
	s_mov_b32 m0, s28
	s_nop 0
	global_load_lds_dwordx4 v[146:147], off
	v_lshl_add_u64 v[146:147], s[42:43], 0, v[128:129]
	s_add_i32 m0, s28, 0x2000
	s_nop 0
	global_load_lds_dwordx4 v[146:147], off
	s_waitcnt vmcnt(6)
	s_barrier
	v_mfma_f32_16x16x32_bf16 v[52:55], v[224:227], v[186:189], v[52:55]
	v_mfma_f32_16x16x32_bf16 v[48:51], v[232:235], v[186:189], v[48:51]
	v_mfma_f32_16x16x32_bf16 v[36:39], v[224:227], v[200:203], v[36:39]
	v_mfma_f32_16x16x32_bf16 v[32:35], v[232:235], v[200:203], v[32:35]
	v_mfma_f32_16x16x32_bf16 v[20:23], v[224:227], v[208:211], v[20:23]
	v_mfma_f32_16x16x32_bf16 v[16:19], v[232:235], v[208:211], v[16:19]
	v_mfma_f32_16x16x32_bf16 v[4:7], v[224:227], v[216:219], v[4:7]
	v_mfma_f32_16x16x32_bf16 v[0:3], v[232:235], v[216:219], v[0:3]
	v_mfma_f32_16x16x32_bf16 v[52:55], v[228:231], v[196:199], v[52:55]
	v_mfma_f32_16x16x32_bf16 v[48:51], v[236:239], v[196:199], v[48:51]
	v_mfma_f32_16x16x32_bf16 v[36:39], v[228:231], v[204:207], v[36:39]
	v_mfma_f32_16x16x32_bf16 v[32:35], v[236:239], v[204:207], v[32:35]
	v_mfma_f32_16x16x32_bf16 v[20:23], v[228:231], v[212:215], v[20:23]
	v_mfma_f32_16x16x32_bf16 v[16:19], v[236:239], v[212:215], v[16:19]
	v_mfma_f32_16x16x32_bf16 v[4:7], v[228:231], v[220:223], v[4:7]
	v_mfma_f32_16x16x32_bf16 v[0:3], v[236:239], v[220:223], v[0:3]
	s_add_i32 s64, s64, 2
	s_add_u32 s0, s0, 0x100
	s_addc_u32 s1, s1, 0
	s_add_u32 s62, s62, 0x100
	s_addc_u32 s63, s63, 0
	s_cmp_gt_u32 s64, 13
	s_barrier
	s_cbranch_scc0 .LBB0_1093
.LBB0_1093:
	ds_read_b128 v[146:149], v167
	ds_read_b128 v[150:153], v167 offset:1024
	ds_read_b128 v[178:181], v167 offset:2048
	ds_read_b128 v[182:185], v167 offset:3072
	s_add_u32 s28, s0, 0xfffc0080
	s_addc_u32 s29, s1, -1
	s_cmp_eq_u32 s64, 12
	s_cselect_b32 s45, s37, s29
	s_cselect_b32 s44, s60, s28
	s_cselect_b32 s43, s13, s63
	s_cselect_b32 s42, s61, s62
	v_lshl_add_u64 v[156:157], s[0:1], 0, v[138:139]
	s_add_i32 m0, s47, 0xc000
	ds_read_b128 v[186:189], v171
	ds_read_b128 v[196:199], v171 offset:1024
	ds_read_b128 v[200:203], v171 offset:2048
	ds_read_b128 v[204:207], v171 offset:3072
	ds_read_b128 v[208:211], v171 offset:4096
	ds_read_b128 v[212:215], v171 offset:5120
	ds_read_b128 v[216:219], v171 offset:6144
	ds_read_b128 v[220:223], v171 offset:7168
	global_load_lds_dwordx4 v[156:157], off
	v_lshl_add_u64 v[156:157], s[0:1], 0, v[140:141]
	s_add_i32 m0, s47, 0xe000
	s_nop 0
	global_load_lds_dwordx4 v[156:157], off
	s_waitcnt lgkmcnt(8)
	s_barrier
	s_waitcnt lgkmcnt(7)
	v_mfma_f32_16x16x32_bf16 v[124:127], v[146:149], v[186:189], v[124:127]
	v_mfma_f32_16x16x32_bf16 v[120:123], v[178:181], v[186:189], v[120:123]
	s_waitcnt lgkmcnt(5)
	v_mfma_f32_16x16x32_bf16 v[108:111], v[146:149], v[200:203], v[108:111]
	v_mfma_f32_16x16x32_bf16 v[104:107], v[178:181], v[200:203], v[104:107]
	s_waitcnt lgkmcnt(3)
	v_mfma_f32_16x16x32_bf16 v[92:95], v[146:149], v[208:211], v[92:95]
	v_mfma_f32_16x16x32_bf16 v[88:91], v[178:181], v[208:211], v[88:91]
	s_waitcnt lgkmcnt(1)
	v_mfma_f32_16x16x32_bf16 v[76:79], v[146:149], v[216:219], v[76:79]
	v_mfma_f32_16x16x32_bf16 v[72:75], v[178:181], v[216:219], v[72:75]
	v_mfma_f32_16x16x32_bf16 v[124:127], v[150:153], v[196:199], v[124:127]
	v_mfma_f32_16x16x32_bf16 v[120:123], v[182:185], v[196:199], v[120:123]
	v_mfma_f32_16x16x32_bf16 v[108:111], v[150:153], v[204:207], v[108:111]
	v_mfma_f32_16x16x32_bf16 v[104:107], v[182:185], v[204:207], v[104:107]
	v_mfma_f32_16x16x32_bf16 v[92:95], v[150:153], v[212:215], v[92:95]
	v_mfma_f32_16x16x32_bf16 v[88:91], v[182:185], v[212:215], v[88:91]
	s_waitcnt lgkmcnt(0)
	v_mfma_f32_16x16x32_bf16 v[76:79], v[150:153], v[220:223], v[76:79]
	v_mfma_f32_16x16x32_bf16 v[72:75], v[182:185], v[220:223], v[72:75]
	s_barrier
	s_add_i32 s28, s56, s11
	v_lshl_add_u64 v[156:157], s[42:43], 0, v[132:133]
	s_mov_b32 m0, s28
	ds_read_b128 v[224:227], v175
	ds_read_b128 v[228:231], v175 offset:1024
	ds_read_b128 v[232:235], v175 offset:2048
	ds_read_b128 v[236:239], v175 offset:3072
	global_load_lds_dwordx4 v[156:157], off
	v_lshl_add_u64 v[160:161], s[42:43], 0, v[128:129]
	s_add_i32 m0, s28, 0x2000
	s_nop 0
	global_load_lds_dwordx4 v[160:161], off
	s_barrier
	s_waitcnt lgkmcnt(3)
	v_mfma_f32_16x16x32_bf16 v[116:119], v[224:227], v[186:189], v[116:119]
	s_waitcnt lgkmcnt(1)
	v_mfma_f32_16x16x32_bf16 v[112:115], v[232:235], v[186:189], v[112:115]
	v_mfma_f32_16x16x32_bf16 v[100:103], v[224:227], v[200:203], v[100:103]
	v_mfma_f32_16x16x32_bf16 v[96:99], v[232:235], v[200:203], v[96:99]
	v_mfma_f32_16x16x32_bf16 v[84:87], v[224:227], v[208:211], v[84:87]
	v_mfma_f32_16x16x32_bf16 v[80:83], v[232:235], v[208:211], v[80:83]
	v_mfma_f32_16x16x32_bf16 v[68:71], v[224:227], v[216:219], v[68:71]
	v_mfma_f32_16x16x32_bf16 v[64:67], v[232:235], v[216:219], v[64:67]
	v_mfma_f32_16x16x32_bf16 v[116:119], v[228:231], v[196:199], v[116:119]
	s_waitcnt lgkmcnt(0)
	v_mfma_f32_16x16x32_bf16 v[112:115], v[236:239], v[196:199], v[112:115]
	v_mfma_f32_16x16x32_bf16 v[100:103], v[228:231], v[204:207], v[100:103]
	v_mfma_f32_16x16x32_bf16 v[96:99], v[236:239], v[204:207], v[96:99]
	v_mfma_f32_16x16x32_bf16 v[84:87], v[228:231], v[212:215], v[84:87]
	v_mfma_f32_16x16x32_bf16 v[80:83], v[236:239], v[212:215], v[80:83]
	v_mfma_f32_16x16x32_bf16 v[68:71], v[228:231], v[220:223], v[68:71]
	v_mfma_f32_16x16x32_bf16 v[64:67], v[236:239], v[220:223], v[64:67]
	s_mov_b32 m0, s47
	v_lshl_add_u64 v[164:165], s[44:45], 0, v[134:135]
	s_barrier
	ds_read_b128 v[186:189], v171 offset:16384
	ds_read_b128 v[196:199], v171 offset:17408
	ds_read_b128 v[200:203], v171 offset:18432
	ds_read_b128 v[204:207], v171 offset:19456
	ds_read_b128 v[208:211], v171 offset:20480
	ds_read_b128 v[212:215], v171 offset:21504
	ds_read_b128 v[216:219], v171 offset:22528
	ds_read_b128 v[220:223], v171 offset:23552
	global_load_lds_dwordx4 v[164:165], off
	v_lshl_add_u64 v[168:169], s[44:45], 0, v[130:131]
	s_mov_b32 m0, s48
	s_nop 0
	global_load_lds_dwordx4 v[168:169], off
	s_barrier
	s_waitcnt lgkmcnt(7)
	v_mfma_f32_16x16x32_bf16 v[60:63], v[146:149], v[186:189], v[60:63]
	v_mfma_f32_16x16x32_bf16 v[56:59], v[178:181], v[186:189], v[56:59]
	s_waitcnt lgkmcnt(5)
	v_mfma_f32_16x16x32_bf16 v[44:47], v[146:149], v[200:203], v[44:47]
	v_mfma_f32_16x16x32_bf16 v[40:43], v[178:181], v[200:203], v[40:43]
	s_waitcnt lgkmcnt(3)
	v_mfma_f32_16x16x32_bf16 v[28:31], v[146:149], v[208:211], v[28:31]
	v_mfma_f32_16x16x32_bf16 v[24:27], v[178:181], v[208:211], v[24:27]
	s_waitcnt lgkmcnt(1)
	v_mfma_f32_16x16x32_bf16 v[12:15], v[146:149], v[216:219], v[12:15]
	v_mfma_f32_16x16x32_bf16 v[8:11], v[178:181], v[216:219], v[8:11]
	v_mfma_f32_16x16x32_bf16 v[60:63], v[150:153], v[196:199], v[60:63]
	v_mfma_f32_16x16x32_bf16 v[56:59], v[182:185], v[196:199], v[56:59]
	v_mfma_f32_16x16x32_bf16 v[44:47], v[150:153], v[204:207], v[44:47]
	v_mfma_f32_16x16x32_bf16 v[40:43], v[182:185], v[204:207], v[40:43]
	v_mfma_f32_16x16x32_bf16 v[28:31], v[150:153], v[212:215], v[28:31]
	v_mfma_f32_16x16x32_bf16 v[24:27], v[182:185], v[212:215], v[24:27]
	s_waitcnt lgkmcnt(0)
	v_mfma_f32_16x16x32_bf16 v[12:15], v[150:153], v[220:223], v[12:15]
	v_mfma_f32_16x16x32_bf16 v[8:11], v[182:185], v[220:223], v[8:11]
	s_barrier
	s_add_u32 s66, s42, 0x40000
	s_addc_u32 s67, s43, 0
	s_add_i32 s28, s57, s11
	v_lshl_add_u64 v[146:147], s[66:67], 0, v[132:133]
	s_mov_b32 m0, s28
	s_nop 0
	global_load_lds_dwordx4 v[146:147], off
	v_lshl_add_u64 v[146:147], s[66:67], 0, v[128:129]
	s_add_i32 m0, s28, 0x2000
	s_nop 0
	global_load_lds_dwordx4 v[146:147], off
	s_waitcnt vmcnt(6)
	s_barrier
	v_mfma_f32_16x16x32_bf16 v[52:55], v[224:227], v[186:189], v[52:55]
	v_mfma_f32_16x16x32_bf16 v[48:51], v[232:235], v[186:189], v[48:51]
	v_mfma_f32_16x16x32_bf16 v[36:39], v[224:227], v[200:203], v[36:39]
	v_mfma_f32_16x16x32_bf16 v[32:35], v[232:235], v[200:203], v[32:35]
	v_mfma_f32_16x16x32_bf16 v[20:23], v[224:227], v[208:211], v[20:23]
	v_mfma_f32_16x16x32_bf16 v[16:19], v[232:235], v[208:211], v[16:19]
	v_mfma_f32_16x16x32_bf16 v[4:7], v[224:227], v[216:219], v[4:7]
	v_mfma_f32_16x16x32_bf16 v[0:3], v[232:235], v[216:219], v[0:3]
	v_mfma_f32_16x16x32_bf16 v[52:55], v[228:231], v[196:199], v[52:55]
	v_mfma_f32_16x16x32_bf16 v[48:51], v[236:239], v[196:199], v[48:51]
	v_mfma_f32_16x16x32_bf16 v[36:39], v[228:231], v[204:207], v[36:39]
	v_mfma_f32_16x16x32_bf16 v[32:35], v[236:239], v[204:207], v[32:35]
	v_mfma_f32_16x16x32_bf16 v[20:23], v[228:231], v[212:215], v[20:23]
	v_mfma_f32_16x16x32_bf16 v[16:19], v[236:239], v[212:215], v[16:19]
	v_mfma_f32_16x16x32_bf16 v[4:7], v[228:231], v[220:223], v[4:7]
	v_mfma_f32_16x16x32_bf16 v[0:3], v[236:239], v[220:223], v[0:3]
	s_add_i32 s28, 0, 0x18000
	v_add_u32_e32 v154, s28, v159
	s_barrier
	ds_read_b128 v[146:149], v154
	ds_read_b128 v[150:153], v154 offset:1024
	ds_read_b128 v[178:181], v154 offset:2048
	ds_read_b128 v[182:185], v154 offset:3072
	s_add_u32 s44, s44, 0x40000
	s_addc_u32 s45, s45, 0
	s_mov_b32 m0, s49
	v_lshl_add_u64 v[172:173], s[44:45], 0, v[134:135]
	ds_read_b128 v[186:189], v171 offset:32768
	ds_read_b128 v[196:199], v171 offset:33792
	ds_read_b128 v[200:203], v171 offset:34816
	ds_read_b128 v[204:207], v171 offset:35840
	ds_read_b128 v[208:211], v171 offset:36864
	ds_read_b128 v[212:215], v171 offset:37888
	ds_read_b128 v[216:219], v171 offset:38912
	ds_read_b128 v[220:223], v171 offset:39936
	global_load_lds_dwordx4 v[172:173], off
	v_lshl_add_u64 v[172:173], s[44:45], 0, v[130:131]
	s_mov_b32 m0, s50
	s_nop 0
	global_load_lds_dwordx4 v[172:173], off
	s_waitcnt lgkmcnt(8)
	s_barrier
	s_waitcnt lgkmcnt(7)
	v_mfma_f32_16x16x32_bf16 v[124:127], v[146:149], v[186:189], v[124:127]
	v_mfma_f32_16x16x32_bf16 v[120:123], v[178:181], v[186:189], v[120:123]
	s_waitcnt lgkmcnt(5)
	v_mfma_f32_16x16x32_bf16 v[108:111], v[146:149], v[200:203], v[108:111]
	v_mfma_f32_16x16x32_bf16 v[104:107], v[178:181], v[200:203], v[104:107]
	s_waitcnt lgkmcnt(3)
	v_mfma_f32_16x16x32_bf16 v[92:95], v[146:149], v[208:211], v[92:95]
	v_mfma_f32_16x16x32_bf16 v[88:91], v[178:181], v[208:211], v[88:91]
	s_waitcnt lgkmcnt(1)
	v_mfma_f32_16x16x32_bf16 v[76:79], v[146:149], v[216:219], v[76:79]
	v_mfma_f32_16x16x32_bf16 v[72:75], v[178:181], v[216:219], v[72:75]
	v_mfma_f32_16x16x32_bf16 v[124:127], v[150:153], v[196:199], v[124:127]
	v_mfma_f32_16x16x32_bf16 v[120:123], v[182:185], v[196:199], v[120:123]
	v_mfma_f32_16x16x32_bf16 v[108:111], v[150:153], v[204:207], v[108:111]
	v_mfma_f32_16x16x32_bf16 v[104:107], v[182:185], v[204:207], v[104:107]
	v_mfma_f32_16x16x32_bf16 v[92:95], v[150:153], v[212:215], v[92:95]
	v_mfma_f32_16x16x32_bf16 v[88:91], v[182:185], v[212:215], v[88:91]
	s_waitcnt lgkmcnt(0)
	v_mfma_f32_16x16x32_bf16 v[76:79], v[150:153], v[220:223], v[76:79]
	v_mfma_f32_16x16x32_bf16 v[72:75], v[182:185], v[220:223], v[72:75]
	s_barrier
	s_add_i32 s29, 0, 0x1c000
	s_add_i32 s28, s28, s11
	v_add_u32_e32 v154, s29, v159
	v_lshl_add_u64 v[156:157], v[156:157], 0, s[6:7]
	s_mov_b32 m0, s28
	ds_read_b128 v[224:227], v154
	ds_read_b128 v[228:231], v154 offset:1024
	ds_read_b128 v[232:235], v154 offset:2048
	ds_read_b128 v[236:239], v154 offset:3072
	global_load_lds_dwordx4 v[156:157], off
	v_lshl_add_u64 v[156:157], v[160:161], 0, s[6:7]
	s_add_i32 m0, s28, 0x2000
	s_nop 0
	global_load_lds_dwordx4 v[156:157], off
	s_barrier
	s_waitcnt lgkmcnt(3)
	v_mfma_f32_16x16x32_bf16 v[116:119], v[224:227], v[186:189], v[116:119]
	s_waitcnt lgkmcnt(1)
	v_mfma_f32_16x16x32_bf16 v[112:115], v[232:235], v[186:189], v[112:115]
	v_mfma_f32_16x16x32_bf16 v[100:103], v[224:227], v[200:203], v[100:103]
	v_mfma_f32_16x16x32_bf16 v[96:99], v[232:235], v[200:203], v[96:99]
	v_mfma_f32_16x16x32_bf16 v[84:87], v[224:227], v[208:211], v[84:87]
	v_mfma_f32_16x16x32_bf16 v[80:83], v[232:235], v[208:211], v[80:83]
	v_mfma_f32_16x16x32_bf16 v[68:71], v[224:227], v[216:219], v[68:71]
	v_mfma_f32_16x16x32_bf16 v[64:67], v[232:235], v[216:219], v[64:67]
	v_mfma_f32_16x16x32_bf16 v[116:119], v[228:231], v[196:199], v[116:119]
	s_waitcnt lgkmcnt(0)
	v_mfma_f32_16x16x32_bf16 v[112:115], v[236:239], v[196:199], v[112:115]
	v_mfma_f32_16x16x32_bf16 v[100:103], v[228:231], v[204:207], v[100:103]
	v_mfma_f32_16x16x32_bf16 v[96:99], v[236:239], v[204:207], v[96:99]
	v_mfma_f32_16x16x32_bf16 v[84:87], v[228:231], v[212:215], v[84:87]
	v_mfma_f32_16x16x32_bf16 v[80:83], v[236:239], v[212:215], v[80:83]
	v_mfma_f32_16x16x32_bf16 v[68:71], v[228:231], v[220:223], v[68:71]
	v_mfma_f32_16x16x32_bf16 v[64:67], v[236:239], v[220:223], v[64:67]
	s_mov_b32 m0, s53
	v_lshl_add_u64 v[156:157], v[164:165], 0, s[6:7]
	s_barrier
	ds_read_b128 v[186:189], v171 offset:49152
	ds_read_b128 v[196:199], v171 offset:50176
	ds_read_b128 v[200:203], v171 offset:51200
	ds_read_b128 v[204:207], v171 offset:52224
	ds_read_b128 v[208:211], v171 offset:53248
	ds_read_b128 v[212:215], v171 offset:54272
	ds_read_b128 v[216:219], v171 offset:55296
	ds_read_b128 v[220:223], v171 offset:56320
	global_load_lds_dwordx4 v[156:157], off
	v_lshl_add_u64 v[156:157], v[168:169], 0, s[6:7]
	s_mov_b32 m0, s54
	s_nop 0
	global_load_lds_dwordx4 v[156:157], off
	s_barrier
	s_waitcnt lgkmcnt(7)
	v_mfma_f32_16x16x32_bf16 v[60:63], v[146:149], v[186:189], v[60:63]
	v_mfma_f32_16x16x32_bf16 v[56:59], v[178:181], v[186:189], v[56:59]
	s_waitcnt lgkmcnt(5)
	v_mfma_f32_16x16x32_bf16 v[44:47], v[146:149], v[200:203], v[44:47]
	v_mfma_f32_16x16x32_bf16 v[40:43], v[178:181], v[200:203], v[40:43]
	s_waitcnt lgkmcnt(3)
	v_mfma_f32_16x16x32_bf16 v[28:31], v[146:149], v[208:211], v[28:31]
	v_mfma_f32_16x16x32_bf16 v[24:27], v[178:181], v[208:211], v[24:27]
	s_waitcnt lgkmcnt(1)
	v_mfma_f32_16x16x32_bf16 v[12:15], v[146:149], v[216:219], v[12:15]
	v_mfma_f32_16x16x32_bf16 v[8:11], v[178:181], v[216:219], v[8:11]
	v_mfma_f32_16x16x32_bf16 v[60:63], v[150:153], v[196:199], v[60:63]
	v_mfma_f32_16x16x32_bf16 v[56:59], v[182:185], v[196:199], v[56:59]
	v_mfma_f32_16x16x32_bf16 v[44:47], v[150:153], v[204:207], v[44:47]
	v_mfma_f32_16x16x32_bf16 v[40:43], v[182:185], v[204:207], v[40:43]
	v_mfma_f32_16x16x32_bf16 v[28:31], v[150:153], v[212:215], v[28:31]
	v_mfma_f32_16x16x32_bf16 v[24:27], v[182:185], v[212:215], v[24:27]
	s_waitcnt lgkmcnt(0)
	v_mfma_f32_16x16x32_bf16 v[12:15], v[150:153], v[220:223], v[12:15]
	v_mfma_f32_16x16x32_bf16 v[8:11], v[182:185], v[220:223], v[8:11]
	s_barrier
	s_add_u32 s42, s42, 0x40080
	s_addc_u32 s43, s43, 0
	s_add_i32 s28, s29, s11
	v_lshl_add_u64 v[146:147], s[42:43], 0, v[132:133]
	s_mov_b32 m0, s28
	s_nop 0
	global_load_lds_dwordx4 v[146:147], off
	v_lshl_add_u64 v[146:147], s[42:43], 0, v[128:129]
	s_add_i32 m0, s28, 0x2000
	s_nop 0
	global_load_lds_dwordx4 v[146:147], off
	s_waitcnt vmcnt(6)
	s_barrier
	v_mfma_f32_16x16x32_bf16 v[52:55], v[224:227], v[186:189], v[52:55]
	v_mfma_f32_16x16x32_bf16 v[48:51], v[232:235], v[186:189], v[48:51]
	v_mfma_f32_16x16x32_bf16 v[36:39], v[224:227], v[200:203], v[36:39]
	v_mfma_f32_16x16x32_bf16 v[32:35], v[232:235], v[200:203], v[32:35]
	v_mfma_f32_16x16x32_bf16 v[20:23], v[224:227], v[208:211], v[20:23]
	v_mfma_f32_16x16x32_bf16 v[16:19], v[232:235], v[208:211], v[16:19]
	v_mfma_f32_16x16x32_bf16 v[4:7], v[224:227], v[216:219], v[4:7]
	v_mfma_f32_16x16x32_bf16 v[0:3], v[232:235], v[216:219], v[0:3]
	v_mfma_f32_16x16x32_bf16 v[52:55], v[228:231], v[196:199], v[52:55]
	v_mfma_f32_16x16x32_bf16 v[48:51], v[236:239], v[196:199], v[48:51]
	v_mfma_f32_16x16x32_bf16 v[36:39], v[228:231], v[204:207], v[36:39]
	v_mfma_f32_16x16x32_bf16 v[32:35], v[236:239], v[204:207], v[32:35]
	v_mfma_f32_16x16x32_bf16 v[20:23], v[228:231], v[212:215], v[20:23]
	v_mfma_f32_16x16x32_bf16 v[16:19], v[236:239], v[212:215], v[16:19]
	v_mfma_f32_16x16x32_bf16 v[4:7], v[228:231], v[220:223], v[4:7]
	v_mfma_f32_16x16x32_bf16 v[0:3], v[236:239], v[220:223], v[0:3]
	s_add_i32 s64, s64, 2
	s_add_u32 s0, s0, 0x100
	s_addc_u32 s1, s1, 0
	s_add_u32 s62, s62, 0x100
	s_addc_u32 s63, s63, 0
	s_cmp_gt_u32 s64, 13
	s_barrier
	s_cbranch_scc0 .LBB0_1093
	v_lshl_add_u32 v168, s4, 8, v155
	v_or_b32_e32 v164, 16, v168
	v_or_b32_e32 v160, 32, v168
	v_or_b32_e32 v156, 48, v168
	v_add_u32_e32 v152, 0x80, v168
	v_add_u32_e32 v150, 0x90, v168
	v_add_u32_e32 v148, 0xa0, v168
	v_add_u32_e32 v146, 0xb0, v168
	v_lshl_or_b32 v172, s5, 7, v163
	v_mov_b32_e32 v178, v240
	v_mov_b32_e32 v179, v240
	v_mov_b32_e32 v154, v241
	s_and_b32 s0, s36, 0x7f
	v_lshl_add_u32 v228, s0, 8, v155
	v_mov_b32_e32 v229, 0
	v_lshlrev_b32_e32 v228, 6, v228
	v_lshl_add_u64 v[230:231], v[136:137], 0, v[228:229]
	v_mov_b32_e32 v228, 0x2000
	v_lshl_add_u64 v[232:233], v[230:231], 0, v[228:229]
	global_load_dwordx4 v[216:219], v[230:231], off
	global_load_dwordx4 v[220:223], v[230:231], off offset:1024
	global_load_dwordx4 v[224:227], v[230:231], off offset:2048
	global_load_dwordx4 v[196:199], v[230:231], off offset:3072
	global_load_dwordx4 v[200:203], v[232:233], off
	global_load_dwordx4 v[204:207], v[232:233], off offset:1024
	global_load_dwordx4 v[208:211], v[232:233], off offset:2048
	global_load_dwordx4 v[212:215], v[232:233], off offset:3072
	v_pk_mul_f32 v[124:125], v[124:125], v[178:179] op_sel_hi:[1,0]
	v_pk_mul_f32 v[126:127], v[126:127], v[178:179] op_sel_hi:[1,0]
	v_mul_f32_e32 v147, 0xbfb8aa3b, v124
	v_exp_f32_e32 v147, v147
	v_mul_f32_e32 v149, 0xbfb8aa3b, v125
	v_exp_f32_e32 v149, v149
	v_mul_f32_e32 v151, 0xbfb8aa3b, v127
	v_add_f32_e32 v147, 1.0, v147
	v_rcp_f32_e32 v180, v147
	v_add_f32_e32 v147, 1.0, v149
	v_mul_f32_e32 v149, 0xbfb8aa3b, v126
	v_exp_f32_e32 v149, v149
	v_exp_f32_e32 v151, v151
	v_rcp_f32_e32 v181, v147
	v_pk_mul_f32 v[116:117], v[116:117], v[178:179] op_sel_hi:[1,0]
	v_add_f32_e32 v147, 1.0, v149
	v_rcp_f32_e32 v182, v147
	v_add_f32_e32 v147, 1.0, v151
	v_rcp_f32_e32 v183, v147
	v_pk_mul_f32 v[124:125], v[124:125], v[180:181]
	v_pk_mul_f32 v[120:121], v[120:121], v[178:179] op_sel_hi:[1,0]
	v_pk_mul_f32 v[116:117], v[116:117], v[124:125]
	v_pk_mul_f32 v[124:125], v[126:127], v[182:183]
	v_mul_f32_e32 v126, 0xbfb8aa3b, v120
	v_exp_f32_e32 v126, v126
	v_pk_mul_f32 v[118:119], v[118:119], v[178:179] op_sel_hi:[1,0]
	v_pk_mul_f32 v[122:123], v[122:123], v[178:179] op_sel_hi:[1,0]
	v_pk_mul_f32 v[118:119], v[118:119], v[124:125]
	v_mul_f32_e32 v124, 0xbfb8aa3b, v121
	v_exp_f32_e32 v125, v124
	v_add_f32_e32 v124, 1.0, v126
	v_mul_f32_e32 v126, 0xbfb8aa3b, v122
	v_mul_f32_e32 v127, 0xbfb8aa3b, v123
	v_exp_f32_e32 v126, v126
	v_exp_f32_e32 v127, v127
	v_add_f32_e32 v125, 1.0, v125
	v_rcp_f32_e32 v124, v124
	v_rcp_f32_e32 v125, v125
	v_add_f32_e32 v126, 1.0, v126
	v_add_f32_e32 v127, 1.0, v127
	v_rcp_f32_e32 v126, v126
	v_rcp_f32_e32 v127, v127
	v_pk_mul_f32 v[112:113], v[112:113], v[178:179] op_sel_hi:[1,0]
	v_pk_mul_f32 v[120:121], v[120:121], v[124:125]
	v_pk_mul_f32 v[114:115], v[114:115], v[178:179] op_sel_hi:[1,0]
	v_pk_mul_f32 v[112:113], v[112:113], v[120:121]
	v_pk_mul_f32 v[120:121], v[122:123], v[126:127]
	v_ashrrev_i32_e32 v173, 31, v172
	v_pk_mul_f32 v[114:115], v[114:115], v[120:121]
	v_cvt_pk_bf16_f32 v116, v116, v117
	v_cvt_pk_bf16_f32 v117, v118, v119
	v_cvt_pk_bf16_f32 v118, v112, v113
	v_mov_b64_e32 v[112:113], s[20:21]
	v_cvt_pk_bf16_f32 v119, v114, v115
	v_mad_i64_i32 v[120:121], s[0:1], v168, s59, v[112:113]
	v_lshlrev_b64 v[114:115], 1, v[172:173]
	v_lshl_add_u64 v[120:121], v[120:121], 0, v[114:115]
	v_pk_mul_f32 v[108:109], v[108:109], v[176:177] op_sel_hi:[1,0]
	global_store_dwordx4 v[120:121], v[116:119], off
	v_mul_f32_e32 v122, 0xbfb8aa3b, v108
	v_pk_mul_f32 v[110:111], v[110:111], v[176:177] op_sel_hi:[1,0]
	v_mul_f32_e32 v116, 0xbfb8aa3b, v109
	v_exp_f32_e32 v122, v122
	v_exp_f32_e32 v117, v116
	v_mul_f32_e32 v118, 0xbfb8aa3b, v110
	v_mul_f32_e32 v119, 0xbfb8aa3b, v111
	v_exp_f32_e32 v118, v118
	v_exp_f32_e32 v119, v119
	v_add_f32_e32 v116, 1.0, v122
	v_add_f32_e32 v117, 1.0, v117
	v_rcp_f32_e32 v116, v116
	v_rcp_f32_e32 v117, v117
	v_add_f32_e32 v118, 1.0, v118
	v_add_f32_e32 v119, 1.0, v119
	v_rcp_f32_e32 v118, v118
	v_rcp_f32_e32 v119, v119
	v_pk_mul_f32 v[100:101], v[100:101], v[176:177] op_sel_hi:[1,0]
	v_pk_mul_f32 v[108:109], v[108:109], v[116:117]
	v_pk_mul_f32 v[104:105], v[104:105], v[176:177] op_sel_hi:[1,0]
	v_pk_mul_f32 v[100:101], v[100:101], v[108:109]
	v_pk_mul_f32 v[108:109], v[110:111], v[118:119]
	v_mul_f32_e32 v110, 0xbfb8aa3b, v104
	v_exp_f32_e32 v110, v110
	v_pk_mul_f32 v[102:103], v[102:103], v[176:177] op_sel_hi:[1,0]
	v_pk_mul_f32 v[106:107], v[106:107], v[176:177] op_sel_hi:[1,0]
	v_pk_mul_f32 v[102:103], v[102:103], v[108:109]
	v_mul_f32_e32 v108, 0xbfb8aa3b, v105
	v_exp_f32_e32 v109, v108
	v_add_f32_e32 v108, 1.0, v110
	v_mul_f32_e32 v110, 0xbfb8aa3b, v106
	v_mul_f32_e32 v111, 0xbfb8aa3b, v107
	v_exp_f32_e32 v110, v110
	v_exp_f32_e32 v111, v111
	v_add_f32_e32 v109, 1.0, v109
	v_rcp_f32_e32 v108, v108
	v_rcp_f32_e32 v109, v109
	v_add_f32_e32 v110, 1.0, v110
	v_add_f32_e32 v111, 1.0, v111
	v_rcp_f32_e32 v110, v110
	v_rcp_f32_e32 v111, v111
	v_pk_mul_f32 v[96:97], v[96:97], v[176:177] op_sel_hi:[1,0]
	v_pk_mul_f32 v[104:105], v[104:105], v[108:109]
	v_pk_mul_f32 v[92:93], v[92:93], v[174:175] op_sel_hi:[1,0]
	v_pk_mul_f32 v[104:105], v[96:97], v[104:105]
	v_pk_mul_f32 v[96:97], v[98:99], v[176:177] op_sel_hi:[1,0]
	v_pk_mul_f32 v[98:99], v[106:107], v[110:111]
	v_pk_mul_f32 v[94:95], v[94:95], v[174:175] op_sel_hi:[1,0]
	v_pk_mul_f32 v[106:107], v[96:97], v[98:99]
	v_cvt_pk_bf16_f32 v96, v100, v101
	v_mad_i64_i32 v[100:101], s[0:1], v164, s59, v[112:113]
	v_cvt_pk_bf16_f32 v97, v102, v103
	v_cvt_pk_bf16_f32 v98, v104, v105
	v_cvt_pk_bf16_f32 v99, v106, v107
	v_lshl_add_u64 v[100:101], v[100:101], 0, v[114:115]
	v_mul_f32_e32 v102, 0xbfb8aa3b, v92
	global_store_dwordx4 v[100:101], v[96:99], off
	v_exp_f32_e32 v102, v102
	v_pk_mul_f32 v[84:85], v[84:85], v[174:175] op_sel_hi:[1,0]
	v_mul_f32_e32 v96, 0xbfb8aa3b, v93
	v_exp_f32_e32 v97, v96
	v_mul_f32_e32 v98, 0xbfb8aa3b, v94
	v_mul_f32_e32 v99, 0xbfb8aa3b, v95
	v_exp_f32_e32 v98, v98
	v_exp_f32_e32 v99, v99
	v_add_f32_e32 v96, 1.0, v102
	v_add_f32_e32 v97, 1.0, v97
	v_rcp_f32_e32 v96, v96
	v_rcp_f32_e32 v97, v97
	v_add_f32_e32 v98, 1.0, v98
	v_add_f32_e32 v99, 1.0, v99
	v_rcp_f32_e32 v98, v98
	v_rcp_f32_e32 v99, v99
	v_pk_mul_f32 v[92:93], v[92:93], v[96:97]
	v_pk_mul_f32 v[88:89], v[88:89], v[174:175] op_sel_hi:[1,0]
	v_pk_mul_f32 v[84:85], v[84:85], v[92:93]
	v_pk_mul_f32 v[92:93], v[94:95], v[98:99]
	v_mul_f32_e32 v94, 0xbfb8aa3b, v88
	v_exp_f32_e32 v94, v94
	v_pk_mul_f32 v[86:87], v[86:87], v[174:175] op_sel_hi:[1,0]
	v_pk_mul_f32 v[90:91], v[90:91], v[174:175] op_sel_hi:[1,0]
	v_pk_mul_f32 v[86:87], v[86:87], v[92:93]
	v_mul_f32_e32 v92, 0xbfb8aa3b, v89
	v_exp_f32_e32 v93, v92
	v_add_f32_e32 v92, 1.0, v94
	v_mul_f32_e32 v94, 0xbfb8aa3b, v90
	v_mul_f32_e32 v95, 0xbfb8aa3b, v91
	v_exp_f32_e32 v94, v94
	v_exp_f32_e32 v95, v95
	v_add_f32_e32 v93, 1.0, v93
	v_rcp_f32_e32 v92, v92
	v_rcp_f32_e32 v93, v93
	v_add_f32_e32 v94, 1.0, v94
	v_add_f32_e32 v95, 1.0, v95
	v_rcp_f32_e32 v94, v94
	v_rcp_f32_e32 v95, v95
	v_pk_mul_f32 v[80:81], v[80:81], v[174:175] op_sel_hi:[1,0]
	v_pk_mul_f32 v[88:89], v[88:89], v[92:93]
	v_pk_mul_f32 v[76:77], v[76:77], v[170:171] op_sel_hi:[1,0]
	v_pk_mul_f32 v[88:89], v[80:81], v[88:89]
	v_pk_mul_f32 v[80:81], v[82:83], v[174:175] op_sel_hi:[1,0]
	v_pk_mul_f32 v[82:83], v[90:91], v[94:95]
	v_pk_mul_f32 v[78:79], v[78:79], v[170:171] op_sel_hi:[1,0]
	v_pk_mul_f32 v[90:91], v[80:81], v[82:83]
	v_cvt_pk_bf16_f32 v80, v84, v85
	v_mad_i64_i32 v[84:85], s[0:1], v160, s59, v[112:113]
	v_cvt_pk_bf16_f32 v81, v86, v87
	v_cvt_pk_bf16_f32 v82, v88, v89
	v_cvt_pk_bf16_f32 v83, v90, v91
	v_lshl_add_u64 v[84:85], v[84:85], 0, v[114:115]
	v_mul_f32_e32 v86, 0xbfb8aa3b, v76
	global_store_dwordx4 v[84:85], v[80:83], off
	v_exp_f32_e32 v86, v86
	v_pk_mul_f32 v[68:69], v[68:69], v[170:171] op_sel_hi:[1,0]
	v_mul_f32_e32 v80, 0xbfb8aa3b, v77
	v_exp_f32_e32 v81, v80
	v_mul_f32_e32 v82, 0xbfb8aa3b, v78
	v_mul_f32_e32 v83, 0xbfb8aa3b, v79
	v_exp_f32_e32 v82, v82
	v_exp_f32_e32 v83, v83
	v_add_f32_e32 v80, 1.0, v86
	v_add_f32_e32 v81, 1.0, v81
	v_rcp_f32_e32 v80, v80
	v_rcp_f32_e32 v81, v81
	v_add_f32_e32 v82, 1.0, v82
	v_add_f32_e32 v83, 1.0, v83
	v_rcp_f32_e32 v82, v82
	v_rcp_f32_e32 v83, v83
	v_pk_mul_f32 v[76:77], v[76:77], v[80:81]
	v_pk_mul_f32 v[72:73], v[72:73], v[170:171] op_sel_hi:[1,0]
	v_pk_mul_f32 v[68:69], v[68:69], v[76:77]
	v_pk_mul_f32 v[76:77], v[78:79], v[82:83]
	v_mul_f32_e32 v78, 0xbfb8aa3b, v72
	v_exp_f32_e32 v78, v78
	v_pk_mul_f32 v[70:71], v[70:71], v[170:171] op_sel_hi:[1,0]
	v_pk_mul_f32 v[74:75], v[74:75], v[170:171] op_sel_hi:[1,0]
	v_pk_mul_f32 v[70:71], v[70:71], v[76:77]
	v_mul_f32_e32 v76, 0xbfb8aa3b, v73
	v_exp_f32_e32 v77, v76
	v_add_f32_e32 v76, 1.0, v78
	v_mul_f32_e32 v78, 0xbfb8aa3b, v74
	v_mul_f32_e32 v79, 0xbfb8aa3b, v75
	v_exp_f32_e32 v78, v78
	v_exp_f32_e32 v79, v79
	v_add_f32_e32 v77, 1.0, v77
	v_rcp_f32_e32 v76, v76
	v_rcp_f32_e32 v77, v77
	v_add_f32_e32 v78, 1.0, v78
	v_add_f32_e32 v79, 1.0, v79
	v_rcp_f32_e32 v78, v78
	v_rcp_f32_e32 v79, v79
	v_pk_mul_f32 v[64:65], v[64:65], v[170:171] op_sel_hi:[1,0]
	v_pk_mul_f32 v[72:73], v[72:73], v[76:77]
	v_pk_mul_f32 v[60:61], v[60:61], v[166:167] op_sel_hi:[1,0]
	v_pk_mul_f32 v[72:73], v[64:65], v[72:73]
	v_pk_mul_f32 v[64:65], v[66:67], v[170:171] op_sel_hi:[1,0]
	v_pk_mul_f32 v[66:67], v[74:75], v[78:79]
	v_pk_mul_f32 v[62:63], v[62:63], v[166:167] op_sel_hi:[1,0]
	v_pk_mul_f32 v[74:75], v[64:65], v[66:67]
	v_cvt_pk_bf16_f32 v64, v68, v69
	v_mad_i64_i32 v[68:69], s[0:1], v156, s59, v[112:113]
	v_cvt_pk_bf16_f32 v65, v70, v71
	v_cvt_pk_bf16_f32 v66, v72, v73
	v_cvt_pk_bf16_f32 v67, v74, v75
	v_lshl_add_u64 v[68:69], v[68:69], 0, v[114:115]
	v_mul_f32_e32 v70, 0xbfb8aa3b, v60
	global_store_dwordx4 v[68:69], v[64:67], off
	v_exp_f32_e32 v70, v70
	v_pk_mul_f32 v[52:53], v[52:53], v[166:167] op_sel_hi:[1,0]
	v_mul_f32_e32 v64, 0xbfb8aa3b, v61
	v_exp_f32_e32 v65, v64
	v_mul_f32_e32 v66, 0xbfb8aa3b, v62
	v_mul_f32_e32 v67, 0xbfb8aa3b, v63
	v_exp_f32_e32 v66, v66
	v_exp_f32_e32 v67, v67
	v_add_f32_e32 v64, 1.0, v70
	v_add_f32_e32 v65, 1.0, v65
	v_rcp_f32_e32 v64, v64
	v_rcp_f32_e32 v65, v65
	v_add_f32_e32 v66, 1.0, v66
	v_add_f32_e32 v67, 1.0, v67
	v_rcp_f32_e32 v66, v66
	v_rcp_f32_e32 v67, v67
	v_pk_mul_f32 v[60:61], v[60:61], v[64:65]
	v_pk_mul_f32 v[56:57], v[56:57], v[166:167] op_sel_hi:[1,0]
	v_pk_mul_f32 v[52:53], v[52:53], v[60:61]
	v_pk_mul_f32 v[60:61], v[62:63], v[66:67]
	v_mul_f32_e32 v62, 0xbfb8aa3b, v56
	v_exp_f32_e32 v62, v62
	v_pk_mul_f32 v[54:55], v[54:55], v[166:167] op_sel_hi:[1,0]
	v_pk_mul_f32 v[58:59], v[58:59], v[166:167] op_sel_hi:[1,0]
	v_pk_mul_f32 v[54:55], v[54:55], v[60:61]
	v_mul_f32_e32 v60, 0xbfb8aa3b, v57
	v_exp_f32_e32 v61, v60
	v_add_f32_e32 v60, 1.0, v62
	v_mul_f32_e32 v62, 0xbfb8aa3b, v58
	v_mul_f32_e32 v63, 0xbfb8aa3b, v59
	v_exp_f32_e32 v62, v62
	v_exp_f32_e32 v63, v63
	v_add_f32_e32 v61, 1.0, v61
	v_rcp_f32_e32 v60, v60
	v_rcp_f32_e32 v61, v61
	v_add_f32_e32 v62, 1.0, v62
	v_add_f32_e32 v63, 1.0, v63
	v_rcp_f32_e32 v62, v62
	v_rcp_f32_e32 v63, v63
	v_pk_mul_f32 v[48:49], v[48:49], v[166:167] op_sel_hi:[1,0]
	v_pk_mul_f32 v[56:57], v[56:57], v[60:61]
	v_pk_mul_f32 v[44:45], v[44:45], v[162:163] op_sel_hi:[1,0]
	v_pk_mul_f32 v[56:57], v[48:49], v[56:57]
	v_pk_mul_f32 v[48:49], v[50:51], v[166:167] op_sel_hi:[1,0]
	v_pk_mul_f32 v[50:51], v[58:59], v[62:63]
	v_pk_mul_f32 v[46:47], v[46:47], v[162:163] op_sel_hi:[1,0]
	v_pk_mul_f32 v[58:59], v[48:49], v[50:51]
	v_cvt_pk_bf16_f32 v48, v52, v53
	v_mad_i64_i32 v[52:53], s[0:1], v152, s59, v[112:113]
	v_cvt_pk_bf16_f32 v49, v54, v55
	v_cvt_pk_bf16_f32 v50, v56, v57
	v_cvt_pk_bf16_f32 v51, v58, v59
	v_lshl_add_u64 v[52:53], v[52:53], 0, v[114:115]
	v_mul_f32_e32 v54, 0xbfb8aa3b, v44
	global_store_dwordx4 v[52:53], v[48:51], off
	v_exp_f32_e32 v54, v54
	v_pk_mul_f32 v[36:37], v[36:37], v[162:163] op_sel_hi:[1,0]
	v_mul_f32_e32 v48, 0xbfb8aa3b, v45
	v_exp_f32_e32 v49, v48
	v_mul_f32_e32 v50, 0xbfb8aa3b, v46
	v_mul_f32_e32 v51, 0xbfb8aa3b, v47
	v_exp_f32_e32 v50, v50
	v_exp_f32_e32 v51, v51
	v_add_f32_e32 v48, 1.0, v54
	v_add_f32_e32 v49, 1.0, v49
	v_rcp_f32_e32 v48, v48
	v_rcp_f32_e32 v49, v49
	v_add_f32_e32 v50, 1.0, v50
	v_add_f32_e32 v51, 1.0, v51
	v_rcp_f32_e32 v50, v50
	v_rcp_f32_e32 v51, v51
	v_pk_mul_f32 v[44:45], v[44:45], v[48:49]
	v_pk_mul_f32 v[40:41], v[40:41], v[162:163] op_sel_hi:[1,0]
	v_pk_mul_f32 v[36:37], v[36:37], v[44:45]
	v_pk_mul_f32 v[44:45], v[46:47], v[50:51]
	v_mul_f32_e32 v46, 0xbfb8aa3b, v40
	v_exp_f32_e32 v46, v46
	v_pk_mul_f32 v[38:39], v[38:39], v[162:163] op_sel_hi:[1,0]
	v_pk_mul_f32 v[42:43], v[42:43], v[162:163] op_sel_hi:[1,0]
	v_pk_mul_f32 v[38:39], v[38:39], v[44:45]
	v_mul_f32_e32 v44, 0xbfb8aa3b, v41
	v_exp_f32_e32 v45, v44
	v_add_f32_e32 v44, 1.0, v46
	v_mul_f32_e32 v46, 0xbfb8aa3b, v42
	v_mul_f32_e32 v47, 0xbfb8aa3b, v43
	v_exp_f32_e32 v46, v46
	v_exp_f32_e32 v47, v47
	v_add_f32_e32 v45, 1.0, v45
	v_rcp_f32_e32 v44, v44
	v_rcp_f32_e32 v45, v45
	v_add_f32_e32 v46, 1.0, v46
	v_add_f32_e32 v47, 1.0, v47
	v_rcp_f32_e32 v46, v46
	v_rcp_f32_e32 v47, v47
	v_pk_mul_f32 v[32:33], v[32:33], v[162:163] op_sel_hi:[1,0]
	v_pk_mul_f32 v[40:41], v[40:41], v[44:45]
	v_pk_mul_f32 v[28:29], v[28:29], v[158:159] op_sel_hi:[1,0]
	v_pk_mul_f32 v[40:41], v[32:33], v[40:41]
	v_pk_mul_f32 v[32:33], v[34:35], v[162:163] op_sel_hi:[1,0]
	v_pk_mul_f32 v[34:35], v[42:43], v[46:47]
	v_pk_mul_f32 v[30:31], v[30:31], v[158:159] op_sel_hi:[1,0]
	v_pk_mul_f32 v[42:43], v[32:33], v[34:35]
	v_cvt_pk_bf16_f32 v32, v36, v37
	v_mad_i64_i32 v[36:37], s[0:1], v150, s59, v[112:113]
	v_cvt_pk_bf16_f32 v33, v38, v39
	v_cvt_pk_bf16_f32 v34, v40, v41
	v_cvt_pk_bf16_f32 v35, v42, v43
	v_lshl_add_u64 v[36:37], v[36:37], 0, v[114:115]
	v_mul_f32_e32 v38, 0xbfb8aa3b, v28
	global_store_dwordx4 v[36:37], v[32:35], off
	v_exp_f32_e32 v38, v38
	v_pk_mul_f32 v[20:21], v[20:21], v[158:159] op_sel_hi:[1,0]
	v_mul_f32_e32 v32, 0xbfb8aa3b, v29
	v_exp_f32_e32 v33, v32
	v_mul_f32_e32 v34, 0xbfb8aa3b, v30
	v_mul_f32_e32 v35, 0xbfb8aa3b, v31
	v_exp_f32_e32 v34, v34
	v_exp_f32_e32 v35, v35
	v_add_f32_e32 v32, 1.0, v38
	v_add_f32_e32 v33, 1.0, v33
	v_rcp_f32_e32 v32, v32
	v_rcp_f32_e32 v33, v33
	v_add_f32_e32 v34, 1.0, v34
	v_add_f32_e32 v35, 1.0, v35
	v_rcp_f32_e32 v34, v34
	v_rcp_f32_e32 v35, v35
	v_pk_mul_f32 v[28:29], v[28:29], v[32:33]
	v_pk_mul_f32 v[24:25], v[24:25], v[158:159] op_sel_hi:[1,0]
	v_pk_mul_f32 v[20:21], v[20:21], v[28:29]
	v_pk_mul_f32 v[28:29], v[30:31], v[34:35]
	v_mul_f32_e32 v30, 0xbfb8aa3b, v24
	v_exp_f32_e32 v30, v30
	v_pk_mul_f32 v[22:23], v[22:23], v[158:159] op_sel_hi:[1,0]
	v_pk_mul_f32 v[26:27], v[26:27], v[158:159] op_sel_hi:[1,0]
	v_pk_mul_f32 v[22:23], v[22:23], v[28:29]
	v_mul_f32_e32 v28, 0xbfb8aa3b, v25
	v_exp_f32_e32 v29, v28
	v_add_f32_e32 v28, 1.0, v30
	v_mul_f32_e32 v30, 0xbfb8aa3b, v26
	v_mul_f32_e32 v31, 0xbfb8aa3b, v27
	v_exp_f32_e32 v30, v30
	v_exp_f32_e32 v31, v31
	v_add_f32_e32 v29, 1.0, v29
	v_rcp_f32_e32 v28, v28
	v_rcp_f32_e32 v29, v29
	v_add_f32_e32 v30, 1.0, v30
	v_add_f32_e32 v31, 1.0, v31
	v_rcp_f32_e32 v30, v30
	v_rcp_f32_e32 v31, v31
	v_pk_mul_f32 v[16:17], v[16:17], v[158:159] op_sel_hi:[1,0]
	v_pk_mul_f32 v[24:25], v[24:25], v[28:29]
	v_pk_mul_f32 v[12:13], v[12:13], v[154:155] op_sel_hi:[1,0]
	v_pk_mul_f32 v[24:25], v[16:17], v[24:25]
	v_pk_mul_f32 v[16:17], v[18:19], v[158:159] op_sel_hi:[1,0]
	v_pk_mul_f32 v[18:19], v[26:27], v[30:31]
	v_pk_mul_f32 v[14:15], v[14:15], v[154:155] op_sel_hi:[1,0]
	v_pk_mul_f32 v[26:27], v[16:17], v[18:19]
	v_cvt_pk_bf16_f32 v16, v20, v21
	v_mad_i64_i32 v[20:21], s[0:1], v148, s59, v[112:113]
	v_cvt_pk_bf16_f32 v17, v22, v23
	v_cvt_pk_bf16_f32 v18, v24, v25
	v_cvt_pk_bf16_f32 v19, v26, v27
	v_lshl_add_u64 v[20:21], v[20:21], 0, v[114:115]
	v_mul_f32_e32 v22, 0xbfb8aa3b, v12
	global_store_dwordx4 v[20:21], v[16:19], off
	v_exp_f32_e32 v22, v22
	v_pk_mul_f32 v[4:5], v[4:5], v[154:155] op_sel_hi:[1,0]
	v_mul_f32_e32 v16, 0xbfb8aa3b, v13
	v_exp_f32_e32 v17, v16
	v_mul_f32_e32 v18, 0xbfb8aa3b, v14
	v_mul_f32_e32 v19, 0xbfb8aa3b, v15
	v_exp_f32_e32 v18, v18
	v_exp_f32_e32 v19, v19
	v_add_f32_e32 v16, 1.0, v22
	v_add_f32_e32 v17, 1.0, v17
	v_rcp_f32_e32 v16, v16
	v_rcp_f32_e32 v17, v17
	v_add_f32_e32 v18, 1.0, v18
	v_add_f32_e32 v19, 1.0, v19
	v_rcp_f32_e32 v18, v18
	v_rcp_f32_e32 v19, v19
	v_pk_mul_f32 v[12:13], v[12:13], v[16:17]
	v_pk_mul_f32 v[8:9], v[8:9], v[154:155] op_sel_hi:[1,0]
	v_pk_mul_f32 v[4:5], v[4:5], v[12:13]
	v_pk_mul_f32 v[12:13], v[14:15], v[18:19]
	v_mul_f32_e32 v14, 0xbfb8aa3b, v8
	v_exp_f32_e32 v14, v14
	v_pk_mul_f32 v[6:7], v[6:7], v[154:155] op_sel_hi:[1,0]
	v_pk_mul_f32 v[10:11], v[10:11], v[154:155] op_sel_hi:[1,0]
	v_pk_mul_f32 v[6:7], v[6:7], v[12:13]
	v_mul_f32_e32 v12, 0xbfb8aa3b, v9
	v_exp_f32_e32 v13, v12
	v_add_f32_e32 v12, 1.0, v14
	v_mul_f32_e32 v14, 0xbfb8aa3b, v10
	v_mul_f32_e32 v15, 0xbfb8aa3b, v11
	v_exp_f32_e32 v14, v14
	v_exp_f32_e32 v15, v15
	v_add_f32_e32 v13, 1.0, v13
	v_rcp_f32_e32 v12, v12
	v_rcp_f32_e32 v13, v13
	v_add_f32_e32 v14, 1.0, v14
	v_add_f32_e32 v15, 1.0, v15
	v_rcp_f32_e32 v14, v14
	v_rcp_f32_e32 v15, v15
	v_pk_mul_f32 v[0:1], v[0:1], v[154:155] op_sel_hi:[1,0]
	v_pk_mul_f32 v[8:9], v[8:9], v[12:13]
	s_and_b64 vcc, exec, s[2:3]
	v_pk_mul_f32 v[8:9], v[0:1], v[8:9]
	v_pk_mul_f32 v[0:1], v[2:3], v[154:155] op_sel_hi:[1,0]
	v_pk_mul_f32 v[2:3], v[10:11], v[14:15]
	s_mov_b32 s5, s12
	v_pk_mul_f32 v[10:11], v[0:1], v[2:3]
	v_cvt_pk_bf16_f32 v0, v4, v5
	v_mad_i64_i32 v[4:5], s[0:1], v146, s59, v[112:113]
	v_cvt_pk_bf16_f32 v1, v6, v7
	v_cvt_pk_bf16_f32 v2, v8, v9
	v_cvt_pk_bf16_f32 v3, v10, v11
	v_lshl_add_u64 v[4:5], v[4:5], 0, v[114:115]
	s_mov_b32 s4, s36
	s_mov_b64 s[42:43], s[40:41]
	s_mov_b64 s[44:45], s[38:39]
	global_store_dwordx4 v[4:5], v[0:3], off
	s_waitcnt vmcnt(8)
	v_xor_b32_e32 v184, 16, v177
	v_xor_b32_e32 v185, 32, v177
	v_lshlrev_b32_e32 v184, 2, v184
	v_lshlrev_b32_e32 v185, 2, v185
	v_mov_b32_e32 v190, s10
	v_pk_add_f32 v[216:217], v[216:217], v[218:219]
	v_pk_add_f32 v[220:221], v[220:221], v[222:223]
	v_pk_add_f32 v[224:225], v[224:225], v[226:227]
	v_pk_add_f32 v[196:197], v[196:197], v[198:199]
	v_pk_add_f32 v[200:201], v[200:201], v[202:203]
	v_pk_add_f32 v[204:205], v[204:205], v[206:207]
	v_pk_add_f32 v[208:209], v[208:209], v[210:211]
	v_pk_add_f32 v[212:213], v[212:213], v[214:215]
	v_add_f32_e32 v216, v216, v217
	v_add_f32_e32 v220, v220, v221
	v_add_f32_e32 v224, v224, v225
	v_add_f32_e32 v196, v196, v197
	v_add_f32_e32 v200, v200, v201
	v_add_f32_e32 v204, v204, v205
	v_add_f32_e32 v208, v208, v209
	v_add_f32_e32 v212, v212, v213
	ds_bpermute_b32 v218, v184, v216
	ds_bpermute_b32 v219, v184, v220
	ds_bpermute_b32 v222, v184, v224
	ds_bpermute_b32 v223, v184, v196
	ds_bpermute_b32 v226, v184, v200
	ds_bpermute_b32 v227, v184, v204
	ds_bpermute_b32 v198, v184, v208
	ds_bpermute_b32 v199, v184, v212
	s_waitcnt lgkmcnt(0)
	v_add_f32_e32 v216, v216, v218
	v_add_f32_e32 v220, v220, v219
	v_add_f32_e32 v224, v224, v222
	v_add_f32_e32 v196, v196, v223
	v_add_f32_e32 v200, v200, v226
	v_add_f32_e32 v204, v204, v227
	v_add_f32_e32 v208, v208, v198
	v_add_f32_e32 v212, v212, v199
	ds_bpermute_b32 v218, v185, v216
	ds_bpermute_b32 v219, v185, v220
	ds_bpermute_b32 v222, v185, v224
	ds_bpermute_b32 v223, v185, v196
	ds_bpermute_b32 v226, v185, v200
	ds_bpermute_b32 v227, v185, v204
	ds_bpermute_b32 v198, v185, v208
	ds_bpermute_b32 v199, v185, v212
	s_waitcnt lgkmcnt(0)
	v_add_f32_e32 v216, v216, v218
	v_add_f32_e32 v220, v220, v219
	v_add_f32_e32 v224, v224, v222
	v_add_f32_e32 v196, v196, v223
	v_add_f32_e32 v200, v200, v226
	v_add_f32_e32 v204, v204, v227
	v_add_f32_e32 v208, v208, v198
	v_add_f32_e32 v212, v212, v199
	v_fma_f32 v216, v216, s8, v190
	v_fma_f32 v220, v220, s8, v190
	v_fma_f32 v224, v224, s8, v190
	v_fma_f32 v196, v196, s8, v190
	v_fma_f32 v200, v200, s8, v190
	v_fma_f32 v204, v204, s8, v190
	v_fma_f32 v208, v208, s8, v190
	v_fma_f32 v212, v212, s8, v190
	v_rsq_f32_e32 v240, v216
	v_rsq_f32_e32 v176, v220
	v_rsq_f32_e32 v174, v224
	v_rsq_f32_e32 v170, v196
	v_rsq_f32_e32 v166, v200
	v_rsq_f32_e32 v162, v204
	v_rsq_f32_e32 v158, v208
	v_rsq_f32_e32 v241, v212
	s_and_b64 vcc, exec, s[2:3]
	s_mov_b32 s5, s12
	s_mov_b32 s4, s36
	s_cbranch_vccz .LBB0_1090
	s_waitcnt vmcnt(0)
	s_cmpk_gt_u32 s9, 0xff
	s_cbranch_scc1 .LBB0_1097
	s_barrier

.LBB0_1169:
	ds_read_b128 v[128:131], v167
	ds_read_b128 v[132:135], v167 offset:1024
	ds_read_b128 v[136:139], v167 offset:2048
	ds_read_b128 v[156:159], v167 offset:3072
	s_add_u32 s6, s40, 0x100
	s_addc_u32 s7, s41, 0
	s_cmp_eq_u32 s65, 40
	s_cselect_b32 s45, s1, s7
	s_cselect_b32 s44, s0, s6
	s_cselect_b32 s43, s39, s64
	s_cselect_b32 s42, s38, s63
	v_lshl_add_u64 v[202:203], s[40:41], 0, v[148:149]
	s_add_i32 m0, s47, 0xc000
	ds_read_b128 v[160:163], v168
	ds_read_b128 v[172:175], v168 offset:1024
	ds_read_b128 v[176:179], v168 offset:2048
	ds_read_b128 v[180:183], v168 offset:3072
	ds_read_b128 v[184:187], v168 offset:4096
	ds_read_b128 v[188:191], v168 offset:5120
	ds_read_b128 v[194:197], v168 offset:6144
	ds_read_b128 v[198:201], v168 offset:7168
	global_load_lds_dwordx4 v[202:203], off
	v_lshl_add_u64 v[202:203], s[40:41], 0, v[150:151]
	s_add_i32 m0, s47, 0xe000
	s_nop 0
	global_load_lds_dwordx4 v[202:203], off
	s_waitcnt lgkmcnt(8)
	s_barrier
	s_waitcnt lgkmcnt(7)
	v_mfma_f32_16x16x32_bf16 v[124:127], v[128:131], v[160:163], v[124:127]
	v_mfma_f32_16x16x32_bf16 v[120:123], v[136:139], v[160:163], v[120:123]
	s_waitcnt lgkmcnt(5)
	v_mfma_f32_16x16x32_bf16 v[108:111], v[128:131], v[176:179], v[108:111]
	v_mfma_f32_16x16x32_bf16 v[104:107], v[136:139], v[176:179], v[104:107]
	s_waitcnt lgkmcnt(3)
	v_mfma_f32_16x16x32_bf16 v[92:95], v[128:131], v[184:187], v[92:95]
	v_mfma_f32_16x16x32_bf16 v[88:91], v[136:139], v[184:187], v[88:91]
	s_waitcnt lgkmcnt(1)
	v_mfma_f32_16x16x32_bf16 v[76:79], v[128:131], v[194:197], v[76:79]
	v_mfma_f32_16x16x32_bf16 v[72:75], v[136:139], v[194:197], v[72:75]
	v_mfma_f32_16x16x32_bf16 v[124:127], v[132:135], v[172:175], v[124:127]
	v_mfma_f32_16x16x32_bf16 v[120:123], v[156:159], v[172:175], v[120:123]
	v_mfma_f32_16x16x32_bf16 v[108:111], v[132:135], v[180:183], v[108:111]
	v_mfma_f32_16x16x32_bf16 v[104:107], v[156:159], v[180:183], v[104:107]
	v_mfma_f32_16x16x32_bf16 v[92:95], v[132:135], v[188:191], v[92:95]
	v_mfma_f32_16x16x32_bf16 v[88:91], v[156:159], v[188:191], v[88:91]
	s_waitcnt lgkmcnt(0)
	v_mfma_f32_16x16x32_bf16 v[76:79], v[132:135], v[198:201], v[76:79]
	v_mfma_f32_16x16x32_bf16 v[72:75], v[156:159], v[198:201], v[72:75]
	s_barrier
	s_add_i32 s28, s57, s46
	v_lshl_add_u64 v[218:219], s[42:43], 0, v[142:143]
	s_mov_b32 m0, s28
	ds_read_b128 v[202:205], v169
	ds_read_b128 v[206:209], v169 offset:1024
	ds_read_b128 v[210:213], v169 offset:2048
	ds_read_b128 v[214:217], v169 offset:3072
	global_load_lds_dwordx4 v[218:219], off
	v_lshl_add_u64 v[220:221], s[42:43], 0, v[146:147]
	s_add_i32 m0, s28, 0x2000
	s_nop 0
	global_load_lds_dwordx4 v[220:221], off
	s_barrier
	s_waitcnt lgkmcnt(3)
	v_mfma_f32_16x16x32_bf16 v[116:119], v[202:205], v[160:163], v[116:119]
	s_waitcnt lgkmcnt(1)
	v_mfma_f32_16x16x32_bf16 v[112:115], v[210:213], v[160:163], v[112:115]
	v_mfma_f32_16x16x32_bf16 v[100:103], v[202:205], v[176:179], v[100:103]
	v_mfma_f32_16x16x32_bf16 v[96:99], v[210:213], v[176:179], v[96:99]
	v_mfma_f32_16x16x32_bf16 v[84:87], v[202:205], v[184:187], v[84:87]
	v_mfma_f32_16x16x32_bf16 v[80:83], v[210:213], v[184:187], v[80:83]
	v_mfma_f32_16x16x32_bf16 v[68:71], v[202:205], v[194:197], v[68:71]
	v_mfma_f32_16x16x32_bf16 v[64:67], v[210:213], v[194:197], v[64:67]
	v_mfma_f32_16x16x32_bf16 v[116:119], v[206:209], v[172:175], v[116:119]
	s_waitcnt lgkmcnt(0)
	v_mfma_f32_16x16x32_bf16 v[112:115], v[214:217], v[172:175], v[112:115]
	v_mfma_f32_16x16x32_bf16 v[100:103], v[206:209], v[180:183], v[100:103]
	v_mfma_f32_16x16x32_bf16 v[96:99], v[214:217], v[180:183], v[96:99]
	v_mfma_f32_16x16x32_bf16 v[84:87], v[206:209], v[188:191], v[84:87]
	v_mfma_f32_16x16x32_bf16 v[80:83], v[214:217], v[188:191], v[80:83]
	v_mfma_f32_16x16x32_bf16 v[68:71], v[206:209], v[198:201], v[68:71]
	v_mfma_f32_16x16x32_bf16 v[64:67], v[214:217], v[198:201], v[64:67]
	s_mov_b32 m0, s47
	v_lshl_add_u64 v[222:223], s[44:45], 0, v[140:141]
	s_barrier
	ds_read_b128 v[160:163], v168 offset:16384
	ds_read_b128 v[172:175], v168 offset:17408
	ds_read_b128 v[176:179], v168 offset:18432
	ds_read_b128 v[180:183], v168 offset:19456
	ds_read_b128 v[184:187], v168 offset:20480
	ds_read_b128 v[188:191], v168 offset:21504
	ds_read_b128 v[194:197], v168 offset:22528
	ds_read_b128 v[198:201], v168 offset:23552
	global_load_lds_dwordx4 v[222:223], off
	v_lshl_add_u64 v[224:225], s[44:45], 0, v[144:145]
	s_mov_b32 m0, s48
	s_nop 0
	global_load_lds_dwordx4 v[224:225], off
	s_barrier
	s_waitcnt lgkmcnt(7)
	v_mfma_f32_16x16x32_bf16 v[60:63], v[128:131], v[160:163], v[60:63]
	v_mfma_f32_16x16x32_bf16 v[56:59], v[136:139], v[160:163], v[56:59]
	s_waitcnt lgkmcnt(5)
	v_mfma_f32_16x16x32_bf16 v[44:47], v[128:131], v[176:179], v[44:47]
	v_mfma_f32_16x16x32_bf16 v[40:43], v[136:139], v[176:179], v[40:43]
	s_waitcnt lgkmcnt(3)
	v_mfma_f32_16x16x32_bf16 v[28:31], v[128:131], v[184:187], v[28:31]
	v_mfma_f32_16x16x32_bf16 v[24:27], v[136:139], v[184:187], v[24:27]
	s_waitcnt lgkmcnt(1)
	v_mfma_f32_16x16x32_bf16 v[12:15], v[128:131], v[194:197], v[12:15]
	v_mfma_f32_16x16x32_bf16 v[8:11], v[136:139], v[194:197], v[8:11]
	v_mfma_f32_16x16x32_bf16 v[60:63], v[132:135], v[172:175], v[60:63]
	v_mfma_f32_16x16x32_bf16 v[56:59], v[156:159], v[172:175], v[56:59]
	v_mfma_f32_16x16x32_bf16 v[44:47], v[132:135], v[180:183], v[44:47]
	v_mfma_f32_16x16x32_bf16 v[40:43], v[156:159], v[180:183], v[40:43]
	v_mfma_f32_16x16x32_bf16 v[28:31], v[132:135], v[188:191], v[28:31]
	v_mfma_f32_16x16x32_bf16 v[24:27], v[156:159], v[188:191], v[24:27]
	s_waitcnt lgkmcnt(0)
	v_mfma_f32_16x16x32_bf16 v[12:15], v[132:135], v[198:201], v[12:15]
	v_mfma_f32_16x16x32_bf16 v[8:11], v[156:159], v[198:201], v[8:11]
	s_barrier
	s_add_u32 s40, s42, 0x2c000
	s_addc_u32 s41, s43, 0
	s_add_i32 s28, s58, s46
	v_lshl_add_u64 v[128:129], s[40:41], 0, v[142:143]
	s_mov_b32 m0, s28
	s_nop 0
	global_load_lds_dwordx4 v[128:129], off
	v_lshl_add_u64 v[128:129], s[40:41], 0, v[146:147]
	s_add_i32 m0, s28, 0x2000
	s_nop 0
	global_load_lds_dwordx4 v[128:129], off
	s_waitcnt vmcnt(6)
	s_barrier
	v_mfma_f32_16x16x32_bf16 v[52:55], v[202:205], v[160:163], v[52:55]
	v_mfma_f32_16x16x32_bf16 v[48:51], v[210:213], v[160:163], v[48:51]
	v_mfma_f32_16x16x32_bf16 v[36:39], v[202:205], v[176:179], v[36:39]
	v_mfma_f32_16x16x32_bf16 v[32:35], v[210:213], v[176:179], v[32:35]
	v_mfma_f32_16x16x32_bf16 v[20:23], v[202:205], v[184:187], v[20:23]
	v_mfma_f32_16x16x32_bf16 v[16:19], v[210:213], v[184:187], v[16:19]
	v_mfma_f32_16x16x32_bf16 v[4:7], v[202:205], v[194:197], v[4:7]
	v_mfma_f32_16x16x32_bf16 v[0:3], v[210:213], v[194:197], v[0:3]
	v_mfma_f32_16x16x32_bf16 v[52:55], v[206:209], v[172:175], v[52:55]
	v_mfma_f32_16x16x32_bf16 v[48:51], v[214:217], v[172:175], v[48:51]
	v_mfma_f32_16x16x32_bf16 v[36:39], v[206:209], v[180:183], v[36:39]
	v_mfma_f32_16x16x32_bf16 v[32:35], v[214:217], v[180:183], v[32:35]
	v_mfma_f32_16x16x32_bf16 v[20:23], v[206:209], v[188:191], v[20:23]
	v_mfma_f32_16x16x32_bf16 v[16:19], v[214:217], v[188:191], v[16:19]
	v_mfma_f32_16x16x32_bf16 v[4:7], v[206:209], v[198:201], v[4:7]
	v_mfma_f32_16x16x32_bf16 v[0:3], v[214:217], v[198:201], v[0:3]
	s_add_i32 s28, 0, 0x18000
	v_add_u32_e32 v156, s28, v165
	s_barrier
	ds_read_b128 v[128:131], v156
	ds_read_b128 v[132:135], v156 offset:1024
	ds_read_b128 v[136:139], v156 offset:2048
	ds_read_b128 v[156:159], v156 offset:3072
	s_add_u32 s40, s44, 0xb0000
	s_addc_u32 s41, s45, 0
	s_mov_b32 m0, s49
	v_lshl_add_u64 v[202:203], s[40:41], 0, v[140:141]
	ds_read_b128 v[160:163], v168 offset:32768
	ds_read_b128 v[172:175], v168 offset:33792
	ds_read_b128 v[176:179], v168 offset:34816
	ds_read_b128 v[180:183], v168 offset:35840
	ds_read_b128 v[184:187], v168 offset:36864
	ds_read_b128 v[188:191], v168 offset:37888
	ds_read_b128 v[194:197], v168 offset:38912
	ds_read_b128 v[198:201], v168 offset:39936
	global_load_lds_dwordx4 v[202:203], off
	v_lshl_add_u64 v[202:203], s[40:41], 0, v[144:145]
	s_mov_b32 m0, s50
	s_nop 0
	global_load_lds_dwordx4 v[202:203], off
	s_waitcnt lgkmcnt(8)
	s_barrier
	s_waitcnt lgkmcnt(7)
	v_mfma_f32_16x16x32_bf16 v[124:127], v[128:131], v[160:163], v[124:127]
	v_mfma_f32_16x16x32_bf16 v[120:123], v[136:139], v[160:163], v[120:123]
	s_waitcnt lgkmcnt(5)
	v_mfma_f32_16x16x32_bf16 v[108:111], v[128:131], v[176:179], v[108:111]
	v_mfma_f32_16x16x32_bf16 v[104:107], v[136:139], v[176:179], v[104:107]
	s_waitcnt lgkmcnt(3)
	v_mfma_f32_16x16x32_bf16 v[92:95], v[128:131], v[184:187], v[92:95]
	v_mfma_f32_16x16x32_bf16 v[88:91], v[136:139], v[184:187], v[88:91]
	s_waitcnt lgkmcnt(1)
	v_mfma_f32_16x16x32_bf16 v[76:79], v[128:131], v[194:197], v[76:79]
	v_mfma_f32_16x16x32_bf16 v[72:75], v[136:139], v[194:197], v[72:75]
	v_mfma_f32_16x16x32_bf16 v[124:127], v[132:135], v[172:175], v[124:127]
	v_mfma_f32_16x16x32_bf16 v[120:123], v[156:159], v[172:175], v[120:123]
	v_mfma_f32_16x16x32_bf16 v[108:111], v[132:135], v[180:183], v[108:111]
	v_mfma_f32_16x16x32_bf16 v[104:107], v[156:159], v[180:183], v[104:107]
	v_mfma_f32_16x16x32_bf16 v[92:95], v[132:135], v[188:191], v[92:95]
	v_mfma_f32_16x16x32_bf16 v[88:91], v[156:159], v[188:191], v[88:91]
	s_waitcnt lgkmcnt(0)
	v_mfma_f32_16x16x32_bf16 v[76:79], v[132:135], v[198:201], v[76:79]
	v_mfma_f32_16x16x32_bf16 v[72:75], v[156:159], v[198:201], v[72:75]
	s_barrier
	s_add_i32 s29, 0, 0x1c000
	s_add_i32 s28, s28, s46
	v_add_u32_e32 v171, s29, v165
	v_lshl_add_u64 v[218:219], v[218:219], 0, s[36:37]
	s_mov_b32 m0, s28
	ds_read_b128 v[202:205], v171
	ds_read_b128 v[206:209], v171 offset:1024
	ds_read_b128 v[210:213], v171 offset:2048
	ds_read_b128 v[214:217], v171 offset:3072
	global_load_lds_dwordx4 v[218:219], off
	v_lshl_add_u64 v[218:219], v[220:221], 0, s[36:37]
	s_add_i32 m0, s28, 0x2000
	s_nop 0
	global_load_lds_dwordx4 v[218:219], off
	s_barrier
	s_waitcnt lgkmcnt(3)
	v_mfma_f32_16x16x32_bf16 v[116:119], v[202:205], v[160:163], v[116:119]
	s_waitcnt lgkmcnt(1)
	v_mfma_f32_16x16x32_bf16 v[112:115], v[210:213], v[160:163], v[112:115]
	v_mfma_f32_16x16x32_bf16 v[100:103], v[202:205], v[176:179], v[100:103]
	v_mfma_f32_16x16x32_bf16 v[96:99], v[210:213], v[176:179], v[96:99]
	v_mfma_f32_16x16x32_bf16 v[84:87], v[202:205], v[184:187], v[84:87]
	v_mfma_f32_16x16x32_bf16 v[80:83], v[210:213], v[184:187], v[80:83]
	v_mfma_f32_16x16x32_bf16 v[68:71], v[202:205], v[194:197], v[68:71]
	v_mfma_f32_16x16x32_bf16 v[64:67], v[210:213], v[194:197], v[64:67]
	v_mfma_f32_16x16x32_bf16 v[116:119], v[206:209], v[172:175], v[116:119]
	s_waitcnt lgkmcnt(0)
	v_mfma_f32_16x16x32_bf16 v[112:115], v[214:217], v[172:175], v[112:115]
	v_mfma_f32_16x16x32_bf16 v[100:103], v[206:209], v[180:183], v[100:103]
	v_mfma_f32_16x16x32_bf16 v[96:99], v[214:217], v[180:183], v[96:99]
	v_mfma_f32_16x16x32_bf16 v[84:87], v[206:209], v[188:191], v[84:87]
	v_mfma_f32_16x16x32_bf16 v[80:83], v[214:217], v[188:191], v[80:83]
	v_mfma_f32_16x16x32_bf16 v[68:71], v[206:209], v[198:201], v[68:71]
	v_mfma_f32_16x16x32_bf16 v[64:67], v[214:217], v[198:201], v[64:67]
	s_mov_b32 m0, s54
	v_lshl_add_u64 v[218:219], v[222:223], 0, s[36:37]
	s_barrier
	ds_read_b128 v[160:163], v168 offset:49152
	ds_read_b128 v[172:175], v168 offset:50176
	ds_read_b128 v[176:179], v168 offset:51200
	ds_read_b128 v[180:183], v168 offset:52224
	ds_read_b128 v[184:187], v168 offset:53248
	ds_read_b128 v[188:191], v168 offset:54272
	ds_read_b128 v[194:197], v168 offset:55296
	ds_read_b128 v[198:201], v168 offset:56320
	global_load_lds_dwordx4 v[218:219], off
	v_lshl_add_u64 v[218:219], v[224:225], 0, s[36:37]
	s_mov_b32 m0, s55
	s_nop 0
	global_load_lds_dwordx4 v[218:219], off
	s_barrier
	s_waitcnt lgkmcnt(7)
	v_mfma_f32_16x16x32_bf16 v[60:63], v[128:131], v[160:163], v[60:63]
	v_mfma_f32_16x16x32_bf16 v[56:59], v[136:139], v[160:163], v[56:59]
	s_waitcnt lgkmcnt(5)
	v_mfma_f32_16x16x32_bf16 v[44:47], v[128:131], v[176:179], v[44:47]
	v_mfma_f32_16x16x32_bf16 v[40:43], v[136:139], v[176:179], v[40:43]
	s_waitcnt lgkmcnt(3)
	v_mfma_f32_16x16x32_bf16 v[28:31], v[128:131], v[184:187], v[28:31]
	v_mfma_f32_16x16x32_bf16 v[24:27], v[136:139], v[184:187], v[24:27]
	s_waitcnt lgkmcnt(1)
	v_mfma_f32_16x16x32_bf16 v[12:15], v[128:131], v[194:197], v[12:15]
	v_mfma_f32_16x16x32_bf16 v[8:11], v[136:139], v[194:197], v[8:11]
	v_mfma_f32_16x16x32_bf16 v[60:63], v[132:135], v[172:175], v[60:63]
	v_mfma_f32_16x16x32_bf16 v[56:59], v[156:159], v[172:175], v[56:59]
	v_mfma_f32_16x16x32_bf16 v[44:47], v[132:135], v[180:183], v[44:47]
	v_mfma_f32_16x16x32_bf16 v[40:43], v[156:159], v[180:183], v[40:43]
	v_mfma_f32_16x16x32_bf16 v[28:31], v[132:135], v[188:191], v[28:31]
	v_mfma_f32_16x16x32_bf16 v[24:27], v[156:159], v[188:191], v[24:27]
	s_waitcnt lgkmcnt(0)
	v_mfma_f32_16x16x32_bf16 v[12:15], v[132:135], v[198:201], v[12:15]
	v_mfma_f32_16x16x32_bf16 v[8:11], v[156:159], v[198:201], v[8:11]
	s_barrier
	s_add_u32 s40, s42, 0x2c080
	s_addc_u32 s41, s43, 0
	s_add_i32 s28, s29, s46
	v_lshl_add_u64 v[128:129], s[40:41], 0, v[142:143]
	s_mov_b32 m0, s28
	s_nop 0
	global_load_lds_dwordx4 v[128:129], off
	v_lshl_add_u64 v[128:129], s[40:41], 0, v[146:147]
	s_add_i32 m0, s28, 0x2000
	s_nop 0
	global_load_lds_dwordx4 v[128:129], off
	s_waitcnt vmcnt(6)
	s_barrier
	v_mfma_f32_16x16x32_bf16 v[52:55], v[202:205], v[160:163], v[52:55]
	v_mfma_f32_16x16x32_bf16 v[48:51], v[210:213], v[160:163], v[48:51]
	v_mfma_f32_16x16x32_bf16 v[36:39], v[202:205], v[176:179], v[36:39]
	v_mfma_f32_16x16x32_bf16 v[32:35], v[210:213], v[176:179], v[32:35]
	v_mfma_f32_16x16x32_bf16 v[20:23], v[202:205], v[184:187], v[20:23]
	v_mfma_f32_16x16x32_bf16 v[16:19], v[210:213], v[184:187], v[16:19]
	v_mfma_f32_16x16x32_bf16 v[4:7], v[202:205], v[194:197], v[4:7]
	v_mfma_f32_16x16x32_bf16 v[0:3], v[210:213], v[194:197], v[0:3]
	v_mfma_f32_16x16x32_bf16 v[52:55], v[206:209], v[172:175], v[52:55]
	v_mfma_f32_16x16x32_bf16 v[48:51], v[214:217], v[172:175], v[48:51]
	v_mfma_f32_16x16x32_bf16 v[36:39], v[206:209], v[180:183], v[36:39]
	v_mfma_f32_16x16x32_bf16 v[32:35], v[214:217], v[180:183], v[32:35]
	v_mfma_f32_16x16x32_bf16 v[20:23], v[206:209], v[188:191], v[20:23]
	v_mfma_f32_16x16x32_bf16 v[16:19], v[214:217], v[188:191], v[16:19]
	v_mfma_f32_16x16x32_bf16 v[4:7], v[206:209], v[198:201], v[4:7]
	v_mfma_f32_16x16x32_bf16 v[0:3], v[214:217], v[198:201], v[0:3]
	s_add_i32 s65, s65, 2
	s_add_u32 s63, s63, 0x100
	s_addc_u32 s64, s64, 0
	s_cmp_gt_u32 s65, 41
	s_mov_b64 s[40:41], s[6:7]
	s_barrier
	s_cbranch_scc0 .LBB0_1169
	v_lshl_add_u32 v171, s62, 8, v164
	v_lshl_or_b32 v188, s10, 8, v166
	s_mov_b32 s63, 0xffff0000
	v_lshlrev_b32_e32 v128, 11, v171
	v_lshl_add_u32 v128, v188, 1, v128
	v_lshlrev_b32_e32 v129, 12, v171
	v_lshl_add_u32 v129, v188, 2, v129
	v_lshlrev_b32_e32 v132, 2, v188
	s_mov_b64 s[70:71], s[68:69]
	global_load_dwordx4 v[194:197], v128, s[70:71]
	global_load_dwordx4 v[198:201], v128, s[70:71] offset:64
	s_add_u32 s70, s70, 0x8000
	s_addc_u32 s71, s71, 0
	global_load_dwordx4 v[202:205], v128, s[70:71]
	global_load_dwordx4 v[206:209], v128, s[70:71] offset:64
	s_add_u32 s70, s70, 0x8000
	s_addc_u32 s71, s71, 0
	global_load_dwordx4 v[210:213], v128, s[70:71]
	global_load_dwordx4 v[214:217], v128, s[70:71] offset:64
	s_add_u32 s70, s70, 0x8000
	s_addc_u32 s71, s71, 0
	global_load_dwordx4 v[218:221], v128, s[70:71]
	global_load_dwordx4 v[222:225], v128, s[70:71] offset:64
	s_add_u32 s70, s70, 0x28000
	s_addc_u32 s71, s71, 0
	global_load_dwordx4 v[226:229], v128, s[70:71]
	global_load_dwordx4 v[230:233], v128, s[70:71] offset:64
	s_add_u32 s70, s70, 0x8000
	s_addc_u32 s71, s71, 0
	global_load_dwordx4 v[234:237], v128, s[70:71]
	global_load_dwordx4 v[238:241], v128, s[70:71] offset:64
	s_add_u32 s70, s70, 0x8000
	s_addc_u32 s71, s71, 0
	global_load_dwordx4 v[172:175], v128, s[70:71]
	global_load_dwordx4 v[176:179], v128, s[70:71] offset:64
	s_add_u32 s70, s70, 0x8000
	s_addc_u32 s71, s71, 0
	global_load_dwordx4 v[180:183], v128, s[70:71]
	global_load_dwordx4 v[184:187], v128, s[70:71] offset:64
	s_bfe_u32 s42, s17, 0x20006
	s_lshl_b32 s43, s10, 4
	s_lshl_b32 s42, s42, 2
	s_add_i32 s43, s43, s42
	v_lshl_add_u32 v130, v171, 6, s43
	v_and_b32_e32 v131, 48, v170
	v_lshl_add_u32 v131, v171, 6, v131
	v_xor_b32_e32 v134, 16, v170
	v_xor_b32_e32 v135, 32, v170
	v_lshlrev_b32_e32 v134, 2, v134
	v_lshlrev_b32_e32 v135, 2, v135
	v_cmp_gt_u32_e64 s[64:65], 16, v170
	s_add_u32 s74, s8, 0x2000
	s_addc_u32 s75, s9, 0
	s_lshl_b32 s42, s62, 7
	s_add_u32 s78, s26, 0x3c08000
	s_addc_u32 s79, s27, 0
	s_add_u32 s78, s78, s42
	s_addc_u32 s79, s79, 0
	s_waitcnt vmcnt(14)
	v_lshlrev_b32_e32 v136, 16, v194
	v_and_b32_e32 v137, s63, v194
	v_pk_add_f32 v[124:125], v[124:125], v[136:137]
	v_lshlrev_b32_e32 v138, 16, v195
	v_and_b32_e32 v139, s63, v195
	v_pk_add_f32 v[126:127], v[126:127], v[138:139]
	v_lshlrev_b32_e32 v190, 16, v196
	v_and_b32_e32 v191, s63, v196
	v_pk_add_f32 v[120:121], v[120:121], v[190:191]
	v_lshlrev_b32_e32 v136, 16, v197
	v_and_b32_e32 v137, s63, v197
	v_pk_add_f32 v[122:123], v[122:123], v[136:137]
	v_lshlrev_b32_e32 v138, 16, v198
	v_and_b32_e32 v139, s63, v198
	v_pk_add_f32 v[116:117], v[116:117], v[138:139]
	v_lshlrev_b32_e32 v190, 16, v199
	v_and_b32_e32 v191, s63, v199
	v_pk_add_f32 v[118:119], v[118:119], v[190:191]
	v_lshlrev_b32_e32 v136, 16, v200
	v_and_b32_e32 v137, s63, v200
	v_pk_add_f32 v[112:113], v[112:113], v[136:137]
	v_lshlrev_b32_e32 v138, 16, v201
	v_and_b32_e32 v139, s63, v201
	v_pk_add_f32 v[114:115], v[114:115], v[138:139]
	v_mul_f32_e32 v156, v120, v120
	v_mul_f32_e32 v189, v112, v112
	v_fmac_f32_e32 v156, v121, v121
	v_fmac_f32_e32 v189, v113, v113
	v_fmac_f32_e32 v156, v122, v122
	v_fmac_f32_e32 v189, v114, v114
	v_fmac_f32_e32 v156, v123, v123
	v_fmac_f32_e32 v189, v115, v115
	v_fmac_f32_e32 v156, v124, v124
	v_fmac_f32_e32 v189, v116, v116
	v_fmac_f32_e32 v156, v125, v125
	v_fmac_f32_e32 v189, v117, v117
	v_fmac_f32_e32 v156, v126, v126
	v_fmac_f32_e32 v189, v118, v118
	v_fmac_f32_e32 v156, v127, v127
	v_fmac_f32_e32 v189, v119, v119
	v_add_f32_e32 v156, v156, v189
	s_waitcnt vmcnt(12)
	v_lshlrev_b32_e32 v190, 16, v202
	v_and_b32_e32 v191, s63, v202
	v_pk_add_f32 v[108:109], v[108:109], v[190:191]
	v_lshlrev_b32_e32 v136, 16, v203
	v_and_b32_e32 v137, s63, v203
	v_pk_add_f32 v[110:111], v[110:111], v[136:137]
	v_lshlrev_b32_e32 v138, 16, v204
	v_and_b32_e32 v139, s63, v204
	v_pk_add_f32 v[104:105], v[104:105], v[138:139]
	v_lshlrev_b32_e32 v190, 16, v205
	v_and_b32_e32 v191, s63, v205
	v_pk_add_f32 v[106:107], v[106:107], v[190:191]
	v_lshlrev_b32_e32 v136, 16, v206
	v_and_b32_e32 v137, s63, v206
	v_pk_add_f32 v[100:101], v[100:101], v[136:137]
	v_lshlrev_b32_e32 v138, 16, v207
	v_and_b32_e32 v139, s63, v207
	v_pk_add_f32 v[102:103], v[102:103], v[138:139]
	v_lshlrev_b32_e32 v190, 16, v208
	v_and_b32_e32 v191, s63, v208
	v_pk_add_f32 v[96:97], v[96:97], v[190:191]
	v_lshlrev_b32_e32 v136, 16, v209
	v_and_b32_e32 v137, s63, v209
	v_pk_add_f32 v[98:99], v[98:99], v[136:137]
	v_mul_f32_e32 v157, v104, v104
	v_mul_f32_e32 v189, v96, v96
	v_fmac_f32_e32 v157, v105, v105
	v_fmac_f32_e32 v189, v97, v97
	v_fmac_f32_e32 v157, v106, v106
	v_fmac_f32_e32 v189, v98, v98
	v_fmac_f32_e32 v157, v107, v107
	v_fmac_f32_e32 v189, v99, v99
	v_fmac_f32_e32 v157, v108, v108
	v_fmac_f32_e32 v189, v100, v100
	v_fmac_f32_e32 v157, v109, v109
	v_fmac_f32_e32 v189, v101, v101
	v_fmac_f32_e32 v157, v110, v110
	v_fmac_f32_e32 v189, v102, v102
	v_fmac_f32_e32 v157, v111, v111
	v_fmac_f32_e32 v189, v103, v103
	v_add_f32_e32 v157, v157, v189
	s_waitcnt vmcnt(10)
	v_lshlrev_b32_e32 v138, 16, v210
	v_and_b32_e32 v139, s63, v210
	v_pk_add_f32 v[92:93], v[92:93], v[138:139]
	v_lshlrev_b32_e32 v190, 16, v211
	v_and_b32_e32 v191, s63, v211
	v_pk_add_f32 v[94:95], v[94:95], v[190:191]
	v_lshlrev_b32_e32 v136, 16, v212
	v_and_b32_e32 v137, s63, v212
	v_pk_add_f32 v[88:89], v[88:89], v[136:137]
	v_lshlrev_b32_e32 v138, 16, v213
	v_and_b32_e32 v139, s63, v213
	v_pk_add_f32 v[90:91], v[90:91], v[138:139]
	v_lshlrev_b32_e32 v190, 16, v214
	v_and_b32_e32 v191, s63, v214
	v_pk_add_f32 v[84:85], v[84:85], v[190:191]
	v_lshlrev_b32_e32 v136, 16, v215
	v_and_b32_e32 v137, s63, v215
	v_pk_add_f32 v[86:87], v[86:87], v[136:137]
	v_lshlrev_b32_e32 v138, 16, v216
	v_and_b32_e32 v139, s63, v216
	v_pk_add_f32 v[80:81], v[80:81], v[138:139]
	v_lshlrev_b32_e32 v190, 16, v217
	v_and_b32_e32 v191, s63, v217
	v_pk_add_f32 v[82:83], v[82:83], v[190:191]
	v_mul_f32_e32 v158, v88, v88
	v_mul_f32_e32 v189, v80, v80
	v_fmac_f32_e32 v158, v89, v89
	v_fmac_f32_e32 v189, v81, v81
	v_fmac_f32_e32 v158, v90, v90
	v_fmac_f32_e32 v189, v82, v82
	v_fmac_f32_e32 v158, v91, v91
	v_fmac_f32_e32 v189, v83, v83
	v_fmac_f32_e32 v158, v92, v92
	v_fmac_f32_e32 v189, v84, v84
	v_fmac_f32_e32 v158, v93, v93
	v_fmac_f32_e32 v189, v85, v85
	v_fmac_f32_e32 v158, v94, v94
	v_fmac_f32_e32 v189, v86, v86
	v_fmac_f32_e32 v158, v95, v95
	v_fmac_f32_e32 v189, v87, v87
	v_add_f32_e32 v158, v158, v189
	s_waitcnt vmcnt(8)
	v_lshlrev_b32_e32 v136, 16, v218
	v_and_b32_e32 v137, s63, v218
	v_pk_add_f32 v[76:77], v[76:77], v[136:137]
	v_lshlrev_b32_e32 v138, 16, v219
	v_and_b32_e32 v139, s63, v219
	v_pk_add_f32 v[78:79], v[78:79], v[138:139]
	v_lshlrev_b32_e32 v190, 16, v220
	v_and_b32_e32 v191, s63, v220
	v_pk_add_f32 v[72:73], v[72:73], v[190:191]
	v_lshlrev_b32_e32 v136, 16, v221
	v_and_b32_e32 v137, s63, v221
	v_pk_add_f32 v[74:75], v[74:75], v[136:137]
	v_lshlrev_b32_e32 v138, 16, v222
	v_and_b32_e32 v139, s63, v222
	v_pk_add_f32 v[68:69], v[68:69], v[138:139]
	v_lshlrev_b32_e32 v190, 16, v223
	v_and_b32_e32 v191, s63, v223
	v_pk_add_f32 v[70:71], v[70:71], v[190:191]
	v_lshlrev_b32_e32 v136, 16, v224
	v_and_b32_e32 v137, s63, v224
	v_pk_add_f32 v[64:65], v[64:65], v[136:137]
	v_lshlrev_b32_e32 v138, 16, v225
	v_and_b32_e32 v139, s63, v225
	v_pk_add_f32 v[66:67], v[66:67], v[138:139]
	v_mul_f32_e32 v159, v72, v72
	v_mul_f32_e32 v189, v64, v64
	v_fmac_f32_e32 v159, v73, v73
	v_fmac_f32_e32 v189, v65, v65
	v_fmac_f32_e32 v159, v74, v74
	v_fmac_f32_e32 v189, v66, v66
	v_fmac_f32_e32 v159, v75, v75
	v_fmac_f32_e32 v189, v67, v67
	v_fmac_f32_e32 v159, v76, v76
	v_fmac_f32_e32 v189, v68, v68
	v_fmac_f32_e32 v159, v77, v77
	v_fmac_f32_e32 v189, v69, v69
	v_fmac_f32_e32 v159, v78, v78
	v_fmac_f32_e32 v189, v70, v70
	v_fmac_f32_e32 v159, v79, v79
	v_fmac_f32_e32 v189, v71, v71
	v_add_f32_e32 v159, v159, v189
	s_waitcnt vmcnt(6)
	v_lshlrev_b32_e32 v190, 16, v226
	v_and_b32_e32 v191, s63, v226
	v_pk_add_f32 v[60:61], v[60:61], v[190:191]
	v_lshlrev_b32_e32 v136, 16, v227
	v_and_b32_e32 v137, s63, v227
	v_pk_add_f32 v[62:63], v[62:63], v[136:137]
	v_lshlrev_b32_e32 v138, 16, v228
	v_and_b32_e32 v139, s63, v228
	v_pk_add_f32 v[56:57], v[56:57], v[138:139]
	v_lshlrev_b32_e32 v190, 16, v229
	v_and_b32_e32 v191, s63, v229
	v_pk_add_f32 v[58:59], v[58:59], v[190:191]
	v_lshlrev_b32_e32 v136, 16, v230
	v_and_b32_e32 v137, s63, v230
	v_pk_add_f32 v[52:53], v[52:53], v[136:137]
	v_lshlrev_b32_e32 v138, 16, v231
	v_and_b32_e32 v139, s63, v231
	v_pk_add_f32 v[54:55], v[54:55], v[138:139]
	v_lshlrev_b32_e32 v190, 16, v232
	v_and_b32_e32 v191, s63, v232
	v_pk_add_f32 v[48:49], v[48:49], v[190:191]
	v_lshlrev_b32_e32 v136, 16, v233
	v_and_b32_e32 v137, s63, v233
	v_pk_add_f32 v[50:51], v[50:51], v[136:137]
	v_mul_f32_e32 v160, v56, v56
	v_mul_f32_e32 v189, v48, v48
	v_fmac_f32_e32 v160, v57, v57
	v_fmac_f32_e32 v189, v49, v49
	v_fmac_f32_e32 v160, v58, v58
	v_fmac_f32_e32 v189, v50, v50
	v_fmac_f32_e32 v160, v59, v59
	v_fmac_f32_e32 v189, v51, v51
	v_fmac_f32_e32 v160, v60, v60
	v_fmac_f32_e32 v189, v52, v52
	v_fmac_f32_e32 v160, v61, v61
	v_fmac_f32_e32 v189, v53, v53
	v_fmac_f32_e32 v160, v62, v62
	v_fmac_f32_e32 v189, v54, v54
	v_fmac_f32_e32 v160, v63, v63
	v_fmac_f32_e32 v189, v55, v55
	v_add_f32_e32 v160, v160, v189
	s_waitcnt vmcnt(4)
	v_lshlrev_b32_e32 v138, 16, v234
	v_and_b32_e32 v139, s63, v234
	v_pk_add_f32 v[44:45], v[44:45], v[138:139]
	v_lshlrev_b32_e32 v190, 16, v235
	v_and_b32_e32 v191, s63, v235
	v_pk_add_f32 v[46:47], v[46:47], v[190:191]
	v_lshlrev_b32_e32 v136, 16, v236
	v_and_b32_e32 v137, s63, v236
	v_pk_add_f32 v[40:41], v[40:41], v[136:137]
	v_lshlrev_b32_e32 v138, 16, v237
	v_and_b32_e32 v139, s63, v237
	v_pk_add_f32 v[42:43], v[42:43], v[138:139]
	v_lshlrev_b32_e32 v190, 16, v238
	v_and_b32_e32 v191, s63, v238
	v_pk_add_f32 v[36:37], v[36:37], v[190:191]
	v_lshlrev_b32_e32 v136, 16, v239
	v_and_b32_e32 v137, s63, v239
	v_pk_add_f32 v[38:39], v[38:39], v[136:137]
	v_lshlrev_b32_e32 v138, 16, v240
	v_and_b32_e32 v139, s63, v240
	v_pk_add_f32 v[32:33], v[32:33], v[138:139]
	v_lshlrev_b32_e32 v190, 16, v241
	v_and_b32_e32 v191, s63, v241
	v_pk_add_f32 v[34:35], v[34:35], v[190:191]
	v_mul_f32_e32 v161, v40, v40
	v_mul_f32_e32 v189, v32, v32
	v_fmac_f32_e32 v161, v41, v41
	v_fmac_f32_e32 v189, v33, v33
	v_fmac_f32_e32 v161, v42, v42
	v_fmac_f32_e32 v189, v34, v34
	v_fmac_f32_e32 v161, v43, v43
	v_fmac_f32_e32 v189, v35, v35
	v_fmac_f32_e32 v161, v44, v44
	v_fmac_f32_e32 v189, v36, v36
	v_fmac_f32_e32 v161, v45, v45
	v_fmac_f32_e32 v189, v37, v37
	v_fmac_f32_e32 v161, v46, v46
	v_fmac_f32_e32 v189, v38, v38
	v_fmac_f32_e32 v161, v47, v47
	v_fmac_f32_e32 v189, v39, v39
	v_add_f32_e32 v161, v161, v189
	s_waitcnt vmcnt(2)
	v_lshlrev_b32_e32 v136, 16, v172
	v_and_b32_e32 v137, s63, v172
	v_pk_add_f32 v[28:29], v[28:29], v[136:137]
	v_lshlrev_b32_e32 v138, 16, v173
	v_and_b32_e32 v139, s63, v173
	v_pk_add_f32 v[30:31], v[30:31], v[138:139]
	v_lshlrev_b32_e32 v190, 16, v174
	v_and_b32_e32 v191, s63, v174
	v_pk_add_f32 v[24:25], v[24:25], v[190:191]
	v_lshlrev_b32_e32 v136, 16, v175
	v_and_b32_e32 v137, s63, v175
	v_pk_add_f32 v[26:27], v[26:27], v[136:137]
	v_lshlrev_b32_e32 v138, 16, v176
	v_and_b32_e32 v139, s63, v176
	v_pk_add_f32 v[20:21], v[20:21], v[138:139]
	v_lshlrev_b32_e32 v190, 16, v177
	v_and_b32_e32 v191, s63, v177
	v_pk_add_f32 v[22:23], v[22:23], v[190:191]
	v_lshlrev_b32_e32 v136, 16, v178
	v_and_b32_e32 v137, s63, v178
	v_pk_add_f32 v[16:17], v[16:17], v[136:137]
	v_lshlrev_b32_e32 v138, 16, v179
	v_and_b32_e32 v139, s63, v179
	v_pk_add_f32 v[18:19], v[18:19], v[138:139]
	v_mul_f32_e32 v162, v24, v24
	v_mul_f32_e32 v189, v16, v16
	v_fmac_f32_e32 v162, v25, v25
	v_fmac_f32_e32 v189, v17, v17
	v_fmac_f32_e32 v162, v26, v26
	v_fmac_f32_e32 v189, v18, v18
	v_fmac_f32_e32 v162, v27, v27
	v_fmac_f32_e32 v189, v19, v19
	v_fmac_f32_e32 v162, v28, v28
	v_fmac_f32_e32 v189, v20, v20
	v_fmac_f32_e32 v162, v29, v29
	v_fmac_f32_e32 v189, v21, v21
	v_fmac_f32_e32 v162, v30, v30
	v_fmac_f32_e32 v189, v22, v22
	v_fmac_f32_e32 v162, v31, v31
	v_fmac_f32_e32 v189, v23, v23
	v_add_f32_e32 v162, v162, v189
	s_waitcnt vmcnt(0)
	v_lshlrev_b32_e32 v190, 16, v180
	v_and_b32_e32 v191, s63, v180
	v_pk_add_f32 v[12:13], v[12:13], v[190:191]
	v_lshlrev_b32_e32 v136, 16, v181
	v_and_b32_e32 v137, s63, v181
	v_pk_add_f32 v[14:15], v[14:15], v[136:137]
	v_lshlrev_b32_e32 v138, 16, v182
	v_and_b32_e32 v139, s63, v182
	v_pk_add_f32 v[8:9], v[8:9], v[138:139]
	v_lshlrev_b32_e32 v190, 16, v183
	v_and_b32_e32 v191, s63, v183
	v_pk_add_f32 v[10:11], v[10:11], v[190:191]
	v_lshlrev_b32_e32 v136, 16, v184
	v_and_b32_e32 v137, s63, v184
	v_pk_add_f32 v[4:5], v[4:5], v[136:137]
	v_lshlrev_b32_e32 v138, 16, v185
	v_and_b32_e32 v139, s63, v185
	v_pk_add_f32 v[6:7], v[6:7], v[138:139]
	v_lshlrev_b32_e32 v190, 16, v186
	v_and_b32_e32 v191, s63, v186
	v_pk_add_f32 v[0:1], v[0:1], v[190:191]
	v_lshlrev_b32_e32 v136, 16, v187
	v_and_b32_e32 v137, s63, v187
	v_pk_add_f32 v[2:3], v[2:3], v[136:137]
	v_mul_f32_e32 v163, v8, v8
	v_mul_f32_e32 v189, v0, v0
	v_fmac_f32_e32 v163, v9, v9
	v_fmac_f32_e32 v189, v1, v1
	v_fmac_f32_e32 v163, v10, v10
	v_fmac_f32_e32 v189, v2, v2
	v_fmac_f32_e32 v163, v11, v11
	v_fmac_f32_e32 v189, v3, v3
	v_fmac_f32_e32 v163, v12, v12
	v_fmac_f32_e32 v189, v4, v4
	v_fmac_f32_e32 v163, v13, v13
	v_fmac_f32_e32 v189, v5, v5
	v_fmac_f32_e32 v163, v14, v14
	v_fmac_f32_e32 v189, v6, v6
	v_fmac_f32_e32 v163, v15, v15
	v_fmac_f32_e32 v189, v7, v7
	v_add_f32_e32 v163, v163, v189
	ds_bpermute_b32 v136, v134, v156
	ds_bpermute_b32 v137, v134, v157
	ds_bpermute_b32 v138, v134, v158
	ds_bpermute_b32 v139, v134, v159
	ds_bpermute_b32 v188, v134, v160
	ds_bpermute_b32 v189, v134, v161
	ds_bpermute_b32 v190, v134, v162
	ds_bpermute_b32 v191, v134, v163
	s_waitcnt lgkmcnt(0)
	v_add_f32_e32 v156, v156, v136
	v_add_f32_e32 v157, v157, v137
	v_add_f32_e32 v158, v158, v138
	v_add_f32_e32 v159, v159, v139
	v_add_f32_e32 v160, v160, v188
	v_add_f32_e32 v161, v161, v189
	v_add_f32_e32 v162, v162, v190
	v_add_f32_e32 v163, v163, v191
	ds_bpermute_b32 v136, v135, v156
	ds_bpermute_b32 v137, v135, v157
	ds_bpermute_b32 v138, v135, v158
	ds_bpermute_b32 v139, v135, v159
	ds_bpermute_b32 v188, v135, v160
	ds_bpermute_b32 v189, v135, v161
	ds_bpermute_b32 v190, v135, v162
	ds_bpermute_b32 v191, v135, v163
	s_waitcnt lgkmcnt(0)
	v_add_f32_e32 v156, v156, v136
	v_add_f32_e32 v157, v157, v137
	v_add_f32_e32 v158, v158, v138
	v_add_f32_e32 v159, v159, v139
	v_add_f32_e32 v160, v160, v188
	v_add_f32_e32 v161, v161, v189
	v_add_f32_e32 v162, v162, v190
	v_add_f32_e32 v163, v163, v191
	s_and_saveexec_b64 s[66:67], s[64:65]
	global_store_dword v130, v156, s[8:9] sc1
	global_store_dword v130, v157, s[8:9] offset:1024 sc1
	global_store_dword v130, v158, s[8:9] offset:2048 sc1
	global_store_dword v130, v159, s[8:9] offset:3072 sc1
	global_store_dword v130, v160, s[74:75] sc1
	global_store_dword v130, v161, s[74:75] offset:1024 sc1
	global_store_dword v130, v162, s[74:75] offset:2048 sc1
	global_store_dword v130, v163, s[74:75] offset:3072 sc1
	s_or_b64 exec, exec, s[66:67]
	global_load_dwordx4 v[210:213], v132, s[22:23]
	global_load_dwordx4 v[214:217], v132, s[22:23] offset:16
	global_load_dwordx4 v[218:221], v132, s[22:23] offset:128
	global_load_dwordx4 v[222:225], v132, s[22:23] offset:144
	s_waitcnt vmcnt(0)
	s_barrier
	s_barrier
	s_cmpk_gt_u32 s17, 0xff
	s_cbranch_scc1 .Lf11_w1_a
	s_and_saveexec_b64 s[40:41], s[14:15]
	s_cbranch_execz .Lf11_t0_done
	v_mov_b32_e32 v133, 0
	v_mov_b32_e32 v189, 1
	global_atomic_add v133, v189, s[78:79]
	s_mov_b32 s80, 0
